# static s_setprio 1 for waves 4-7 also at every GEMM epilogue start
# speedup vs baseline: 1.0028x; 1.0028x over previous
; #define PG8_STAGE(bufoff, gbase, voff) do { _Pragma("unroll") for (int _i = 0; _i < 2; ++_i) \
;         __builtin_amdgcn_global_load_lds((const unsigned*)((const char*)(gbase) + (voff)[_i]), (PG8_LAS unsigned*)(lds + (bufoff) + ldsw + _i * 8192), 16, 0, 0); } while (0)
; #define PG8_LDA(dst, b, h) do { _Pragma("unroll") for (int m = 0; m < 4; ++m) _Pragma("unroll") for (int k = 0; k < 2; ++k) dst[m][k] = *(const PG8_LAS bf16x8*)(lds + PG8_SA(b, h) + aoff + m * 2048 + k * 1024); } while (0)
; #define PG8_LDB(dst, b, h) do { _Pragma("unroll") for (int n = 0; n < 2; ++n) _Pragma("unroll") for (int k = 0; k < 2; ++k) dst[n][k] = *(const PG8_LAS bf16x8*)(lds + PG8_SB(b, h) + boff + n * 2048 + k * 1024); } while (0)
; #define PG8_MMA(ai, bj, At, Bt) do { __builtin_amdgcn_s_setprio(1); _Pragma("unroll") for (int m = 0; m < 4; ++m) _Pragma("unroll") for (int n = 0; n < 2; ++n) _Pragma("unroll") for (int k = 0; k < 2; ++k) \
;         acc[ai][bj][m][n] = __builtin_amdgcn_mfma_f32_16x16x32_bf16(Bt[n][k], At[m][k], acc[ai][bj][m][n], 0, 0, 0); __builtin_amdgcn_s_setprio(0); } while (0)
; #define PG8_WAIT_V(n) asm volatile("s_waitcnt vmcnt(" #n ")" ::: "memory")
; #define PG8_WAIT_L(n) asm volatile("s_waitcnt lgkmcnt(" #n ")" ::: "memory")
; #define PG8_BAR __builtin_amdgcn_s_barrier()
; #define PG8_SCHED __builtin_amdgcn_sched_barrier(0)
; template <class Epi, class Sched, bool ALIGN_EPI = false, bool SP2 = false>
; __device__ __forceinline__ void gemm_phase(PG8_LAS unsigned char* lds, const Gemm g, const Sched& S, const Epi& E) {
;     ...
;             PG8_LDB(B0, 0, 0); PG8_LDB(B1, 0, 1); PG8_SCHED; PG8_LDA(At, 0, 0); PG8_STAGE(PG8_SA(1, 1), a1 + hstepA, voffA);
;             PG8_WAIT_V(8); PG8_WAIT_L(0); PG8_BAR; PG8_MMA(0, 0, At, B0); PG8_MMA(0, 1, At, B1); PG8_BAR; PG8_SCHED;
;             PG8_LDA(At, 0, 1); PG8_STAGE(PG8_SB(0, 0), b2, voffB); PG8_STAGE(PG8_SB(0, 1), b2 + hstepB, voffB); PG8_STAGE(PG8_SA(0, 0), a2, voffA);
;             PG8_WAIT_V(8); PG8_WAIT_L(0); PG8_BAR; PG8_MMA(1, 0, At, B0); PG8_MMA(1, 1, At, B1); PG8_BAR; PG8_SCHED;
.LBB0_148:
	s_add_u32 s20, s18, 0xfffc0080
	s_addc_u32 s21, s19, -1
	s_add_i32 s47, 0, 0x10000
	s_cmp_eq_u32 s46, 12
	s_cselect_b32 s23, s11, s21
	s_cselect_b32 s22, s42, s20
	s_cselect_b32 s21, s9, s45
	s_cselect_b32 s20, s43, s44
	s_add_i32 s50, 0, 0x14000
	v_add_u32_e32 v142, s47, v175
	v_add_u32_e32 v170, s50, v175
	ds_read_b128 v[130:133], v142
	ds_read_b128 v[134:137], v142 offset:1024
	ds_read_b128 v[138:141], v142 offset:2048
	ds_read_b128 v[142:145], v142 offset:3072
	ds_read_b128 v[158:161], v170
	ds_read_b128 v[162:165], v170 offset:1024
	ds_read_b128 v[166:169], v170 offset:2048
	ds_read_b128 v[178:181], v170 offset:3072
	v_lshl_add_u64 v[172:173], s[18:19], 0, v[154:155]
	s_add_i32 m0, s30, 0xc000
	ds_read_b128 v[184:187], v183
	ds_read_b128 v[188:191], v183 offset:1024
	ds_read_b128 v[212:215], v183 offset:2048
	ds_read_b128 v[216:219], v183 offset:3072
	ds_read_b128 v[220:223], v183 offset:4096
	ds_read_b128 v[224:227], v183 offset:5120
	ds_read_b128 v[228:231], v183 offset:6144
	ds_read_b128 v[232:235], v183 offset:7168
	global_load_lds_dwordx4 v[172:173], off
	v_lshl_add_u64 v[172:173], s[18:19], 0, v[156:157]
	s_add_i32 m0, s30, 0xe000
	s_nop 0
	global_load_lds_dwordx4 v[172:173], off
	s_waitcnt vmcnt(8)
	s_waitcnt lgkmcnt(0)
	s_barrier
	s_setprio 1
	s_waitcnt lgkmcnt(0)
	v_mfma_f32_16x16x32_bf16 v[126:129], v[130:133], v[184:187], v[126:129]
	v_mfma_f32_16x16x32_bf16 v[118:121], v[138:141], v[184:187], v[118:121]
	v_mfma_f32_16x16x32_bf16 v[110:113], v[130:133], v[212:215], v[110:113]
	v_mfma_f32_16x16x32_bf16 v[102:105], v[138:141], v[212:215], v[102:105]
	v_mfma_f32_16x16x32_bf16 v[94:97], v[130:133], v[220:223], v[94:97]
	v_mfma_f32_16x16x32_bf16 v[86:89], v[138:141], v[220:223], v[86:89]
	v_mfma_f32_16x16x32_bf16 v[78:81], v[130:133], v[228:231], v[78:81]
	v_mfma_f32_16x16x32_bf16 v[70:73], v[138:141], v[228:231], v[70:73]
	v_mfma_f32_16x16x32_bf16 v[126:129], v[134:137], v[188:191], v[126:129]
	v_mfma_f32_16x16x32_bf16 v[118:121], v[142:145], v[188:191], v[118:121]
	v_mfma_f32_16x16x32_bf16 v[110:113], v[134:137], v[216:219], v[110:113]
	v_mfma_f32_16x16x32_bf16 v[102:105], v[142:145], v[216:219], v[102:105]
	v_mfma_f32_16x16x32_bf16 v[94:97], v[134:137], v[224:227], v[94:97]
	v_mfma_f32_16x16x32_bf16 v[86:89], v[142:145], v[224:227], v[86:89]
	v_mfma_f32_16x16x32_bf16 v[78:81], v[134:137], v[232:235], v[78:81]
	v_mfma_f32_16x16x32_bf16 v[70:73], v[142:145], v[232:235], v[70:73]
	s_setprio 0
	s_setprio 1
	v_mfma_f32_16x16x32_bf16 v[122:125], v[158:161], v[184:187], v[122:125]
	v_mfma_f32_16x16x32_bf16 v[114:117], v[166:169], v[184:187], v[114:117]
	v_mfma_f32_16x16x32_bf16 v[106:109], v[158:161], v[212:215], v[106:109]
	v_mfma_f32_16x16x32_bf16 v[98:101], v[166:169], v[212:215], v[98:101]
	v_mfma_f32_16x16x32_bf16 v[90:93], v[158:161], v[220:223], v[90:93]
	v_mfma_f32_16x16x32_bf16 v[82:85], v[166:169], v[220:223], v[82:85]
	v_mfma_f32_16x16x32_bf16 v[74:77], v[158:161], v[228:231], v[74:77]
	v_mfma_f32_16x16x32_bf16 v[66:69], v[166:169], v[228:231], v[66:69]
	v_mfma_f32_16x16x32_bf16 v[122:125], v[162:165], v[188:191], v[122:125]
	v_mfma_f32_16x16x32_bf16 v[114:117], v[178:181], v[188:191], v[114:117]
	v_mfma_f32_16x16x32_bf16 v[106:109], v[162:165], v[216:219], v[106:109]
	v_mfma_f32_16x16x32_bf16 v[98:101], v[178:181], v[216:219], v[98:101]
	v_mfma_f32_16x16x32_bf16 v[90:93], v[162:165], v[224:227], v[90:93]
	v_mfma_f32_16x16x32_bf16 v[82:85], v[178:181], v[224:227], v[82:85]
	v_mfma_f32_16x16x32_bf16 v[74:77], v[162:165], v[232:235], v[74:77]
	v_mfma_f32_16x16x32_bf16 v[66:69], v[178:181], v[232:235], v[66:69]
	s_setprio 0
	s_barrier
	s_add_i32 s47, s47, s28
	v_lshl_add_u64 v[172:173], s[20:21], 0, v[0:1]
	s_mov_b32 m0, s47
	ds_read_b128 v[184:187], v183 offset:16384
	ds_read_b128 v[188:191], v183 offset:17408
	ds_read_b128 v[212:215], v183 offset:18432
	ds_read_b128 v[216:219], v183 offset:19456
	ds_read_b128 v[220:223], v183 offset:20480
	ds_read_b128 v[224:227], v183 offset:21504
	ds_read_b128 v[228:231], v183 offset:22528
	ds_read_b128 v[232:235], v183 offset:23552
	global_load_lds_dwordx4 v[172:173], off
	s_add_i32 m0, s47, 0x2000
	s_add_u32 s48, s20, 0x40000
	v_lshl_add_u64 v[192:193], s[20:21], 0, v[146:147]
	s_addc_u32 s49, s21, 0
	s_add_i32 s47, s50, s28
	global_load_lds_dwordx4 v[192:193], off
	v_lshl_add_u64 v[198:199], s[48:49], 0, v[0:1]
	s_mov_b32 m0, s47
	v_lshl_add_u64 v[200:201], s[22:23], 0, v[148:149]
	global_load_lds_dwordx4 v[198:199], off
	v_lshl_add_u64 v[198:199], s[48:49], 0, v[146:147]
	s_add_i32 m0, s47, 0x2000
	s_nop 0
	global_load_lds_dwordx4 v[198:199], off
	v_lshl_add_u64 v[198:199], s[22:23], 0, v[150:151]
	s_mov_b32 m0, s30
	s_nop 0
	global_load_lds_dwordx4 v[198:199], off
	s_mov_b32 m0, s31
	s_nop 0
	global_load_lds_dwordx4 v[200:201], off
	s_waitcnt vmcnt(8)
	s_waitcnt lgkmcnt(0)
	s_barrier
; #define PG8_STAGE(bufoff, gbase, voff) do { _Pragma("unroll") for (int _i = 0; _i < 2; ++_i) \
;         __builtin_amdgcn_global_load_lds((const unsigned*)((const char*)(gbase) + (voff)[_i]), (PG8_LAS unsigned*)(lds + (bufoff) + ldsw + _i * 8192), 16, 0, 0); } while (0)
; #define PG8_LDA(dst, b, h) do { _Pragma("unroll") for (int m = 0; m < 4; ++m) _Pragma("unroll") for (int k = 0; k < 2; ++k) dst[m][k] = *(const PG8_LAS bf16x8*)(lds + PG8_SA(b, h) + aoff + m * 2048 + k * 1024); } while (0)
; #define PG8_LDB(dst, b, h) do { _Pragma("unroll") for (int n = 0; n < 2; ++n) _Pragma("unroll") for (int k = 0; k < 2; ++k) dst[n][k] = *(const PG8_LAS bf16x8*)(lds + PG8_SB(b, h) + boff + n * 2048 + k * 1024); } while (0)
; #define PG8_MMA(ai, bj, At, Bt) do { __builtin_amdgcn_s_setprio(1); _Pragma("unroll") for (int m = 0; m < 4; ++m) _Pragma("unroll") for (int n = 0; n < 2; ++n) _Pragma("unroll") for (int k = 0; k < 2; ++k) \
;         acc[ai][bj][m][n] = __builtin_amdgcn_mfma_f32_16x16x32_bf16(Bt[n][k], At[m][k], acc[ai][bj][m][n], 0, 0, 0); __builtin_amdgcn_s_setprio(0); } while (0)
; #define PG8_WAIT_V(n) asm volatile("s_waitcnt vmcnt(" #n ")" ::: "memory")
; #define PG8_WAIT_L(n) asm volatile("s_waitcnt lgkmcnt(" #n ")" ::: "memory")
; #define PG8_BAR __builtin_amdgcn_s_barrier()
; #define PG8_SCHED __builtin_amdgcn_sched_barrier(0)
; template <class Epi, class Sched, bool ALIGN_EPI = false, bool SP2 = false>
; __device__ __forceinline__ void gemm_phase(PG8_LAS unsigned char* lds, const Gemm g, const Sched& S, const Epi& E) {
;     ...
;             PG8_WAIT_V(8); PG8_WAIT_L(0); PG8_BAR; PG8_MMA(1, 0, At, B0); PG8_MMA(1, 1, At, B1); PG8_BAR; PG8_SCHED;
;             PG8_LDB(B0, 1, 0); PG8_LDB(B1, 1, 1); PG8_SCHED; PG8_LDA(At, 1, 0); PG8_STAGE(PG8_SA(0, 1), a2 + hstepA, voffA);
;             PG8_WAIT_V(8); PG8_WAIT_L(0); PG8_BAR; PG8_MMA(0, 0, At, B0); PG8_MMA(0, 1, At, B1); PG8_BAR; PG8_SCHED;
;             PG8_LDA(At, 1, 1); PG8_STAGE(PG8_SB(1, 0), b3, voffB); PG8_STAGE(PG8_SB(1, 1), b3 + hstepB, voffB); PG8_STAGE(PG8_SA(1, 0), a3, voffA);
	s_setprio 1
	s_waitcnt lgkmcnt(0)
	v_mfma_f32_16x16x32_bf16 v[62:65], v[130:133], v[184:187], v[62:65]
	v_mfma_f32_16x16x32_bf16 v[54:57], v[138:141], v[184:187], v[54:57]
	v_mfma_f32_16x16x32_bf16 v[46:49], v[130:133], v[212:215], v[46:49]
	v_mfma_f32_16x16x32_bf16 v[38:41], v[138:141], v[212:215], v[38:41]
	v_mfma_f32_16x16x32_bf16 v[30:33], v[130:133], v[220:223], v[30:33]
	v_mfma_f32_16x16x32_bf16 v[22:25], v[138:141], v[220:223], v[22:25]
	v_mfma_f32_16x16x32_bf16 v[14:17], v[130:133], v[228:231], v[14:17]
	v_mfma_f32_16x16x32_bf16 v[6:9], v[138:141], v[228:231], v[6:9]
	v_mfma_f32_16x16x32_bf16 v[62:65], v[134:137], v[188:191], v[62:65]
	v_mfma_f32_16x16x32_bf16 v[54:57], v[142:145], v[188:191], v[54:57]
	v_mfma_f32_16x16x32_bf16 v[46:49], v[134:137], v[216:219], v[46:49]
	v_mfma_f32_16x16x32_bf16 v[38:41], v[142:145], v[216:219], v[38:41]
	v_mfma_f32_16x16x32_bf16 v[30:33], v[134:137], v[224:227], v[30:33]
	v_mfma_f32_16x16x32_bf16 v[22:25], v[142:145], v[224:227], v[22:25]
	v_mfma_f32_16x16x32_bf16 v[14:17], v[134:137], v[232:235], v[14:17]
	v_mfma_f32_16x16x32_bf16 v[6:9], v[142:145], v[232:235], v[6:9]
	s_setprio 0
	s_setprio 1
	v_mfma_f32_16x16x32_bf16 v[58:61], v[158:161], v[184:187], v[58:61]
	v_mfma_f32_16x16x32_bf16 v[50:53], v[166:169], v[184:187], v[50:53]
	v_mfma_f32_16x16x32_bf16 v[42:45], v[158:161], v[212:215], v[42:45]
	v_mfma_f32_16x16x32_bf16 v[34:37], v[166:169], v[212:215], v[34:37]
	v_mfma_f32_16x16x32_bf16 v[26:29], v[158:161], v[220:223], v[26:29]
	v_mfma_f32_16x16x32_bf16 v[18:21], v[166:169], v[220:223], v[18:21]
	v_mfma_f32_16x16x32_bf16 v[10:13], v[158:161], v[228:231], v[10:13]
	v_mfma_f32_16x16x32_bf16 v[2:5], v[166:169], v[228:231], v[2:5]
	v_mfma_f32_16x16x32_bf16 v[58:61], v[162:165], v[188:191], v[58:61]
	v_mfma_f32_16x16x32_bf16 v[50:53], v[178:181], v[188:191], v[50:53]
	v_mfma_f32_16x16x32_bf16 v[42:45], v[162:165], v[216:219], v[42:45]
	v_mfma_f32_16x16x32_bf16 v[34:37], v[178:181], v[216:219], v[34:37]
	v_mfma_f32_16x16x32_bf16 v[26:29], v[162:165], v[224:227], v[26:29]
	v_mfma_f32_16x16x32_bf16 v[18:21], v[178:181], v[224:227], v[18:21]
	v_mfma_f32_16x16x32_bf16 v[10:13], v[162:165], v[232:235], v[10:13]
	v_mfma_f32_16x16x32_bf16 v[2:5], v[178:181], v[232:235], v[2:5]
	s_setprio 0
	s_barrier
	s_add_i32 s47, 0, 0x18000
	s_add_i32 s48, 0, 0x1c000
	v_add_u32_e32 v142, s47, v175
	v_add_u32_e32 v170, s48, v175
	ds_read_b128 v[130:133], v142
	ds_read_b128 v[134:137], v142 offset:1024
	ds_read_b128 v[138:141], v142 offset:2048
	ds_read_b128 v[142:145], v142 offset:3072
	ds_read_b128 v[158:161], v170
	ds_read_b128 v[162:165], v170 offset:1024
	ds_read_b128 v[166:169], v170 offset:2048
	ds_read_b128 v[178:181], v170 offset:3072
	s_add_u32 s22, s22, 0x40000
	s_addc_u32 s23, s23, 0
	s_mov_b32 m0, s34
	v_lshl_add_u64 v[206:207], s[22:23], 0, v[150:151]
	ds_read_b128 v[184:187], v183 offset:32768
	ds_read_b128 v[188:191], v183 offset:33792
	ds_read_b128 v[212:215], v183 offset:34816
	ds_read_b128 v[216:219], v183 offset:35840
	ds_read_b128 v[220:223], v183 offset:36864
	ds_read_b128 v[224:227], v183 offset:37888
	ds_read_b128 v[228:231], v183 offset:38912
	ds_read_b128 v[232:235], v183 offset:39936
	global_load_lds_dwordx4 v[206:207], off
	v_lshl_add_u64 v[206:207], s[22:23], 0, v[148:149]
	s_mov_b32 m0, s35
	s_nop 0
	global_load_lds_dwordx4 v[206:207], off
	s_waitcnt vmcnt(8)
	s_waitcnt lgkmcnt(0)
	s_barrier
	s_setprio 1
	s_waitcnt lgkmcnt(0)
	v_mfma_f32_16x16x32_bf16 v[126:129], v[130:133], v[184:187], v[126:129]
	v_mfma_f32_16x16x32_bf16 v[118:121], v[138:141], v[184:187], v[118:121]
	v_mfma_f32_16x16x32_bf16 v[110:113], v[130:133], v[212:215], v[110:113]
	v_mfma_f32_16x16x32_bf16 v[102:105], v[138:141], v[212:215], v[102:105]
	v_mfma_f32_16x16x32_bf16 v[94:97], v[130:133], v[220:223], v[94:97]
	v_mfma_f32_16x16x32_bf16 v[86:89], v[138:141], v[220:223], v[86:89]
	v_mfma_f32_16x16x32_bf16 v[78:81], v[130:133], v[228:231], v[78:81]
	v_mfma_f32_16x16x32_bf16 v[70:73], v[138:141], v[228:231], v[70:73]
	v_mfma_f32_16x16x32_bf16 v[126:129], v[134:137], v[188:191], v[126:129]
	v_mfma_f32_16x16x32_bf16 v[118:121], v[142:145], v[188:191], v[118:121]
	v_mfma_f32_16x16x32_bf16 v[110:113], v[134:137], v[216:219], v[110:113]
	v_mfma_f32_16x16x32_bf16 v[102:105], v[142:145], v[216:219], v[102:105]
	v_mfma_f32_16x16x32_bf16 v[94:97], v[134:137], v[224:227], v[94:97]
	v_mfma_f32_16x16x32_bf16 v[86:89], v[142:145], v[224:227], v[86:89]
	v_mfma_f32_16x16x32_bf16 v[78:81], v[134:137], v[232:235], v[78:81]
	v_mfma_f32_16x16x32_bf16 v[70:73], v[142:145], v[232:235], v[70:73]
	s_setprio 0
	s_setprio 1
	v_mfma_f32_16x16x32_bf16 v[122:125], v[158:161], v[184:187], v[122:125]
	v_mfma_f32_16x16x32_bf16 v[114:117], v[166:169], v[184:187], v[114:117]
	v_mfma_f32_16x16x32_bf16 v[106:109], v[158:161], v[212:215], v[106:109]
	v_mfma_f32_16x16x32_bf16 v[98:101], v[166:169], v[212:215], v[98:101]
	v_mfma_f32_16x16x32_bf16 v[90:93], v[158:161], v[220:223], v[90:93]
	v_mfma_f32_16x16x32_bf16 v[82:85], v[166:169], v[220:223], v[82:85]
	v_mfma_f32_16x16x32_bf16 v[74:77], v[158:161], v[228:231], v[74:77]
	v_mfma_f32_16x16x32_bf16 v[66:69], v[166:169], v[228:231], v[66:69]
	v_mfma_f32_16x16x32_bf16 v[122:125], v[162:165], v[188:191], v[122:125]
	v_mfma_f32_16x16x32_bf16 v[114:117], v[178:181], v[188:191], v[114:117]
	v_mfma_f32_16x16x32_bf16 v[106:109], v[162:165], v[216:219], v[106:109]
	v_mfma_f32_16x16x32_bf16 v[98:101], v[178:181], v[216:219], v[98:101]
	v_mfma_f32_16x16x32_bf16 v[90:93], v[162:165], v[224:227], v[90:93]
	v_mfma_f32_16x16x32_bf16 v[82:85], v[178:181], v[224:227], v[82:85]
	v_mfma_f32_16x16x32_bf16 v[74:77], v[162:165], v[232:235], v[74:77]
	v_mfma_f32_16x16x32_bf16 v[66:69], v[178:181], v[232:235], v[66:69]
	s_setprio 0
	s_barrier
; #define PG8_STAGE(bufoff, gbase, voff) do { _Pragma("unroll") for (int _i = 0; _i < 2; ++_i) \
;         __builtin_amdgcn_global_load_lds((const unsigned*)((const char*)(gbase) + (voff)[_i]), (PG8_LAS unsigned*)(lds + (bufoff) + ldsw + _i * 8192), 16, 0, 0); } while (0)
; #define PG8_LDA(dst, b, h) do { _Pragma("unroll") for (int m = 0; m < 4; ++m) _Pragma("unroll") for (int k = 0; k < 2; ++k) dst[m][k] = *(const PG8_LAS bf16x8*)(lds + PG8_SA(b, h) + aoff + m * 2048 + k * 1024); } while (0)
; #define PG8_MMA(ai, bj, At, Bt) do { __builtin_amdgcn_s_setprio(1); _Pragma("unroll") for (int m = 0; m < 4; ++m) _Pragma("unroll") for (int n = 0; n < 2; ++n) _Pragma("unroll") for (int k = 0; k < 2; ++k) \
;         acc[ai][bj][m][n] = __builtin_amdgcn_mfma_f32_16x16x32_bf16(Bt[n][k], At[m][k], acc[ai][bj][m][n], 0, 0, 0); __builtin_amdgcn_s_setprio(0); } while (0)
; #define PG8_WAIT_V(n) asm volatile("s_waitcnt vmcnt(" #n ")" ::: "memory")
; #define PG8_WAIT_L(n) asm volatile("s_waitcnt lgkmcnt(" #n ")" ::: "memory")
; #define PG8_BAR __builtin_amdgcn_s_barrier()
; #define PG8_SCHED __builtin_amdgcn_sched_barrier(0)
; template <class Epi, class Sched, bool ALIGN_EPI = false, bool SP2 = false>
; __device__ __forceinline__ void gemm_phase(PG8_LAS unsigned char* lds, const Gemm g, const Sched& S, const Epi& E) {
;     ...
;             PG8_LDA(At, 1, 1); PG8_STAGE(PG8_SB(1, 0), b3, voffB); PG8_STAGE(PG8_SB(1, 1), b3 + hstepB, voffB); PG8_STAGE(PG8_SA(1, 0), a3, voffA);
;             PG8_WAIT_V(8); PG8_WAIT_L(0); PG8_BAR; PG8_MMA(1, 0, At, B0); PG8_MMA(1, 1, At, B1); PG8_BAR; PG8_SCHED;
;     ...
;         if constexpr (ALIGN_EPI) { if (wr == 0) PG8_BAR; }
	s_add_i32 s22, s47, s28
	v_lshl_add_u64 v[172:173], v[172:173], 0, s[88:89]
	s_mov_b32 m0, s22
	ds_read_b128 v[184:187], v183 offset:49152
	ds_read_b128 v[188:191], v183 offset:50176
	ds_read_b128 v[212:215], v183 offset:51200
	ds_read_b128 v[216:219], v183 offset:52224
	ds_read_b128 v[220:223], v183 offset:53248
	ds_read_b128 v[224:227], v183 offset:54272
	ds_read_b128 v[228:231], v183 offset:55296
	ds_read_b128 v[232:235], v183 offset:56320
	global_load_lds_dwordx4 v[172:173], off
	s_add_i32 m0, s22, 0x2000
	s_add_u32 s20, s20, 0x40080
	v_lshl_add_u64 v[172:173], v[192:193], 0, s[88:89]
	s_addc_u32 s21, s21, 0
	s_add_i32 s22, s48, s28
	global_load_lds_dwordx4 v[172:173], off
	v_lshl_add_u64 v[172:173], s[20:21], 0, v[0:1]
	s_mov_b32 m0, s22
	s_nop 0
	global_load_lds_dwordx4 v[172:173], off
	v_lshl_add_u64 v[172:173], s[20:21], 0, v[146:147]
	s_add_i32 m0, s22, 0x2000
	s_nop 0
	global_load_lds_dwordx4 v[172:173], off
	v_lshl_add_u64 v[172:173], v[198:199], 0, s[88:89]
	s_mov_b32 m0, s38
	s_nop 0
	global_load_lds_dwordx4 v[172:173], off
	v_lshl_add_u64 v[172:173], v[200:201], 0, s[88:89]
	s_mov_b32 m0, s39
	s_nop 0
	global_load_lds_dwordx4 v[172:173], off
	s_waitcnt vmcnt(8)
	s_waitcnt lgkmcnt(0)
	s_barrier
	s_setprio 1
	s_waitcnt lgkmcnt(0)
	v_mfma_f32_16x16x32_bf16 v[62:65], v[130:133], v[184:187], v[62:65]
	v_mfma_f32_16x16x32_bf16 v[54:57], v[138:141], v[184:187], v[54:57]
	v_mfma_f32_16x16x32_bf16 v[46:49], v[130:133], v[212:215], v[46:49]
	v_mfma_f32_16x16x32_bf16 v[38:41], v[138:141], v[212:215], v[38:41]
	v_mfma_f32_16x16x32_bf16 v[30:33], v[130:133], v[220:223], v[30:33]
	v_mfma_f32_16x16x32_bf16 v[22:25], v[138:141], v[220:223], v[22:25]
	v_mfma_f32_16x16x32_bf16 v[14:17], v[130:133], v[228:231], v[14:17]
	v_mfma_f32_16x16x32_bf16 v[6:9], v[138:141], v[228:231], v[6:9]
	v_mfma_f32_16x16x32_bf16 v[62:65], v[134:137], v[188:191], v[62:65]
	v_mfma_f32_16x16x32_bf16 v[54:57], v[142:145], v[188:191], v[54:57]
	v_mfma_f32_16x16x32_bf16 v[46:49], v[134:137], v[216:219], v[46:49]
	v_mfma_f32_16x16x32_bf16 v[38:41], v[142:145], v[216:219], v[38:41]
	v_mfma_f32_16x16x32_bf16 v[30:33], v[134:137], v[224:227], v[30:33]
	v_mfma_f32_16x16x32_bf16 v[22:25], v[142:145], v[224:227], v[22:25]
	v_mfma_f32_16x16x32_bf16 v[14:17], v[134:137], v[232:235], v[14:17]
	v_mfma_f32_16x16x32_bf16 v[6:9], v[142:145], v[232:235], v[6:9]
	s_setprio 0
	s_setprio 1
	v_mfma_f32_16x16x32_bf16 v[58:61], v[158:161], v[184:187], v[58:61]
	v_mfma_f32_16x16x32_bf16 v[50:53], v[166:169], v[184:187], v[50:53]
	v_mfma_f32_16x16x32_bf16 v[42:45], v[158:161], v[212:215], v[42:45]
	v_mfma_f32_16x16x32_bf16 v[34:37], v[166:169], v[212:215], v[34:37]
	v_mfma_f32_16x16x32_bf16 v[26:29], v[158:161], v[220:223], v[26:29]
	v_mfma_f32_16x16x32_bf16 v[18:21], v[166:169], v[220:223], v[18:21]
	v_mfma_f32_16x16x32_bf16 v[10:13], v[158:161], v[228:231], v[10:13]
	v_mfma_f32_16x16x32_bf16 v[2:5], v[166:169], v[228:231], v[2:5]
	v_mfma_f32_16x16x32_bf16 v[58:61], v[162:165], v[188:191], v[58:61]
	v_mfma_f32_16x16x32_bf16 v[50:53], v[178:181], v[188:191], v[50:53]
	v_mfma_f32_16x16x32_bf16 v[42:45], v[162:165], v[216:219], v[42:45]
	v_mfma_f32_16x16x32_bf16 v[34:37], v[178:181], v[216:219], v[34:37]
	v_mfma_f32_16x16x32_bf16 v[26:29], v[162:165], v[224:227], v[26:29]
	v_mfma_f32_16x16x32_bf16 v[18:21], v[178:181], v[224:227], v[18:21]
	v_mfma_f32_16x16x32_bf16 v[10:13], v[162:165], v[232:235], v[10:13]
	v_mfma_f32_16x16x32_bf16 v[2:5], v[178:181], v[232:235], v[2:5]
	s_setprio 0
	s_barrier
	s_add_i32 s46, s46, 2
	s_add_u32 s18, s18, 0x100
	s_addc_u32 s19, s19, 0
	s_add_u32 s44, s44, 0x100
	s_addc_u32 s45, s45, 0
	s_cmp_gt_u32 s46, 13
	s_cbranch_scc0 .LBB0_148
	v_readfirstlane_b32 s100, v238
	s_nop 3
	s_bfe_u32 s100, s100, 0x40006
	s_cmp_ge_u32 s100, 4
	s_cbranch_scc0 .Lepiprio_0
	s_setprio 1
.Lepiprio_0:
	s_and_b64 vcc, exec, s[6:7]
	s_cbranch_vccz .LBB0_151
	s_barrier

; #define PG8_STAGE(bufoff, gbase, voff) do { _Pragma("unroll") for (int _i = 0; _i < 2; ++_i) \
;         __builtin_amdgcn_global_load_lds((const unsigned*)((const char*)(gbase) + (voff)[_i]), (PG8_LAS unsigned*)(lds + (bufoff) + ldsw + _i * 8192), 16, 0, 0); } while (0)
; #define PG8_LDA(dst, b, h) do { _Pragma("unroll") for (int m = 0; m < 4; ++m) _Pragma("unroll") for (int k = 0; k < 2; ++k) dst[m][k] = *(const PG8_LAS bf16x8*)(lds + PG8_SA(b, h) + aoff + m * 2048 + k * 1024); } while (0)
; #define PG8_LDB(dst, b, h) do { _Pragma("unroll") for (int n = 0; n < 2; ++n) _Pragma("unroll") for (int k = 0; k < 2; ++k) dst[n][k] = *(const PG8_LAS bf16x8*)(lds + PG8_SB(b, h) + boff + n * 2048 + k * 1024); } while (0)
; #define PG8_MMA(ai, bj, At, Bt) do { __builtin_amdgcn_s_setprio(1); _Pragma("unroll") for (int m = 0; m < 4; ++m) _Pragma("unroll") for (int n = 0; n < 2; ++n) _Pragma("unroll") for (int k = 0; k < 2; ++k) \
;         acc[ai][bj][m][n] = __builtin_amdgcn_mfma_f32_16x16x32_bf16(Bt[n][k], At[m][k], acc[ai][bj][m][n], 0, 0, 0); __builtin_amdgcn_s_setprio(0); } while (0)
; #define PG8_WAIT_V(n) asm volatile("s_waitcnt vmcnt(" #n ")" ::: "memory")
; #define PG8_WAIT_L(n) asm volatile("s_waitcnt lgkmcnt(" #n ")" ::: "memory")
; #define PG8_BAR __builtin_amdgcn_s_barrier()
; #define PG8_SCHED __builtin_amdgcn_sched_barrier(0)
; template <class Epi, class Sched, bool ALIGN_EPI = false, bool SP2 = false>
; __device__ __forceinline__ void gemm_phase(PG8_LAS unsigned char* lds, const Gemm g, const Sched& S, const Epi& E) {
;     ...
;             PG8_LDB(B0, 0, 0); PG8_LDB(B1, 0, 1); PG8_SCHED; PG8_LDA(At, 0, 0); PG8_STAGE(PG8_SA(1, 1), a1 + hstepA, voffA);
;             PG8_WAIT_V(8); PG8_WAIT_L(0); PG8_BAR; PG8_MMA(0, 0, At, B0); PG8_MMA(0, 1, At, B1); PG8_BAR; PG8_SCHED;
;             PG8_LDA(At, 0, 1); PG8_STAGE(PG8_SB(0, 0), b2, voffB); PG8_STAGE(PG8_SB(0, 1), b2 + hstepB, voffB); PG8_STAGE(PG8_SA(0, 0), a2, voffA);
;             PG8_WAIT_V(8); PG8_WAIT_L(0); PG8_BAR; PG8_MMA(1, 0, At, B0); PG8_MMA(1, 1, At, B1); PG8_BAR; PG8_SCHED;
.LBB0_227:
	s_add_u32 s20, s18, 0x100
	s_addc_u32 s21, s19, 0
	s_add_i32 s56, 0, 0x10000
	s_cmp_eq_u32 s55, 40
	s_cselect_b32 s25, s1, s21
	s_cselect_b32 s24, s0, s20
	s_cselect_b32 s23, s17, s54
	s_cselect_b32 s22, s16, s41
	s_add_i32 s57, 0, 0x14000
	v_add_u32_e32 v142, s56, v183
	v_add_u32_e32 v158, s57, v183
	ds_read_b128 v[130:133], v142
	ds_read_b128 v[134:137], v142 offset:1024
	ds_read_b128 v[138:141], v142 offset:2048
	ds_read_b128 v[142:145], v142 offset:3072
	ds_read_b128 v[146:149], v158
	ds_read_b128 v[150:153], v158 offset:1024
	ds_read_b128 v[154:157], v158 offset:2048
	ds_read_b128 v[158:161], v158 offset:3072
	v_lshl_add_u64 v[180:181], s[18:19], 0, v[164:165]
	s_add_i32 m0, s42, 0xc000
	ds_read_b128 v[168:171], v185
	ds_read_b128 v[172:175], v185 offset:1024
	ds_read_b128 v[176:179], v185 offset:2048
	ds_read_b128 v[186:189], v185 offset:3072
	ds_read_b128 v[190:193], v185 offset:4096
	ds_read_b128 v[212:215], v185 offset:5120
	ds_read_b128 v[216:219], v185 offset:6144
	ds_read_b128 v[220:223], v185 offset:7168
	global_load_lds_dwordx4 v[180:181], off
	v_lshl_add_u64 v[180:181], s[18:19], 0, v[166:167]
	s_add_i32 m0, s42, 0xe000
	s_nop 0
	global_load_lds_dwordx4 v[180:181], off
	s_waitcnt vmcnt(8)
	s_waitcnt lgkmcnt(0)
	s_barrier
	s_setprio 1
	s_waitcnt lgkmcnt(0)
	v_mfma_f32_16x16x32_bf16 v[126:129], v[130:133], v[168:171], v[126:129]
	v_mfma_f32_16x16x32_bf16 v[122:125], v[138:141], v[168:171], v[122:125]
	v_mfma_f32_16x16x32_bf16 v[110:113], v[130:133], v[176:179], v[110:113]
	v_mfma_f32_16x16x32_bf16 v[106:109], v[138:141], v[176:179], v[106:109]
	v_mfma_f32_16x16x32_bf16 v[94:97], v[130:133], v[190:193], v[94:97]
	v_mfma_f32_16x16x32_bf16 v[90:93], v[138:141], v[190:193], v[90:93]
	v_mfma_f32_16x16x32_bf16 v[78:81], v[130:133], v[216:219], v[78:81]
	v_mfma_f32_16x16x32_bf16 v[74:77], v[138:141], v[216:219], v[74:77]
	v_mfma_f32_16x16x32_bf16 v[126:129], v[134:137], v[172:175], v[126:129]
	v_mfma_f32_16x16x32_bf16 v[122:125], v[142:145], v[172:175], v[122:125]
	v_mfma_f32_16x16x32_bf16 v[110:113], v[134:137], v[186:189], v[110:113]
	v_mfma_f32_16x16x32_bf16 v[106:109], v[142:145], v[186:189], v[106:109]
	v_mfma_f32_16x16x32_bf16 v[94:97], v[134:137], v[212:215], v[94:97]
	v_mfma_f32_16x16x32_bf16 v[90:93], v[142:145], v[212:215], v[90:93]
	v_mfma_f32_16x16x32_bf16 v[78:81], v[134:137], v[220:223], v[78:81]
	v_mfma_f32_16x16x32_bf16 v[74:77], v[142:145], v[220:223], v[74:77]
	s_setprio 0
	s_setprio 1
	v_mfma_f32_16x16x32_bf16 v[118:121], v[146:149], v[168:171], v[118:121]
	v_mfma_f32_16x16x32_bf16 v[114:117], v[154:157], v[168:171], v[114:117]
	v_mfma_f32_16x16x32_bf16 v[102:105], v[146:149], v[176:179], v[102:105]
	v_mfma_f32_16x16x32_bf16 v[98:101], v[154:157], v[176:179], v[98:101]
	v_mfma_f32_16x16x32_bf16 v[86:89], v[146:149], v[190:193], v[86:89]
	v_mfma_f32_16x16x32_bf16 v[82:85], v[154:157], v[190:193], v[82:85]
	v_mfma_f32_16x16x32_bf16 v[70:73], v[146:149], v[216:219], v[70:73]
	v_mfma_f32_16x16x32_bf16 v[66:69], v[154:157], v[216:219], v[66:69]
	v_mfma_f32_16x16x32_bf16 v[118:121], v[150:153], v[172:175], v[118:121]
	v_mfma_f32_16x16x32_bf16 v[114:117], v[158:161], v[172:175], v[114:117]
	v_mfma_f32_16x16x32_bf16 v[102:105], v[150:153], v[186:189], v[102:105]
	v_mfma_f32_16x16x32_bf16 v[98:101], v[158:161], v[186:189], v[98:101]
	v_mfma_f32_16x16x32_bf16 v[86:89], v[150:153], v[212:215], v[86:89]
	v_mfma_f32_16x16x32_bf16 v[82:85], v[158:161], v[212:215], v[82:85]
	v_mfma_f32_16x16x32_bf16 v[70:73], v[150:153], v[220:223], v[70:73]
	v_mfma_f32_16x16x32_bf16 v[66:69], v[158:161], v[220:223], v[66:69]
	s_setprio 0
	s_barrier
	s_add_i32 s18, s56, s35
	v_lshl_add_u64 v[180:181], s[22:23], 0, v[0:1]
	s_mov_b32 m0, s18
	ds_read_b128 v[168:171], v185 offset:16384
	ds_read_b128 v[172:175], v185 offset:17408
	ds_read_b128 v[176:179], v185 offset:18432
	ds_read_b128 v[186:189], v185 offset:19456
	ds_read_b128 v[190:193], v185 offset:20480
	ds_read_b128 v[212:215], v185 offset:21504
	ds_read_b128 v[216:219], v185 offset:22528
	ds_read_b128 v[220:223], v185 offset:23552
	global_load_lds_dwordx4 v[180:181], off
	s_add_i32 m0, s18, 0x2000
	s_add_u32 s18, s22, 0xb0000
	v_lshl_add_u64 v[198:199], s[22:23], 0, v[162:163]
	s_addc_u32 s19, s23, 0
	s_add_i32 s56, s57, s35
	global_load_lds_dwordx4 v[198:199], off
	v_lshl_add_u64 v[200:201], s[18:19], 0, v[0:1]
	s_mov_b32 m0, s56
	v_lshl_add_u64 v[206:207], s[24:25], 0, v[162:163]
	global_load_lds_dwordx4 v[200:201], off
	v_lshl_add_u64 v[200:201], s[18:19], 0, v[162:163]
	s_add_i32 m0, s56, 0x2000
	s_nop 0
	global_load_lds_dwordx4 v[200:201], off
	v_lshl_add_u64 v[200:201], s[24:25], 0, v[0:1]
	s_mov_b32 m0, s42
	s_nop 0
	global_load_lds_dwordx4 v[200:201], off
	s_mov_b32 m0, s43
	s_nop 0
	global_load_lds_dwordx4 v[206:207], off
	s_waitcnt vmcnt(8)
	s_waitcnt lgkmcnt(0)
	s_barrier
; #define PG8_STAGE(bufoff, gbase, voff) do { _Pragma("unroll") for (int _i = 0; _i < 2; ++_i) \
;         __builtin_amdgcn_global_load_lds((const unsigned*)((const char*)(gbase) + (voff)[_i]), (PG8_LAS unsigned*)(lds + (bufoff) + ldsw + _i * 8192), 16, 0, 0); } while (0)
; #define PG8_LDA(dst, b, h) do { _Pragma("unroll") for (int m = 0; m < 4; ++m) _Pragma("unroll") for (int k = 0; k < 2; ++k) dst[m][k] = *(const PG8_LAS bf16x8*)(lds + PG8_SA(b, h) + aoff + m * 2048 + k * 1024); } while (0)
; #define PG8_LDB(dst, b, h) do { _Pragma("unroll") for (int n = 0; n < 2; ++n) _Pragma("unroll") for (int k = 0; k < 2; ++k) dst[n][k] = *(const PG8_LAS bf16x8*)(lds + PG8_SB(b, h) + boff + n * 2048 + k * 1024); } while (0)
; #define PG8_MMA(ai, bj, At, Bt) do { __builtin_amdgcn_s_setprio(1); _Pragma("unroll") for (int m = 0; m < 4; ++m) _Pragma("unroll") for (int n = 0; n < 2; ++n) _Pragma("unroll") for (int k = 0; k < 2; ++k) \
;         acc[ai][bj][m][n] = __builtin_amdgcn_mfma_f32_16x16x32_bf16(Bt[n][k], At[m][k], acc[ai][bj][m][n], 0, 0, 0); __builtin_amdgcn_s_setprio(0); } while (0)
; #define PG8_WAIT_V(n) asm volatile("s_waitcnt vmcnt(" #n ")" ::: "memory")
; #define PG8_WAIT_L(n) asm volatile("s_waitcnt lgkmcnt(" #n ")" ::: "memory")
; #define PG8_BAR __builtin_amdgcn_s_barrier()
; #define PG8_SCHED __builtin_amdgcn_sched_barrier(0)
; template <class Epi, class Sched, bool ALIGN_EPI = false, bool SP2 = false>
; __device__ __forceinline__ void gemm_phase(PG8_LAS unsigned char* lds, const Gemm g, const Sched& S, const Epi& E) {
;     ...
;             PG8_WAIT_V(8); PG8_WAIT_L(0); PG8_BAR; PG8_MMA(1, 0, At, B0); PG8_MMA(1, 1, At, B1); PG8_BAR; PG8_SCHED;
;             PG8_LDB(B0, 1, 0); PG8_LDB(B1, 1, 1); PG8_SCHED; PG8_LDA(At, 1, 0); PG8_STAGE(PG8_SA(0, 1), a2 + hstepA, voffA);
;             PG8_WAIT_V(8); PG8_WAIT_L(0); PG8_BAR; PG8_MMA(0, 0, At, B0); PG8_MMA(0, 1, At, B1); PG8_BAR; PG8_SCHED;
;             PG8_LDA(At, 1, 1); PG8_STAGE(PG8_SB(1, 0), b3, voffB); PG8_STAGE(PG8_SB(1, 1), b3 + hstepB, voffB); PG8_STAGE(PG8_SA(1, 0), a3, voffA);
	s_setprio 1
	s_waitcnt lgkmcnt(0)
	v_mfma_f32_16x16x32_bf16 v[62:65], v[130:133], v[168:171], v[62:65]
	v_mfma_f32_16x16x32_bf16 v[58:61], v[138:141], v[168:171], v[58:61]
	v_mfma_f32_16x16x32_bf16 v[46:49], v[130:133], v[176:179], v[46:49]
	v_mfma_f32_16x16x32_bf16 v[42:45], v[138:141], v[176:179], v[42:45]
	v_mfma_f32_16x16x32_bf16 v[30:33], v[130:133], v[190:193], v[30:33]
	v_mfma_f32_16x16x32_bf16 v[26:29], v[138:141], v[190:193], v[26:29]
	v_mfma_f32_16x16x32_bf16 v[14:17], v[130:133], v[216:219], v[14:17]
	v_mfma_f32_16x16x32_bf16 v[10:13], v[138:141], v[216:219], v[10:13]
	v_mfma_f32_16x16x32_bf16 v[62:65], v[134:137], v[172:175], v[62:65]
	v_mfma_f32_16x16x32_bf16 v[58:61], v[142:145], v[172:175], v[58:61]
	v_mfma_f32_16x16x32_bf16 v[46:49], v[134:137], v[186:189], v[46:49]
	v_mfma_f32_16x16x32_bf16 v[42:45], v[142:145], v[186:189], v[42:45]
	v_mfma_f32_16x16x32_bf16 v[30:33], v[134:137], v[212:215], v[30:33]
	v_mfma_f32_16x16x32_bf16 v[26:29], v[142:145], v[212:215], v[26:29]
	v_mfma_f32_16x16x32_bf16 v[14:17], v[134:137], v[220:223], v[14:17]
	v_mfma_f32_16x16x32_bf16 v[10:13], v[142:145], v[220:223], v[10:13]
	s_setprio 0
	s_setprio 1
	v_mfma_f32_16x16x32_bf16 v[54:57], v[146:149], v[168:171], v[54:57]
	v_mfma_f32_16x16x32_bf16 v[50:53], v[154:157], v[168:171], v[50:53]
	v_mfma_f32_16x16x32_bf16 v[38:41], v[146:149], v[176:179], v[38:41]
	v_mfma_f32_16x16x32_bf16 v[34:37], v[154:157], v[176:179], v[34:37]
	v_mfma_f32_16x16x32_bf16 v[22:25], v[146:149], v[190:193], v[22:25]
	v_mfma_f32_16x16x32_bf16 v[18:21], v[154:157], v[190:193], v[18:21]
	v_mfma_f32_16x16x32_bf16 v[6:9], v[146:149], v[216:219], v[6:9]
	v_mfma_f32_16x16x32_bf16 v[2:5], v[154:157], v[216:219], v[2:5]
	v_mfma_f32_16x16x32_bf16 v[54:57], v[150:153], v[172:175], v[54:57]
	v_mfma_f32_16x16x32_bf16 v[50:53], v[158:161], v[172:175], v[50:53]
	v_mfma_f32_16x16x32_bf16 v[38:41], v[150:153], v[186:189], v[38:41]
	v_mfma_f32_16x16x32_bf16 v[34:37], v[158:161], v[186:189], v[34:37]
	v_mfma_f32_16x16x32_bf16 v[22:25], v[150:153], v[212:215], v[22:25]
	v_mfma_f32_16x16x32_bf16 v[18:21], v[158:161], v[212:215], v[18:21]
	v_mfma_f32_16x16x32_bf16 v[6:9], v[150:153], v[220:223], v[6:9]
	v_mfma_f32_16x16x32_bf16 v[2:5], v[158:161], v[220:223], v[2:5]
	s_setprio 0
	s_barrier
	s_add_i32 s56, 0, 0x18000
	s_add_i32 s57, 0, 0x1c000
	v_add_u32_e32 v142, s56, v183
	v_add_u32_e32 v158, s57, v183
	ds_read_b128 v[130:133], v142
	ds_read_b128 v[134:137], v142 offset:1024
	ds_read_b128 v[138:141], v142 offset:2048
	ds_read_b128 v[142:145], v142 offset:3072
	ds_read_b128 v[146:149], v158
	ds_read_b128 v[150:153], v158 offset:1024
	ds_read_b128 v[154:157], v158 offset:2048
	ds_read_b128 v[158:161], v158 offset:3072
	s_add_u32 s18, s24, 0xb0000
	s_addc_u32 s19, s25, 0
	s_mov_b32 m0, s44
	v_lshl_add_u64 v[208:209], s[18:19], 0, v[0:1]
	ds_read_b128 v[168:171], v185 offset:32768
	ds_read_b128 v[172:175], v185 offset:33792
	ds_read_b128 v[176:179], v185 offset:34816
	ds_read_b128 v[186:189], v185 offset:35840
	ds_read_b128 v[190:193], v185 offset:36864
	ds_read_b128 v[212:215], v185 offset:37888
	ds_read_b128 v[216:219], v185 offset:38912
	ds_read_b128 v[220:223], v185 offset:39936
	global_load_lds_dwordx4 v[208:209], off
	v_lshl_add_u64 v[208:209], s[18:19], 0, v[162:163]
	s_mov_b32 m0, s45
	s_nop 0
	global_load_lds_dwordx4 v[208:209], off
	s_waitcnt vmcnt(8)
	s_waitcnt lgkmcnt(0)
	s_barrier
	s_setprio 1
	s_waitcnt lgkmcnt(0)
	v_mfma_f32_16x16x32_bf16 v[126:129], v[130:133], v[168:171], v[126:129]
	v_mfma_f32_16x16x32_bf16 v[122:125], v[138:141], v[168:171], v[122:125]
	v_mfma_f32_16x16x32_bf16 v[110:113], v[130:133], v[176:179], v[110:113]
	v_mfma_f32_16x16x32_bf16 v[106:109], v[138:141], v[176:179], v[106:109]
	v_mfma_f32_16x16x32_bf16 v[94:97], v[130:133], v[190:193], v[94:97]
	v_mfma_f32_16x16x32_bf16 v[90:93], v[138:141], v[190:193], v[90:93]
	v_mfma_f32_16x16x32_bf16 v[78:81], v[130:133], v[216:219], v[78:81]
	v_mfma_f32_16x16x32_bf16 v[74:77], v[138:141], v[216:219], v[74:77]
	v_mfma_f32_16x16x32_bf16 v[126:129], v[134:137], v[172:175], v[126:129]
	v_mfma_f32_16x16x32_bf16 v[122:125], v[142:145], v[172:175], v[122:125]
	v_mfma_f32_16x16x32_bf16 v[110:113], v[134:137], v[186:189], v[110:113]
	v_mfma_f32_16x16x32_bf16 v[106:109], v[142:145], v[186:189], v[106:109]
	v_mfma_f32_16x16x32_bf16 v[94:97], v[134:137], v[212:215], v[94:97]
	v_mfma_f32_16x16x32_bf16 v[90:93], v[142:145], v[212:215], v[90:93]
	v_mfma_f32_16x16x32_bf16 v[78:81], v[134:137], v[220:223], v[78:81]
	v_mfma_f32_16x16x32_bf16 v[74:77], v[142:145], v[220:223], v[74:77]
	s_setprio 0
	s_setprio 1
	v_mfma_f32_16x16x32_bf16 v[118:121], v[146:149], v[168:171], v[118:121]
	v_mfma_f32_16x16x32_bf16 v[114:117], v[154:157], v[168:171], v[114:117]
	v_mfma_f32_16x16x32_bf16 v[102:105], v[146:149], v[176:179], v[102:105]
	v_mfma_f32_16x16x32_bf16 v[98:101], v[154:157], v[176:179], v[98:101]
	v_mfma_f32_16x16x32_bf16 v[86:89], v[146:149], v[190:193], v[86:89]
	v_mfma_f32_16x16x32_bf16 v[82:85], v[154:157], v[190:193], v[82:85]
	v_mfma_f32_16x16x32_bf16 v[70:73], v[146:149], v[216:219], v[70:73]
	v_mfma_f32_16x16x32_bf16 v[66:69], v[154:157], v[216:219], v[66:69]
	v_mfma_f32_16x16x32_bf16 v[118:121], v[150:153], v[172:175], v[118:121]
	v_mfma_f32_16x16x32_bf16 v[114:117], v[158:161], v[172:175], v[114:117]
	v_mfma_f32_16x16x32_bf16 v[102:105], v[150:153], v[186:189], v[102:105]
	v_mfma_f32_16x16x32_bf16 v[98:101], v[158:161], v[186:189], v[98:101]
	v_mfma_f32_16x16x32_bf16 v[86:89], v[150:153], v[212:215], v[86:89]
	v_mfma_f32_16x16x32_bf16 v[82:85], v[158:161], v[212:215], v[82:85]
	v_mfma_f32_16x16x32_bf16 v[70:73], v[150:153], v[220:223], v[70:73]
	v_mfma_f32_16x16x32_bf16 v[66:69], v[158:161], v[220:223], v[66:69]
	s_setprio 0
	s_barrier
; #define PG8_STAGE(bufoff, gbase, voff) do { _Pragma("unroll") for (int _i = 0; _i < 2; ++_i) \
;         __builtin_amdgcn_global_load_lds((const unsigned*)((const char*)(gbase) + (voff)[_i]), (PG8_LAS unsigned*)(lds + (bufoff) + ldsw + _i * 8192), 16, 0, 0); } while (0)
; #define PG8_LDA(dst, b, h) do { _Pragma("unroll") for (int m = 0; m < 4; ++m) _Pragma("unroll") for (int k = 0; k < 2; ++k) dst[m][k] = *(const PG8_LAS bf16x8*)(lds + PG8_SA(b, h) + aoff + m * 2048 + k * 1024); } while (0)
; #define PG8_MMA(ai, bj, At, Bt) do { __builtin_amdgcn_s_setprio(1); _Pragma("unroll") for (int m = 0; m < 4; ++m) _Pragma("unroll") for (int n = 0; n < 2; ++n) _Pragma("unroll") for (int k = 0; k < 2; ++k) \
;         acc[ai][bj][m][n] = __builtin_amdgcn_mfma_f32_16x16x32_bf16(Bt[n][k], At[m][k], acc[ai][bj][m][n], 0, 0, 0); __builtin_amdgcn_s_setprio(0); } while (0)
; #define PG8_WAIT_V(n) asm volatile("s_waitcnt vmcnt(" #n ")" ::: "memory")
; #define PG8_WAIT_L(n) asm volatile("s_waitcnt lgkmcnt(" #n ")" ::: "memory")
; #define PG8_BAR __builtin_amdgcn_s_barrier()
; #define PG8_SCHED __builtin_amdgcn_sched_barrier(0)
; template <class Epi, class Sched, bool ALIGN_EPI = false, bool SP2 = false>
; __device__ __forceinline__ void gemm_phase(PG8_LAS unsigned char* lds, const Gemm g, const Sched& S, const Epi& E) {
;     ...
;             PG8_LDA(At, 1, 1); PG8_STAGE(PG8_SB(1, 0), b3, voffB); PG8_STAGE(PG8_SB(1, 1), b3 + hstepB, voffB); PG8_STAGE(PG8_SA(1, 0), a3, voffA);
;             PG8_WAIT_V(8); PG8_WAIT_L(0); PG8_BAR; PG8_MMA(1, 0, At, B0); PG8_MMA(1, 1, At, B1); PG8_BAR; PG8_SCHED;
;     ...
;         if constexpr (ALIGN_EPI) { if (wr == 0) PG8_BAR; }
	s_add_i32 s18, s56, s35
	v_lshl_add_u64 v[180:181], v[180:181], 0, s[88:89]
	s_mov_b32 m0, s18
	ds_read_b128 v[168:171], v185 offset:49152
	ds_read_b128 v[172:175], v185 offset:50176
	ds_read_b128 v[176:179], v185 offset:51200
	ds_read_b128 v[186:189], v185 offset:52224
	ds_read_b128 v[190:193], v185 offset:53248
	ds_read_b128 v[212:215], v185 offset:54272
	ds_read_b128 v[216:219], v185 offset:55296
	ds_read_b128 v[220:223], v185 offset:56320
	global_load_lds_dwordx4 v[180:181], off
	s_add_i32 m0, s18, 0x2000
	s_add_u32 s18, s22, 0xb0080
	v_lshl_add_u64 v[180:181], v[198:199], 0, s[88:89]
	s_addc_u32 s19, s23, 0
	s_add_i32 s22, s57, s35
	global_load_lds_dwordx4 v[180:181], off
	v_lshl_add_u64 v[180:181], s[18:19], 0, v[0:1]
	s_mov_b32 m0, s22
	s_nop 0
	global_load_lds_dwordx4 v[180:181], off
	v_lshl_add_u64 v[180:181], s[18:19], 0, v[162:163]
	s_add_i32 m0, s22, 0x2000
	s_nop 0
	global_load_lds_dwordx4 v[180:181], off
	v_lshl_add_u64 v[180:181], v[200:201], 0, s[88:89]
	s_mov_b32 m0, s47
	s_nop 0
	global_load_lds_dwordx4 v[180:181], off
	v_lshl_add_u64 v[180:181], v[206:207], 0, s[88:89]
	s_mov_b32 m0, s48
	s_nop 0
	global_load_lds_dwordx4 v[180:181], off
	s_waitcnt vmcnt(8)
	s_waitcnt lgkmcnt(0)
	s_barrier
	s_setprio 1
	s_waitcnt lgkmcnt(0)
	v_mfma_f32_16x16x32_bf16 v[62:65], v[130:133], v[168:171], v[62:65]
	v_mfma_f32_16x16x32_bf16 v[58:61], v[138:141], v[168:171], v[58:61]
	v_mfma_f32_16x16x32_bf16 v[46:49], v[130:133], v[176:179], v[46:49]
	v_mfma_f32_16x16x32_bf16 v[42:45], v[138:141], v[176:179], v[42:45]
	v_mfma_f32_16x16x32_bf16 v[30:33], v[130:133], v[190:193], v[30:33]
	v_mfma_f32_16x16x32_bf16 v[26:29], v[138:141], v[190:193], v[26:29]
	v_mfma_f32_16x16x32_bf16 v[14:17], v[130:133], v[216:219], v[14:17]
	v_mfma_f32_16x16x32_bf16 v[10:13], v[138:141], v[216:219], v[10:13]
	v_mfma_f32_16x16x32_bf16 v[62:65], v[134:137], v[172:175], v[62:65]
	v_mfma_f32_16x16x32_bf16 v[58:61], v[142:145], v[172:175], v[58:61]
	v_mfma_f32_16x16x32_bf16 v[46:49], v[134:137], v[186:189], v[46:49]
	v_mfma_f32_16x16x32_bf16 v[42:45], v[142:145], v[186:189], v[42:45]
	v_mfma_f32_16x16x32_bf16 v[30:33], v[134:137], v[212:215], v[30:33]
	v_mfma_f32_16x16x32_bf16 v[26:29], v[142:145], v[212:215], v[26:29]
	v_mfma_f32_16x16x32_bf16 v[14:17], v[134:137], v[220:223], v[14:17]
	v_mfma_f32_16x16x32_bf16 v[10:13], v[142:145], v[220:223], v[10:13]
	s_setprio 0
	s_setprio 1
	v_mfma_f32_16x16x32_bf16 v[54:57], v[146:149], v[168:171], v[54:57]
	v_mfma_f32_16x16x32_bf16 v[50:53], v[154:157], v[168:171], v[50:53]
	v_mfma_f32_16x16x32_bf16 v[38:41], v[146:149], v[176:179], v[38:41]
	v_mfma_f32_16x16x32_bf16 v[34:37], v[154:157], v[176:179], v[34:37]
	v_mfma_f32_16x16x32_bf16 v[22:25], v[146:149], v[190:193], v[22:25]
	v_mfma_f32_16x16x32_bf16 v[18:21], v[154:157], v[190:193], v[18:21]
	v_mfma_f32_16x16x32_bf16 v[6:9], v[146:149], v[216:219], v[6:9]
	v_mfma_f32_16x16x32_bf16 v[2:5], v[154:157], v[216:219], v[2:5]
	v_mfma_f32_16x16x32_bf16 v[54:57], v[150:153], v[172:175], v[54:57]
	v_mfma_f32_16x16x32_bf16 v[50:53], v[158:161], v[172:175], v[50:53]
	v_mfma_f32_16x16x32_bf16 v[38:41], v[150:153], v[186:189], v[38:41]
	v_mfma_f32_16x16x32_bf16 v[34:37], v[158:161], v[186:189], v[34:37]
	v_mfma_f32_16x16x32_bf16 v[22:25], v[150:153], v[212:215], v[22:25]
	v_mfma_f32_16x16x32_bf16 v[18:21], v[158:161], v[212:215], v[18:21]
	v_mfma_f32_16x16x32_bf16 v[6:9], v[150:153], v[220:223], v[6:9]
	v_mfma_f32_16x16x32_bf16 v[2:5], v[158:161], v[220:223], v[2:5]
	s_setprio 0
	s_barrier
	s_add_i32 s55, s55, 2
	s_add_u32 s41, s41, 0x100
	s_addc_u32 s54, s54, 0
	s_cmp_gt_u32 s55, 41
	s_mov_b64 s[18:19], s[20:21]
	s_cbranch_scc0 .LBB0_227
	v_readfirstlane_b32 s100, v238
	s_nop 3
	s_bfe_u32 s100, s100, 0x40006
	s_cmp_ge_u32 s100, 4
	s_cbranch_scc0 .Lepiprio_1
	s_setprio 1
.Lepiprio_1:
	s_and_b64 vcc, exec, s[12:13]
	s_cbranch_vccz .LBB0_230
	s_barrier

; #define PG8_STAGE(bufoff, gbase, voff) do { _Pragma("unroll") for (int _i = 0; _i < 2; ++_i) \
;         __builtin_amdgcn_global_load_lds((const unsigned*)((const char*)(gbase) + (voff)[_i]), (PG8_LAS unsigned*)(lds + (bufoff) + ldsw + _i * 8192), 16, 0, 0); } while (0)
; #define PG8_LDA(dst, b, h) do { _Pragma("unroll") for (int m = 0; m < 4; ++m) _Pragma("unroll") for (int k = 0; k < 2; ++k) dst[m][k] = *(const PG8_LAS bf16x8*)(lds + PG8_SA(b, h) + aoff + m * 2048 + k * 1024); } while (0)
; #define PG8_LDB(dst, b, h) do { _Pragma("unroll") for (int n = 0; n < 2; ++n) _Pragma("unroll") for (int k = 0; k < 2; ++k) dst[n][k] = *(const PG8_LAS bf16x8*)(lds + PG8_SB(b, h) + boff + n * 2048 + k * 1024); } while (0)
; #define PG8_MMA(ai, bj, At, Bt) do { __builtin_amdgcn_s_setprio(1); _Pragma("unroll") for (int m = 0; m < 4; ++m) _Pragma("unroll") for (int n = 0; n < 2; ++n) _Pragma("unroll") for (int k = 0; k < 2; ++k) \
;         acc[ai][bj][m][n] = __builtin_amdgcn_mfma_f32_16x16x32_bf16(Bt[n][k], At[m][k], acc[ai][bj][m][n], 0, 0, 0); __builtin_amdgcn_s_setprio(0); } while (0)
; #define PG8_WAIT_V(n) asm volatile("s_waitcnt vmcnt(" #n ")" ::: "memory")
; #define PG8_WAIT_L(n) asm volatile("s_waitcnt lgkmcnt(" #n ")" ::: "memory")
; #define PG8_BAR __builtin_amdgcn_s_barrier()
; #define PG8_SCHED __builtin_amdgcn_sched_barrier(0)
; template <class Epi, class Sched, bool ALIGN_EPI = false, bool SP2 = false>
; __device__ __forceinline__ void gemm_phase(PG8_LAS unsigned char* lds, const Gemm g, const Sched& S, const Epi& E) {
;     ...
;             PG8_LDB(B0, 0, 0); PG8_LDB(B1, 0, 1); PG8_SCHED; PG8_LDA(At, 0, 0); PG8_STAGE(PG8_SA(1, 1), a1 + hstepA, voffA);
;             PG8_WAIT_V(8); PG8_WAIT_L(0); PG8_BAR; PG8_MMA(0, 0, At, B0); PG8_MMA(0, 1, At, B1); PG8_BAR; PG8_SCHED;
;             PG8_LDA(At, 0, 1); PG8_STAGE(PG8_SB(0, 0), b2, voffB); PG8_STAGE(PG8_SB(0, 1), b2 + hstepB, voffB); PG8_STAGE(PG8_SA(0, 0), a2, voffA);
;             PG8_WAIT_V(8); PG8_WAIT_L(0); PG8_BAR; PG8_MMA(1, 0, At, B0); PG8_MMA(1, 1, At, B1); PG8_BAR; PG8_SCHED;
.LBB0_323:
	s_add_u32 s18, s16, 0xfffc0080
	s_addc_u32 s19, s17, -1
	s_add_i32 s47, 0, 0x10000
	s_cmp_eq_u32 s46, 12
	s_cselect_b32 s21, s9, s19
	s_cselect_b32 s20, s42, s18
	v_add_u32_e32 v0, s47, v179
	s_cselect_b32 s19, s7, s45
	s_cselect_b32 s18, s43, s44
	s_add_i32 s50, 0, 0x14000
	ds_read_b128 v[130:133], v0
	ds_read_b128 v[134:137], v0 offset:1024
	ds_read_b128 v[138:141], v0 offset:2048
	ds_read_b128 v[142:145], v0 offset:3072
	v_add_u32_e32 v0, s50, v179
	ds_read_b128 v[164:167], v0
	ds_read_b128 v[168:171], v0 offset:1024
	ds_read_b128 v[180:183], v0 offset:2048
	ds_read_b128 v[212:215], v0 offset:3072
	v_lshl_add_u64 v[172:173], s[16:17], 0, v[160:161]
	s_add_i32 m0, s30, 0xc000
	ds_read_b128 v[216:219], v193
	ds_read_b128 v[220:223], v193 offset:1024
	ds_read_b128 v[224:227], v193 offset:2048
	ds_read_b128 v[228:231], v193 offset:3072
	ds_read_b128 v[232:235], v193 offset:4096
	ds_read_b128 v[246:249], v193 offset:5120
	ds_read_b128 v[206:209], v193 offset:6144
	ds_read_b128 v[198:201], v193 offset:7168
	global_load_lds_dwordx4 v[172:173], off
	v_lshl_add_u64 v[172:173], s[16:17], 0, v[162:163]
	s_add_i32 m0, s30, 0xe000
	s_nop 0
	global_load_lds_dwordx4 v[172:173], off
	s_waitcnt vmcnt(8)
	s_waitcnt lgkmcnt(0)
	s_barrier
	s_setprio 1
	s_waitcnt lgkmcnt(0)
	v_mfma_f32_16x16x32_bf16 v[126:129], v[130:133], v[216:219], v[126:129]
	v_mfma_f32_16x16x32_bf16 v[122:125], v[138:141], v[216:219], v[122:125]
	v_mfma_f32_16x16x32_bf16 v[110:113], v[130:133], v[224:227], v[110:113]
	v_mfma_f32_16x16x32_bf16 v[106:109], v[138:141], v[224:227], v[106:109]
	v_mfma_f32_16x16x32_bf16 v[94:97], v[130:133], v[232:235], v[94:97]
	v_mfma_f32_16x16x32_bf16 v[90:93], v[138:141], v[232:235], v[90:93]
	v_mfma_f32_16x16x32_bf16 v[78:81], v[130:133], v[206:209], v[78:81]
	v_mfma_f32_16x16x32_bf16 v[74:77], v[138:141], v[206:209], v[74:77]
	v_mfma_f32_16x16x32_bf16 v[126:129], v[134:137], v[220:223], v[126:129]
	v_mfma_f32_16x16x32_bf16 v[122:125], v[142:145], v[220:223], v[122:125]
	v_mfma_f32_16x16x32_bf16 v[110:113], v[134:137], v[228:231], v[110:113]
	v_mfma_f32_16x16x32_bf16 v[106:109], v[142:145], v[228:231], v[106:109]
	v_mfma_f32_16x16x32_bf16 v[94:97], v[134:137], v[246:249], v[94:97]
	v_mfma_f32_16x16x32_bf16 v[90:93], v[142:145], v[246:249], v[90:93]
	v_mfma_f32_16x16x32_bf16 v[78:81], v[134:137], v[198:201], v[78:81]
	v_mfma_f32_16x16x32_bf16 v[74:77], v[142:145], v[198:201], v[74:77]
	s_setprio 0
	s_setprio 1
	v_mfma_f32_16x16x32_bf16 v[118:121], v[164:167], v[216:219], v[118:121]
	v_mfma_f32_16x16x32_bf16 v[114:117], v[180:183], v[216:219], v[114:117]
	v_mfma_f32_16x16x32_bf16 v[102:105], v[164:167], v[224:227], v[102:105]
	v_mfma_f32_16x16x32_bf16 v[98:101], v[180:183], v[224:227], v[98:101]
	v_mfma_f32_16x16x32_bf16 v[86:89], v[164:167], v[232:235], v[86:89]
	v_mfma_f32_16x16x32_bf16 v[82:85], v[180:183], v[232:235], v[82:85]
	v_mfma_f32_16x16x32_bf16 v[70:73], v[164:167], v[206:209], v[70:73]
	v_mfma_f32_16x16x32_bf16 v[66:69], v[180:183], v[206:209], v[66:69]
	v_mfma_f32_16x16x32_bf16 v[118:121], v[168:171], v[220:223], v[118:121]
	v_mfma_f32_16x16x32_bf16 v[114:117], v[212:215], v[220:223], v[114:117]
	v_mfma_f32_16x16x32_bf16 v[102:105], v[168:171], v[228:231], v[102:105]
	v_mfma_f32_16x16x32_bf16 v[98:101], v[212:215], v[228:231], v[98:101]
	v_mfma_f32_16x16x32_bf16 v[86:89], v[168:171], v[246:249], v[86:89]
	v_mfma_f32_16x16x32_bf16 v[82:85], v[212:215], v[246:249], v[82:85]
	v_mfma_f32_16x16x32_bf16 v[70:73], v[168:171], v[198:201], v[70:73]
	v_mfma_f32_16x16x32_bf16 v[66:69], v[212:215], v[198:201], v[66:69]
	s_setprio 0
	s_barrier
	s_add_i32 s47, s47, s28
	v_lshl_add_u64 v[172:173], s[18:19], 0, v[150:151]
	s_mov_b32 m0, s47
	ds_read_b128 v[198:201], v193 offset:16384
	ds_read_b128 v[206:209], v193 offset:17408
	ds_read_b128 v[216:219], v193 offset:18432
	ds_read_b128 v[220:223], v193 offset:19456
	ds_read_b128 v[224:227], v193 offset:20480
	ds_read_b128 v[228:231], v193 offset:21504
	ds_read_b128 v[232:235], v193 offset:22528
	ds_read_b128 v[246:249], v193 offset:23552
	global_load_lds_dwordx4 v[172:173], off
	s_add_i32 m0, s47, 0x2000
	s_add_u32 s48, s18, 0x40000
	v_lshl_add_u64 v[176:177], s[18:19], 0, v[146:147]
	s_addc_u32 s49, s19, 0
	s_add_i32 s47, s50, s28
	global_load_lds_dwordx4 v[176:177], off
	v_lshl_add_u64 v[184:185], s[48:49], 0, v[150:151]
	s_mov_b32 m0, s47
	v_lshl_add_u64 v[190:191], s[20:21], 0, v[148:149]
	global_load_lds_dwordx4 v[184:185], off
	v_lshl_add_u64 v[184:185], s[48:49], 0, v[146:147]
	s_add_i32 m0, s47, 0x2000
	s_nop 0
	global_load_lds_dwordx4 v[184:185], off
	v_lshl_add_u64 v[184:185], s[20:21], 0, v[152:153]
	s_mov_b32 m0, s30
	s_nop 0
	global_load_lds_dwordx4 v[184:185], off
	s_mov_b32 m0, s31
	s_nop 0
	global_load_lds_dwordx4 v[190:191], off
	s_waitcnt vmcnt(8)
	s_waitcnt lgkmcnt(0)
	s_barrier
; #define PG8_STAGE(bufoff, gbase, voff) do { _Pragma("unroll") for (int _i = 0; _i < 2; ++_i) \
;         __builtin_amdgcn_global_load_lds((const unsigned*)((const char*)(gbase) + (voff)[_i]), (PG8_LAS unsigned*)(lds + (bufoff) + ldsw + _i * 8192), 16, 0, 0); } while (0)
; #define PG8_LDA(dst, b, h) do { _Pragma("unroll") for (int m = 0; m < 4; ++m) _Pragma("unroll") for (int k = 0; k < 2; ++k) dst[m][k] = *(const PG8_LAS bf16x8*)(lds + PG8_SA(b, h) + aoff + m * 2048 + k * 1024); } while (0)
; #define PG8_LDB(dst, b, h) do { _Pragma("unroll") for (int n = 0; n < 2; ++n) _Pragma("unroll") for (int k = 0; k < 2; ++k) dst[n][k] = *(const PG8_LAS bf16x8*)(lds + PG8_SB(b, h) + boff + n * 2048 + k * 1024); } while (0)
; #define PG8_MMA(ai, bj, At, Bt) do { __builtin_amdgcn_s_setprio(1); _Pragma("unroll") for (int m = 0; m < 4; ++m) _Pragma("unroll") for (int n = 0; n < 2; ++n) _Pragma("unroll") for (int k = 0; k < 2; ++k) \
;         acc[ai][bj][m][n] = __builtin_amdgcn_mfma_f32_16x16x32_bf16(Bt[n][k], At[m][k], acc[ai][bj][m][n], 0, 0, 0); __builtin_amdgcn_s_setprio(0); } while (0)
; #define PG8_WAIT_V(n) asm volatile("s_waitcnt vmcnt(" #n ")" ::: "memory")
; #define PG8_WAIT_L(n) asm volatile("s_waitcnt lgkmcnt(" #n ")" ::: "memory")
; #define PG8_BAR __builtin_amdgcn_s_barrier()
; #define PG8_SCHED __builtin_amdgcn_sched_barrier(0)
; template <class Epi, class Sched, bool ALIGN_EPI = false, bool SP2 = false>
; __device__ __forceinline__ void gemm_phase(PG8_LAS unsigned char* lds, const Gemm g, const Sched& S, const Epi& E) {
;     ...
;             PG8_WAIT_V(8); PG8_WAIT_L(0); PG8_BAR; PG8_MMA(1, 0, At, B0); PG8_MMA(1, 1, At, B1); PG8_BAR; PG8_SCHED;
;             PG8_LDB(B0, 1, 0); PG8_LDB(B1, 1, 1); PG8_SCHED; PG8_LDA(At, 1, 0); PG8_STAGE(PG8_SA(0, 1), a2 + hstepA, voffA);
;             PG8_WAIT_V(8); PG8_WAIT_L(0); PG8_BAR; PG8_MMA(0, 0, At, B0); PG8_MMA(0, 1, At, B1); PG8_BAR; PG8_SCHED;
;             PG8_LDA(At, 1, 1); PG8_STAGE(PG8_SB(1, 0), b3, voffB); PG8_STAGE(PG8_SB(1, 1), b3 + hstepB, voffB); PG8_STAGE(PG8_SA(1, 0), a3, voffA);
	s_setprio 1
	s_waitcnt lgkmcnt(0)
	v_mfma_f32_16x16x32_bf16 v[62:65], v[130:133], v[198:201], v[62:65]
	v_mfma_f32_16x16x32_bf16 v[58:61], v[138:141], v[198:201], v[58:61]
	v_mfma_f32_16x16x32_bf16 v[46:49], v[130:133], v[216:219], v[46:49]
	v_mfma_f32_16x16x32_bf16 v[42:45], v[138:141], v[216:219], v[42:45]
	v_mfma_f32_16x16x32_bf16 v[30:33], v[130:133], v[224:227], v[30:33]
	v_mfma_f32_16x16x32_bf16 v[26:29], v[138:141], v[224:227], v[26:29]
	v_mfma_f32_16x16x32_bf16 v[14:17], v[130:133], v[232:235], v[14:17]
	v_mfma_f32_16x16x32_bf16 v[10:13], v[138:141], v[232:235], v[10:13]
	v_mfma_f32_16x16x32_bf16 v[62:65], v[134:137], v[206:209], v[62:65]
	v_mfma_f32_16x16x32_bf16 v[58:61], v[142:145], v[206:209], v[58:61]
	v_mfma_f32_16x16x32_bf16 v[46:49], v[134:137], v[220:223], v[46:49]
	v_mfma_f32_16x16x32_bf16 v[42:45], v[142:145], v[220:223], v[42:45]
	v_mfma_f32_16x16x32_bf16 v[30:33], v[134:137], v[228:231], v[30:33]
	v_mfma_f32_16x16x32_bf16 v[26:29], v[142:145], v[228:231], v[26:29]
	v_mfma_f32_16x16x32_bf16 v[14:17], v[134:137], v[246:249], v[14:17]
	v_mfma_f32_16x16x32_bf16 v[10:13], v[142:145], v[246:249], v[10:13]
	s_setprio 0
	s_setprio 1
	v_mfma_f32_16x16x32_bf16 v[54:57], v[164:167], v[198:201], v[54:57]
	v_mfma_f32_16x16x32_bf16 v[50:53], v[180:183], v[198:201], v[50:53]
	v_mfma_f32_16x16x32_bf16 v[38:41], v[164:167], v[216:219], v[38:41]
	v_mfma_f32_16x16x32_bf16 v[34:37], v[180:183], v[216:219], v[34:37]
	v_mfma_f32_16x16x32_bf16 v[22:25], v[164:167], v[224:227], v[22:25]
	v_mfma_f32_16x16x32_bf16 v[18:21], v[180:183], v[224:227], v[18:21]
	v_mfma_f32_16x16x32_bf16 v[6:9], v[164:167], v[232:235], v[6:9]
	v_mfma_f32_16x16x32_bf16 v[2:5], v[180:183], v[232:235], v[2:5]
	v_mfma_f32_16x16x32_bf16 v[54:57], v[168:171], v[206:209], v[54:57]
	v_mfma_f32_16x16x32_bf16 v[50:53], v[212:215], v[206:209], v[50:53]
	v_mfma_f32_16x16x32_bf16 v[38:41], v[168:171], v[220:223], v[38:41]
	v_mfma_f32_16x16x32_bf16 v[34:37], v[212:215], v[220:223], v[34:37]
	v_mfma_f32_16x16x32_bf16 v[22:25], v[168:171], v[228:231], v[22:25]
	v_mfma_f32_16x16x32_bf16 v[18:21], v[212:215], v[228:231], v[18:21]
	v_mfma_f32_16x16x32_bf16 v[6:9], v[168:171], v[246:249], v[6:9]
	v_mfma_f32_16x16x32_bf16 v[2:5], v[212:215], v[246:249], v[2:5]
	s_setprio 0
	s_barrier
	s_add_i32 s47, 0, 0x18000
	v_add_u32_e32 v0, s47, v179
	s_add_i32 s48, 0, 0x1c000
	ds_read_b128 v[130:133], v0
	ds_read_b128 v[134:137], v0 offset:1024
	ds_read_b128 v[138:141], v0 offset:2048
	ds_read_b128 v[142:145], v0 offset:3072
	v_add_u32_e32 v0, s48, v179
	ds_read_b128 v[164:167], v0
	ds_read_b128 v[168:171], v0 offset:1024
	ds_read_b128 v[180:183], v0 offset:2048
	ds_read_b128 v[198:201], v0 offset:3072
	s_add_u32 s20, s20, 0x40000
	s_addc_u32 s21, s21, 0
	s_mov_b32 m0, s34
	v_lshl_add_u64 v[236:237], s[20:21], 0, v[152:153]
	ds_read_b128 v[206:209], v193 offset:32768
	ds_read_b128 v[212:215], v193 offset:33792
	ds_read_b128 v[216:219], v193 offset:34816
	ds_read_b128 v[220:223], v193 offset:35840
	ds_read_b128 v[224:227], v193 offset:36864
	ds_read_b128 v[228:231], v193 offset:37888
	ds_read_b128 v[232:235], v193 offset:38912
	ds_read_b128 v[246:249], v193 offset:39936
	global_load_lds_dwordx4 v[236:237], off
	v_lshl_add_u64 v[236:237], s[20:21], 0, v[148:149]
	s_mov_b32 m0, s35
	s_nop 0
	global_load_lds_dwordx4 v[236:237], off
	s_waitcnt vmcnt(8)
	s_waitcnt lgkmcnt(0)
	s_barrier
	s_setprio 1
	s_waitcnt lgkmcnt(0)
	v_mfma_f32_16x16x32_bf16 v[126:129], v[130:133], v[206:209], v[126:129]
	v_mfma_f32_16x16x32_bf16 v[122:125], v[138:141], v[206:209], v[122:125]
	v_mfma_f32_16x16x32_bf16 v[110:113], v[130:133], v[216:219], v[110:113]
	v_mfma_f32_16x16x32_bf16 v[106:109], v[138:141], v[216:219], v[106:109]
	v_mfma_f32_16x16x32_bf16 v[94:97], v[130:133], v[224:227], v[94:97]
	v_mfma_f32_16x16x32_bf16 v[90:93], v[138:141], v[224:227], v[90:93]
	v_mfma_f32_16x16x32_bf16 v[78:81], v[130:133], v[232:235], v[78:81]
	v_mfma_f32_16x16x32_bf16 v[74:77], v[138:141], v[232:235], v[74:77]
	v_mfma_f32_16x16x32_bf16 v[126:129], v[134:137], v[212:215], v[126:129]
	v_mfma_f32_16x16x32_bf16 v[122:125], v[142:145], v[212:215], v[122:125]
	v_mfma_f32_16x16x32_bf16 v[110:113], v[134:137], v[220:223], v[110:113]
	v_mfma_f32_16x16x32_bf16 v[106:109], v[142:145], v[220:223], v[106:109]
	v_mfma_f32_16x16x32_bf16 v[94:97], v[134:137], v[228:231], v[94:97]
	v_mfma_f32_16x16x32_bf16 v[90:93], v[142:145], v[228:231], v[90:93]
	v_mfma_f32_16x16x32_bf16 v[78:81], v[134:137], v[246:249], v[78:81]
	v_mfma_f32_16x16x32_bf16 v[74:77], v[142:145], v[246:249], v[74:77]
	s_setprio 0
	s_setprio 1
	v_mfma_f32_16x16x32_bf16 v[118:121], v[164:167], v[206:209], v[118:121]
	v_mfma_f32_16x16x32_bf16 v[114:117], v[180:183], v[206:209], v[114:117]
	v_mfma_f32_16x16x32_bf16 v[102:105], v[164:167], v[216:219], v[102:105]
	v_mfma_f32_16x16x32_bf16 v[98:101], v[180:183], v[216:219], v[98:101]
	v_mfma_f32_16x16x32_bf16 v[86:89], v[164:167], v[224:227], v[86:89]
	v_mfma_f32_16x16x32_bf16 v[82:85], v[180:183], v[224:227], v[82:85]
	v_mfma_f32_16x16x32_bf16 v[70:73], v[164:167], v[232:235], v[70:73]
	v_mfma_f32_16x16x32_bf16 v[66:69], v[180:183], v[232:235], v[66:69]
	v_mfma_f32_16x16x32_bf16 v[118:121], v[168:171], v[212:215], v[118:121]
	v_mfma_f32_16x16x32_bf16 v[114:117], v[198:201], v[212:215], v[114:117]
	v_mfma_f32_16x16x32_bf16 v[102:105], v[168:171], v[220:223], v[102:105]
	v_mfma_f32_16x16x32_bf16 v[98:101], v[198:201], v[220:223], v[98:101]
	v_mfma_f32_16x16x32_bf16 v[86:89], v[168:171], v[228:231], v[86:89]
	v_mfma_f32_16x16x32_bf16 v[82:85], v[198:201], v[228:231], v[82:85]
	v_mfma_f32_16x16x32_bf16 v[70:73], v[168:171], v[246:249], v[70:73]
	v_mfma_f32_16x16x32_bf16 v[66:69], v[198:201], v[246:249], v[66:69]
	s_setprio 0
	s_barrier
; #define PG8_STAGE(bufoff, gbase, voff) do { _Pragma("unroll") for (int _i = 0; _i < 2; ++_i) \
;         __builtin_amdgcn_global_load_lds((const unsigned*)((const char*)(gbase) + (voff)[_i]), (PG8_LAS unsigned*)(lds + (bufoff) + ldsw + _i * 8192), 16, 0, 0); } while (0)
; #define PG8_LDA(dst, b, h) do { _Pragma("unroll") for (int m = 0; m < 4; ++m) _Pragma("unroll") for (int k = 0; k < 2; ++k) dst[m][k] = *(const PG8_LAS bf16x8*)(lds + PG8_SA(b, h) + aoff + m * 2048 + k * 1024); } while (0)
; #define PG8_MMA(ai, bj, At, Bt) do { __builtin_amdgcn_s_setprio(1); _Pragma("unroll") for (int m = 0; m < 4; ++m) _Pragma("unroll") for (int n = 0; n < 2; ++n) _Pragma("unroll") for (int k = 0; k < 2; ++k) \
;         acc[ai][bj][m][n] = __builtin_amdgcn_mfma_f32_16x16x32_bf16(Bt[n][k], At[m][k], acc[ai][bj][m][n], 0, 0, 0); __builtin_amdgcn_s_setprio(0); } while (0)
; #define PG8_WAIT_V(n) asm volatile("s_waitcnt vmcnt(" #n ")" ::: "memory")
; #define PG8_WAIT_L(n) asm volatile("s_waitcnt lgkmcnt(" #n ")" ::: "memory")
; #define PG8_BAR __builtin_amdgcn_s_barrier()
; #define PG8_SCHED __builtin_amdgcn_sched_barrier(0)
; template <class Epi, class Sched, bool ALIGN_EPI = false, bool SP2 = false>
; __device__ __forceinline__ void gemm_phase(PG8_LAS unsigned char* lds, const Gemm g, const Sched& S, const Epi& E) {
;     ...
;             PG8_LDA(At, 1, 1); PG8_STAGE(PG8_SB(1, 0), b3, voffB); PG8_STAGE(PG8_SB(1, 1), b3 + hstepB, voffB); PG8_STAGE(PG8_SA(1, 0), a3, voffA);
;             PG8_WAIT_V(8); PG8_WAIT_L(0); PG8_BAR; PG8_MMA(1, 0, At, B0); PG8_MMA(1, 1, At, B1); PG8_BAR; PG8_SCHED;
;     ...
;         if constexpr (ALIGN_EPI) { if (wr == 0) PG8_BAR; }
	s_add_i32 s20, s47, s28
	v_lshl_add_u64 v[172:173], v[172:173], 0, s[88:89]
	s_mov_b32 m0, s20
	ds_read_b128 v[206:209], v193 offset:49152
	ds_read_b128 v[212:215], v193 offset:50176
	ds_read_b128 v[216:219], v193 offset:51200
	ds_read_b128 v[220:223], v193 offset:52224
	ds_read_b128 v[224:227], v193 offset:53248
	ds_read_b128 v[228:231], v193 offset:54272
	ds_read_b128 v[232:235], v193 offset:55296
	ds_read_b128 v[246:249], v193 offset:56320
	global_load_lds_dwordx4 v[172:173], off
	s_add_i32 m0, s20, 0x2000
	s_add_u32 s18, s18, 0x40080
	v_lshl_add_u64 v[172:173], v[176:177], 0, s[88:89]
	s_addc_u32 s19, s19, 0
	s_add_i32 s20, s48, s28
	global_load_lds_dwordx4 v[172:173], off
	v_lshl_add_u64 v[172:173], s[18:19], 0, v[150:151]
	s_mov_b32 m0, s20
	s_nop 0
	global_load_lds_dwordx4 v[172:173], off
	v_lshl_add_u64 v[172:173], s[18:19], 0, v[146:147]
	s_add_i32 m0, s20, 0x2000
	s_nop 0
	global_load_lds_dwordx4 v[172:173], off
	v_lshl_add_u64 v[172:173], v[184:185], 0, s[88:89]
	s_mov_b32 m0, s38
	s_nop 0
	global_load_lds_dwordx4 v[172:173], off
	v_lshl_add_u64 v[172:173], v[190:191], 0, s[88:89]
	s_mov_b32 m0, s39
	s_nop 0
	global_load_lds_dwordx4 v[172:173], off
	s_waitcnt vmcnt(8)
	s_waitcnt lgkmcnt(0)
	s_barrier
	s_setprio 1
	s_waitcnt lgkmcnt(0)
	v_mfma_f32_16x16x32_bf16 v[62:65], v[130:133], v[206:209], v[62:65]
	v_mfma_f32_16x16x32_bf16 v[58:61], v[138:141], v[206:209], v[58:61]
	v_mfma_f32_16x16x32_bf16 v[46:49], v[130:133], v[216:219], v[46:49]
	v_mfma_f32_16x16x32_bf16 v[42:45], v[138:141], v[216:219], v[42:45]
	v_mfma_f32_16x16x32_bf16 v[30:33], v[130:133], v[224:227], v[30:33]
	v_mfma_f32_16x16x32_bf16 v[26:29], v[138:141], v[224:227], v[26:29]
	v_mfma_f32_16x16x32_bf16 v[14:17], v[130:133], v[232:235], v[14:17]
	v_mfma_f32_16x16x32_bf16 v[10:13], v[138:141], v[232:235], v[10:13]
	v_mfma_f32_16x16x32_bf16 v[62:65], v[134:137], v[212:215], v[62:65]
	v_mfma_f32_16x16x32_bf16 v[58:61], v[142:145], v[212:215], v[58:61]
	v_mfma_f32_16x16x32_bf16 v[46:49], v[134:137], v[220:223], v[46:49]
	v_mfma_f32_16x16x32_bf16 v[42:45], v[142:145], v[220:223], v[42:45]
	v_mfma_f32_16x16x32_bf16 v[30:33], v[134:137], v[228:231], v[30:33]
	v_mfma_f32_16x16x32_bf16 v[26:29], v[142:145], v[228:231], v[26:29]
	v_mfma_f32_16x16x32_bf16 v[14:17], v[134:137], v[246:249], v[14:17]
	v_mfma_f32_16x16x32_bf16 v[10:13], v[142:145], v[246:249], v[10:13]
	s_setprio 0
	s_setprio 1
	v_mfma_f32_16x16x32_bf16 v[54:57], v[164:167], v[206:209], v[54:57]
	v_mfma_f32_16x16x32_bf16 v[50:53], v[180:183], v[206:209], v[50:53]
	v_mfma_f32_16x16x32_bf16 v[38:41], v[164:167], v[216:219], v[38:41]
	v_mfma_f32_16x16x32_bf16 v[34:37], v[180:183], v[216:219], v[34:37]
	v_mfma_f32_16x16x32_bf16 v[22:25], v[164:167], v[224:227], v[22:25]
	v_mfma_f32_16x16x32_bf16 v[18:21], v[180:183], v[224:227], v[18:21]
	v_mfma_f32_16x16x32_bf16 v[6:9], v[164:167], v[232:235], v[6:9]
	v_mfma_f32_16x16x32_bf16 v[2:5], v[180:183], v[232:235], v[2:5]
	v_mfma_f32_16x16x32_bf16 v[54:57], v[168:171], v[212:215], v[54:57]
	v_mfma_f32_16x16x32_bf16 v[50:53], v[198:201], v[212:215], v[50:53]
	v_mfma_f32_16x16x32_bf16 v[38:41], v[168:171], v[220:223], v[38:41]
	v_mfma_f32_16x16x32_bf16 v[34:37], v[198:201], v[220:223], v[34:37]
	v_mfma_f32_16x16x32_bf16 v[22:25], v[168:171], v[228:231], v[22:25]
	v_mfma_f32_16x16x32_bf16 v[18:21], v[198:201], v[228:231], v[18:21]
	v_mfma_f32_16x16x32_bf16 v[6:9], v[168:171], v[246:249], v[6:9]
	v_mfma_f32_16x16x32_bf16 v[2:5], v[198:201], v[246:249], v[2:5]
	s_setprio 0
	s_barrier
	s_add_i32 s46, s46, 2
	s_add_u32 s16, s16, 0x100
	s_addc_u32 s17, s17, 0
	s_add_u32 s44, s44, 0x100
	s_addc_u32 s45, s45, 0
	s_cmp_gt_u32 s46, 13
	s_cbranch_scc0 .LBB0_323
	v_readfirstlane_b32 s100, v238
	s_nop 3
	s_bfe_u32 s100, s100, 0x40006
	s_cmp_ge_u32 s100, 4
	s_cbranch_scc0 .Lepiprio_2
	s_setprio 1
.Lepiprio_2:
	s_and_b64 vcc, exec, s[4:5]
	s_cbranch_vccz .LBB0_326
	s_barrier

; #define PG8_STAGE(bufoff, gbase, voff) do { _Pragma("unroll") for (int _i = 0; _i < 2; ++_i) \
;         __builtin_amdgcn_global_load_lds((const unsigned*)((const char*)(gbase) + (voff)[_i]), (PG8_LAS unsigned*)(lds + (bufoff) + ldsw + _i * 8192), 16, 0, 0); } while (0)
; #define PG8_LDA(dst, b, h) do { _Pragma("unroll") for (int m = 0; m < 4; ++m) _Pragma("unroll") for (int k = 0; k < 2; ++k) dst[m][k] = *(const PG8_LAS bf16x8*)(lds + PG8_SA(b, h) + aoff + m * 2048 + k * 1024); } while (0)
; #define PG8_LDB(dst, b, h) do { _Pragma("unroll") for (int n = 0; n < 2; ++n) _Pragma("unroll") for (int k = 0; k < 2; ++k) dst[n][k] = *(const PG8_LAS bf16x8*)(lds + PG8_SB(b, h) + boff + n * 2048 + k * 1024); } while (0)
; #define PG8_MMA(ai, bj, At, Bt) do { __builtin_amdgcn_s_setprio(1); _Pragma("unroll") for (int m = 0; m < 4; ++m) _Pragma("unroll") for (int n = 0; n < 2; ++n) _Pragma("unroll") for (int k = 0; k < 2; ++k) \
;         acc[ai][bj][m][n] = __builtin_amdgcn_mfma_f32_16x16x32_bf16(Bt[n][k], At[m][k], acc[ai][bj][m][n], 0, 0, 0); __builtin_amdgcn_s_setprio(0); } while (0)
; #define PG8_WAIT_V(n) asm volatile("s_waitcnt vmcnt(" #n ")" ::: "memory")
; #define PG8_WAIT_L(n) asm volatile("s_waitcnt lgkmcnt(" #n ")" ::: "memory")
; #define PG8_BAR __builtin_amdgcn_s_barrier()
; #define PG8_SCHED __builtin_amdgcn_sched_barrier(0)
; template <class Epi, class Sched, bool ALIGN_EPI = false, bool SP2 = false>
; __device__ __forceinline__ void gemm_phase(PG8_LAS unsigned char* lds, const Gemm g, const Sched& S, const Epi& E) {
;     ...
;             PG8_LDB(B0, 0, 0); PG8_LDB(B1, 0, 1); PG8_SCHED; PG8_LDA(At, 0, 0); PG8_STAGE(PG8_SA(1, 1), a1 + hstepA, voffA);
;             PG8_WAIT_V(8); PG8_WAIT_L(0); PG8_BAR; PG8_MMA(0, 0, At, B0); PG8_MMA(0, 1, At, B1); PG8_BAR; PG8_SCHED;
;             PG8_LDA(At, 0, 1); PG8_STAGE(PG8_SB(0, 0), b2, voffB); PG8_STAGE(PG8_SB(0, 1), b2 + hstepB, voffB); PG8_STAGE(PG8_SA(0, 0), a2, voffA);
;             PG8_WAIT_V(8); PG8_WAIT_L(0); PG8_BAR; PG8_MMA(1, 0, At, B0); PG8_MMA(1, 1, At, B1); PG8_BAR; PG8_SCHED;
.LBB0_457:
	s_add_u32 s18, s16, 0xfffc0080
	s_addc_u32 s19, s17, -1
	s_add_i32 s47, 0, 0x10000
	s_cmp_eq_u32 s46, 12
	s_cselect_b32 s21, s9, s19
	s_cselect_b32 s20, s42, s18
	s_cselect_b32 s19, s7, s45
	s_cselect_b32 s18, s43, s44
	s_add_i32 s50, 0, 0x14000
	v_add_u32_e32 v154, s47, v173
	v_add_u32_e32 v170, s50, v173
	ds_read_b128 v[130:133], v154
	ds_read_b128 v[134:137], v154 offset:1024
	ds_read_b128 v[138:141], v154 offset:2048
	ds_read_b128 v[154:157], v154 offset:3072
	ds_read_b128 v[158:161], v170
	ds_read_b128 v[162:165], v170 offset:1024
	ds_read_b128 v[166:169], v170 offset:2048
	ds_read_b128 v[178:181], v170 offset:3072
	v_lshl_add_u64 v[224:225], s[16:17], 0, v[150:151]
	s_add_i32 m0, s30, 0xc000
	ds_read_b128 v[182:185], v177
	ds_read_b128 v[186:189], v177 offset:1024
	ds_read_b128 v[190:193], v177 offset:2048
	ds_read_b128 v[198:201], v177 offset:3072
	ds_read_b128 v[206:209], v177 offset:4096
	ds_read_b128 v[212:215], v177 offset:5120
	ds_read_b128 v[216:219], v177 offset:6144
	ds_read_b128 v[220:223], v177 offset:7168
	global_load_lds_dwordx4 v[224:225], off
	v_lshl_add_u64 v[224:225], s[16:17], 0, v[152:153]
	s_add_i32 m0, s30, 0xe000
	s_nop 0
	global_load_lds_dwordx4 v[224:225], off
	s_waitcnt vmcnt(8)
	s_waitcnt lgkmcnt(0)
	s_barrier
	s_setprio 1
	s_waitcnt lgkmcnt(0)
	v_mfma_f32_16x16x32_bf16 v[126:129], v[130:133], v[182:185], v[126:129]
	v_mfma_f32_16x16x32_bf16 v[122:125], v[138:141], v[182:185], v[122:125]
	v_mfma_f32_16x16x32_bf16 v[118:121], v[130:133], v[190:193], v[118:121]
	v_mfma_f32_16x16x32_bf16 v[110:113], v[138:141], v[190:193], v[110:113]
	v_mfma_f32_16x16x32_bf16 v[102:105], v[130:133], v[206:209], v[102:105]
	v_mfma_f32_16x16x32_bf16 v[94:97], v[138:141], v[206:209], v[94:97]
	v_mfma_f32_16x16x32_bf16 v[86:89], v[130:133], v[216:219], v[86:89]
	v_mfma_f32_16x16x32_bf16 v[78:81], v[138:141], v[216:219], v[78:81]
	v_mfma_f32_16x16x32_bf16 v[126:129], v[134:137], v[186:189], v[126:129]
	v_mfma_f32_16x16x32_bf16 v[122:125], v[154:157], v[186:189], v[122:125]
	v_mfma_f32_16x16x32_bf16 v[118:121], v[134:137], v[198:201], v[118:121]
	v_mfma_f32_16x16x32_bf16 v[110:113], v[154:157], v[198:201], v[110:113]
	v_mfma_f32_16x16x32_bf16 v[102:105], v[134:137], v[212:215], v[102:105]
	v_mfma_f32_16x16x32_bf16 v[94:97], v[154:157], v[212:215], v[94:97]
	v_mfma_f32_16x16x32_bf16 v[86:89], v[134:137], v[220:223], v[86:89]
	v_mfma_f32_16x16x32_bf16 v[78:81], v[154:157], v[220:223], v[78:81]
	s_setprio 0
	s_setprio 1
	v_mfma_f32_16x16x32_bf16 v[114:117], v[158:161], v[182:185], v[114:117]
	v_mfma_f32_16x16x32_bf16 v[106:109], v[166:169], v[182:185], v[106:109]
	v_mfma_f32_16x16x32_bf16 v[98:101], v[158:161], v[190:193], v[98:101]
	v_mfma_f32_16x16x32_bf16 v[90:93], v[166:169], v[190:193], v[90:93]
	v_mfma_f32_16x16x32_bf16 v[82:85], v[158:161], v[206:209], v[82:85]
	v_mfma_f32_16x16x32_bf16 v[74:77], v[166:169], v[206:209], v[74:77]
	v_mfma_f32_16x16x32_bf16 v[70:73], v[158:161], v[216:219], v[70:73]
	v_mfma_f32_16x16x32_bf16 v[66:69], v[166:169], v[216:219], v[66:69]
	v_mfma_f32_16x16x32_bf16 v[114:117], v[162:165], v[186:189], v[114:117]
	v_mfma_f32_16x16x32_bf16 v[106:109], v[178:181], v[186:189], v[106:109]
	v_mfma_f32_16x16x32_bf16 v[98:101], v[162:165], v[198:201], v[98:101]
	v_mfma_f32_16x16x32_bf16 v[90:93], v[178:181], v[198:201], v[90:93]
	v_mfma_f32_16x16x32_bf16 v[82:85], v[162:165], v[212:215], v[82:85]
	v_mfma_f32_16x16x32_bf16 v[74:77], v[178:181], v[212:215], v[74:77]
	v_mfma_f32_16x16x32_bf16 v[70:73], v[162:165], v[220:223], v[70:73]
	v_mfma_f32_16x16x32_bf16 v[66:69], v[178:181], v[220:223], v[66:69]
	s_setprio 0
	s_barrier
	s_add_i32 s47, s47, s29
	v_lshl_add_u64 v[224:225], s[18:19], 0, v[0:1]
	s_mov_b32 m0, s47
	ds_read_b128 v[182:185], v177 offset:16384
	ds_read_b128 v[186:189], v177 offset:17408
	ds_read_b128 v[190:193], v177 offset:18432
	ds_read_b128 v[198:201], v177 offset:19456
	ds_read_b128 v[206:209], v177 offset:20480
	ds_read_b128 v[212:215], v177 offset:21504
	ds_read_b128 v[216:219], v177 offset:22528
	ds_read_b128 v[220:223], v177 offset:23552
	global_load_lds_dwordx4 v[224:225], off
	s_add_i32 m0, s47, 0x2000
	s_add_u32 s48, s18, 0x40000
	v_lshl_add_u64 v[226:227], s[18:19], 0, v[146:147]
	s_addc_u32 s49, s19, 0
	s_add_i32 s47, s50, s29
	global_load_lds_dwordx4 v[226:227], off
	v_lshl_add_u64 v[228:229], s[48:49], 0, v[0:1]
	s_mov_b32 m0, s47
	v_lshl_add_u64 v[230:231], s[20:21], 0, v[144:145]
	global_load_lds_dwordx4 v[228:229], off
	v_lshl_add_u64 v[228:229], s[48:49], 0, v[146:147]
	s_add_i32 m0, s47, 0x2000
	s_nop 0
	global_load_lds_dwordx4 v[228:229], off
	v_lshl_add_u64 v[228:229], s[20:21], 0, v[142:143]
	s_mov_b32 m0, s30
	s_nop 0
	global_load_lds_dwordx4 v[228:229], off
	s_mov_b32 m0, s31
	s_nop 0
	global_load_lds_dwordx4 v[230:231], off
	s_waitcnt vmcnt(8)
	s_waitcnt lgkmcnt(0)
	s_barrier
; #define PG8_STAGE(bufoff, gbase, voff) do { _Pragma("unroll") for (int _i = 0; _i < 2; ++_i) \
;         __builtin_amdgcn_global_load_lds((const unsigned*)((const char*)(gbase) + (voff)[_i]), (PG8_LAS unsigned*)(lds + (bufoff) + ldsw + _i * 8192), 16, 0, 0); } while (0)
; #define PG8_LDA(dst, b, h) do { _Pragma("unroll") for (int m = 0; m < 4; ++m) _Pragma("unroll") for (int k = 0; k < 2; ++k) dst[m][k] = *(const PG8_LAS bf16x8*)(lds + PG8_SA(b, h) + aoff + m * 2048 + k * 1024); } while (0)
; #define PG8_LDB(dst, b, h) do { _Pragma("unroll") for (int n = 0; n < 2; ++n) _Pragma("unroll") for (int k = 0; k < 2; ++k) dst[n][k] = *(const PG8_LAS bf16x8*)(lds + PG8_SB(b, h) + boff + n * 2048 + k * 1024); } while (0)
; #define PG8_MMA(ai, bj, At, Bt) do { __builtin_amdgcn_s_setprio(1); _Pragma("unroll") for (int m = 0; m < 4; ++m) _Pragma("unroll") for (int n = 0; n < 2; ++n) _Pragma("unroll") for (int k = 0; k < 2; ++k) \
;         acc[ai][bj][m][n] = __builtin_amdgcn_mfma_f32_16x16x32_bf16(Bt[n][k], At[m][k], acc[ai][bj][m][n], 0, 0, 0); __builtin_amdgcn_s_setprio(0); } while (0)
; #define PG8_WAIT_V(n) asm volatile("s_waitcnt vmcnt(" #n ")" ::: "memory")
; #define PG8_WAIT_L(n) asm volatile("s_waitcnt lgkmcnt(" #n ")" ::: "memory")
; #define PG8_BAR __builtin_amdgcn_s_barrier()
; #define PG8_SCHED __builtin_amdgcn_sched_barrier(0)
; template <class Epi, class Sched, bool ALIGN_EPI = false, bool SP2 = false>
; __device__ __forceinline__ void gemm_phase(PG8_LAS unsigned char* lds, const Gemm g, const Sched& S, const Epi& E) {
;     ...
;             PG8_WAIT_V(8); PG8_WAIT_L(0); PG8_BAR; PG8_MMA(1, 0, At, B0); PG8_MMA(1, 1, At, B1); PG8_BAR; PG8_SCHED;
;             PG8_LDB(B0, 1, 0); PG8_LDB(B1, 1, 1); PG8_SCHED; PG8_LDA(At, 1, 0); PG8_STAGE(PG8_SA(0, 1), a2 + hstepA, voffA);
;             PG8_WAIT_V(8); PG8_WAIT_L(0); PG8_BAR; PG8_MMA(0, 0, At, B0); PG8_MMA(0, 1, At, B1); PG8_BAR; PG8_SCHED;
;             PG8_LDA(At, 1, 1); PG8_STAGE(PG8_SB(1, 0), b3, voffB); PG8_STAGE(PG8_SB(1, 1), b3 + hstepB, voffB); PG8_STAGE(PG8_SA(1, 0), a3, voffA);
	s_setprio 1
	s_waitcnt lgkmcnt(0)
	v_mfma_f32_16x16x32_bf16 v[62:65], v[130:133], v[182:185], v[62:65]
	v_mfma_f32_16x16x32_bf16 v[58:61], v[138:141], v[182:185], v[58:61]
	v_mfma_f32_16x16x32_bf16 v[54:57], v[130:133], v[190:193], v[54:57]
	v_mfma_f32_16x16x32_bf16 v[46:49], v[138:141], v[190:193], v[46:49]
	v_mfma_f32_16x16x32_bf16 v[38:41], v[130:133], v[206:209], v[38:41]
	v_mfma_f32_16x16x32_bf16 v[30:33], v[138:141], v[206:209], v[30:33]
	v_mfma_f32_16x16x32_bf16 v[22:25], v[130:133], v[216:219], v[22:25]
	v_mfma_f32_16x16x32_bf16 v[14:17], v[138:141], v[216:219], v[14:17]
	v_mfma_f32_16x16x32_bf16 v[62:65], v[134:137], v[186:189], v[62:65]
	v_mfma_f32_16x16x32_bf16 v[58:61], v[154:157], v[186:189], v[58:61]
	v_mfma_f32_16x16x32_bf16 v[54:57], v[134:137], v[198:201], v[54:57]
	v_mfma_f32_16x16x32_bf16 v[46:49], v[154:157], v[198:201], v[46:49]
	v_mfma_f32_16x16x32_bf16 v[38:41], v[134:137], v[212:215], v[38:41]
	v_mfma_f32_16x16x32_bf16 v[30:33], v[154:157], v[212:215], v[30:33]
	v_mfma_f32_16x16x32_bf16 v[22:25], v[134:137], v[220:223], v[22:25]
	v_mfma_f32_16x16x32_bf16 v[14:17], v[154:157], v[220:223], v[14:17]
	s_setprio 0
	s_setprio 1
	v_mfma_f32_16x16x32_bf16 v[50:53], v[158:161], v[182:185], v[50:53]
	v_mfma_f32_16x16x32_bf16 v[42:45], v[166:169], v[182:185], v[42:45]
	v_mfma_f32_16x16x32_bf16 v[34:37], v[158:161], v[190:193], v[34:37]
	v_mfma_f32_16x16x32_bf16 v[26:29], v[166:169], v[190:193], v[26:29]
	v_mfma_f32_16x16x32_bf16 v[18:21], v[158:161], v[206:209], v[18:21]
	v_mfma_f32_16x16x32_bf16 v[10:13], v[166:169], v[206:209], v[10:13]
	v_mfma_f32_16x16x32_bf16 v[6:9], v[158:161], v[216:219], v[6:9]
	v_mfma_f32_16x16x32_bf16 v[2:5], v[166:169], v[216:219], v[2:5]
	v_mfma_f32_16x16x32_bf16 v[50:53], v[162:165], v[186:189], v[50:53]
	v_mfma_f32_16x16x32_bf16 v[42:45], v[178:181], v[186:189], v[42:45]
	v_mfma_f32_16x16x32_bf16 v[34:37], v[162:165], v[198:201], v[34:37]
	v_mfma_f32_16x16x32_bf16 v[26:29], v[178:181], v[198:201], v[26:29]
	v_mfma_f32_16x16x32_bf16 v[18:21], v[162:165], v[212:215], v[18:21]
	v_mfma_f32_16x16x32_bf16 v[10:13], v[178:181], v[212:215], v[10:13]
	v_mfma_f32_16x16x32_bf16 v[6:9], v[162:165], v[220:223], v[6:9]
	v_mfma_f32_16x16x32_bf16 v[2:5], v[178:181], v[220:223], v[2:5]
	s_setprio 0
	s_barrier
	s_add_i32 s47, 0, 0x18000
	s_add_i32 s48, 0, 0x1c000
	v_add_u32_e32 v154, s47, v173
	v_add_u32_e32 v170, s48, v173
	ds_read_b128 v[130:133], v154
	ds_read_b128 v[134:137], v154 offset:1024
	ds_read_b128 v[138:141], v154 offset:2048
	ds_read_b128 v[154:157], v154 offset:3072
	ds_read_b128 v[158:161], v170
	ds_read_b128 v[162:165], v170 offset:1024
	ds_read_b128 v[166:169], v170 offset:2048
	ds_read_b128 v[178:181], v170 offset:3072
	s_add_u32 s20, s20, 0x40000
	s_addc_u32 s21, s21, 0
	s_mov_b32 m0, s34
	v_lshl_add_u64 v[232:233], s[20:21], 0, v[142:143]
	ds_read_b128 v[182:185], v177 offset:32768
	ds_read_b128 v[186:189], v177 offset:33792
	ds_read_b128 v[190:193], v177 offset:34816
	ds_read_b128 v[198:201], v177 offset:35840
	ds_read_b128 v[206:209], v177 offset:36864
	ds_read_b128 v[212:215], v177 offset:37888
	ds_read_b128 v[216:219], v177 offset:38912
	ds_read_b128 v[220:223], v177 offset:39936
	global_load_lds_dwordx4 v[232:233], off
	v_lshl_add_u64 v[232:233], s[20:21], 0, v[144:145]
	s_mov_b32 m0, s35
	s_nop 0
	global_load_lds_dwordx4 v[232:233], off
	s_waitcnt vmcnt(8)
	s_waitcnt lgkmcnt(0)
	s_barrier
	s_setprio 1
	s_waitcnt lgkmcnt(0)
	v_mfma_f32_16x16x32_bf16 v[126:129], v[130:133], v[182:185], v[126:129]
	v_mfma_f32_16x16x32_bf16 v[122:125], v[138:141], v[182:185], v[122:125]
	v_mfma_f32_16x16x32_bf16 v[118:121], v[130:133], v[190:193], v[118:121]
	v_mfma_f32_16x16x32_bf16 v[110:113], v[138:141], v[190:193], v[110:113]
	v_mfma_f32_16x16x32_bf16 v[102:105], v[130:133], v[206:209], v[102:105]
	v_mfma_f32_16x16x32_bf16 v[94:97], v[138:141], v[206:209], v[94:97]
	v_mfma_f32_16x16x32_bf16 v[86:89], v[130:133], v[216:219], v[86:89]
	v_mfma_f32_16x16x32_bf16 v[78:81], v[138:141], v[216:219], v[78:81]
	v_mfma_f32_16x16x32_bf16 v[126:129], v[134:137], v[186:189], v[126:129]
	v_mfma_f32_16x16x32_bf16 v[122:125], v[154:157], v[186:189], v[122:125]
	v_mfma_f32_16x16x32_bf16 v[118:121], v[134:137], v[198:201], v[118:121]
	v_mfma_f32_16x16x32_bf16 v[110:113], v[154:157], v[198:201], v[110:113]
	v_mfma_f32_16x16x32_bf16 v[102:105], v[134:137], v[212:215], v[102:105]
	v_mfma_f32_16x16x32_bf16 v[94:97], v[154:157], v[212:215], v[94:97]
	v_mfma_f32_16x16x32_bf16 v[86:89], v[134:137], v[220:223], v[86:89]
	v_mfma_f32_16x16x32_bf16 v[78:81], v[154:157], v[220:223], v[78:81]
	s_setprio 0
	s_setprio 1
	v_mfma_f32_16x16x32_bf16 v[114:117], v[158:161], v[182:185], v[114:117]
	v_mfma_f32_16x16x32_bf16 v[106:109], v[166:169], v[182:185], v[106:109]
	v_mfma_f32_16x16x32_bf16 v[98:101], v[158:161], v[190:193], v[98:101]
	v_mfma_f32_16x16x32_bf16 v[90:93], v[166:169], v[190:193], v[90:93]
	v_mfma_f32_16x16x32_bf16 v[82:85], v[158:161], v[206:209], v[82:85]
	v_mfma_f32_16x16x32_bf16 v[74:77], v[166:169], v[206:209], v[74:77]
	v_mfma_f32_16x16x32_bf16 v[70:73], v[158:161], v[216:219], v[70:73]
	v_mfma_f32_16x16x32_bf16 v[66:69], v[166:169], v[216:219], v[66:69]
	v_mfma_f32_16x16x32_bf16 v[114:117], v[162:165], v[186:189], v[114:117]
	v_mfma_f32_16x16x32_bf16 v[106:109], v[178:181], v[186:189], v[106:109]
	v_mfma_f32_16x16x32_bf16 v[98:101], v[162:165], v[198:201], v[98:101]
	v_mfma_f32_16x16x32_bf16 v[90:93], v[178:181], v[198:201], v[90:93]
	v_mfma_f32_16x16x32_bf16 v[82:85], v[162:165], v[212:215], v[82:85]
	v_mfma_f32_16x16x32_bf16 v[74:77], v[178:181], v[212:215], v[74:77]
	v_mfma_f32_16x16x32_bf16 v[70:73], v[162:165], v[220:223], v[70:73]
	v_mfma_f32_16x16x32_bf16 v[66:69], v[178:181], v[220:223], v[66:69]
	s_setprio 0
	s_barrier
; #define PG8_STAGE(bufoff, gbase, voff) do { _Pragma("unroll") for (int _i = 0; _i < 2; ++_i) \
;         __builtin_amdgcn_global_load_lds((const unsigned*)((const char*)(gbase) + (voff)[_i]), (PG8_LAS unsigned*)(lds + (bufoff) + ldsw + _i * 8192), 16, 0, 0); } while (0)
; #define PG8_LDA(dst, b, h) do { _Pragma("unroll") for (int m = 0; m < 4; ++m) _Pragma("unroll") for (int k = 0; k < 2; ++k) dst[m][k] = *(const PG8_LAS bf16x8*)(lds + PG8_SA(b, h) + aoff + m * 2048 + k * 1024); } while (0)
; #define PG8_MMA(ai, bj, At, Bt) do { __builtin_amdgcn_s_setprio(1); _Pragma("unroll") for (int m = 0; m < 4; ++m) _Pragma("unroll") for (int n = 0; n < 2; ++n) _Pragma("unroll") for (int k = 0; k < 2; ++k) \
;         acc[ai][bj][m][n] = __builtin_amdgcn_mfma_f32_16x16x32_bf16(Bt[n][k], At[m][k], acc[ai][bj][m][n], 0, 0, 0); __builtin_amdgcn_s_setprio(0); } while (0)
; #define PG8_WAIT_V(n) asm volatile("s_waitcnt vmcnt(" #n ")" ::: "memory")
; #define PG8_WAIT_L(n) asm volatile("s_waitcnt lgkmcnt(" #n ")" ::: "memory")
; #define PG8_BAR __builtin_amdgcn_s_barrier()
; #define PG8_SCHED __builtin_amdgcn_sched_barrier(0)
; template <class Epi, class Sched, bool ALIGN_EPI = false, bool SP2 = false>
; __device__ __forceinline__ void gemm_phase(PG8_LAS unsigned char* lds, const Gemm g, const Sched& S, const Epi& E) {
;     ...
;             PG8_LDA(At, 1, 1); PG8_STAGE(PG8_SB(1, 0), b3, voffB); PG8_STAGE(PG8_SB(1, 1), b3 + hstepB, voffB); PG8_STAGE(PG8_SA(1, 0), a3, voffA);
;             PG8_WAIT_V(8); PG8_WAIT_L(0); PG8_BAR; PG8_MMA(1, 0, At, B0); PG8_MMA(1, 1, At, B1); PG8_BAR; PG8_SCHED;
;     ...
;         if constexpr (ALIGN_EPI) { if (wr == 0) PG8_BAR; }
	s_add_i32 s20, s47, s29
	v_lshl_add_u64 v[224:225], v[224:225], 0, s[88:89]
	s_mov_b32 m0, s20
	ds_read_b128 v[182:185], v177 offset:49152
	ds_read_b128 v[186:189], v177 offset:50176
	ds_read_b128 v[190:193], v177 offset:51200
	ds_read_b128 v[198:201], v177 offset:52224
	ds_read_b128 v[206:209], v177 offset:53248
	ds_read_b128 v[212:215], v177 offset:54272
	ds_read_b128 v[216:219], v177 offset:55296
	ds_read_b128 v[220:223], v177 offset:56320
	global_load_lds_dwordx4 v[224:225], off
	s_add_i32 m0, s20, 0x2000
	s_add_u32 s18, s18, 0x40080
	v_lshl_add_u64 v[224:225], v[226:227], 0, s[88:89]
	s_addc_u32 s19, s19, 0
	s_add_i32 s20, s48, s29
	global_load_lds_dwordx4 v[224:225], off
	v_lshl_add_u64 v[224:225], s[18:19], 0, v[0:1]
	s_mov_b32 m0, s20
	s_nop 0
	global_load_lds_dwordx4 v[224:225], off
	v_lshl_add_u64 v[224:225], s[18:19], 0, v[146:147]
	s_add_i32 m0, s20, 0x2000
	s_nop 0
	global_load_lds_dwordx4 v[224:225], off
	v_lshl_add_u64 v[224:225], v[228:229], 0, s[88:89]
	s_mov_b32 m0, s38
	s_nop 0
	global_load_lds_dwordx4 v[224:225], off
	v_lshl_add_u64 v[224:225], v[230:231], 0, s[88:89]
	s_mov_b32 m0, s39
	s_nop 0
	global_load_lds_dwordx4 v[224:225], off
	s_waitcnt vmcnt(8)
	s_waitcnt lgkmcnt(0)
	s_barrier
	s_setprio 1
	s_waitcnt lgkmcnt(0)
	v_mfma_f32_16x16x32_bf16 v[62:65], v[130:133], v[182:185], v[62:65]
	v_mfma_f32_16x16x32_bf16 v[58:61], v[138:141], v[182:185], v[58:61]
	v_mfma_f32_16x16x32_bf16 v[54:57], v[130:133], v[190:193], v[54:57]
	v_mfma_f32_16x16x32_bf16 v[46:49], v[138:141], v[190:193], v[46:49]
	v_mfma_f32_16x16x32_bf16 v[38:41], v[130:133], v[206:209], v[38:41]
	v_mfma_f32_16x16x32_bf16 v[30:33], v[138:141], v[206:209], v[30:33]
	v_mfma_f32_16x16x32_bf16 v[22:25], v[130:133], v[216:219], v[22:25]
	v_mfma_f32_16x16x32_bf16 v[14:17], v[138:141], v[216:219], v[14:17]
	v_mfma_f32_16x16x32_bf16 v[62:65], v[134:137], v[186:189], v[62:65]
	v_mfma_f32_16x16x32_bf16 v[58:61], v[154:157], v[186:189], v[58:61]
	v_mfma_f32_16x16x32_bf16 v[54:57], v[134:137], v[198:201], v[54:57]
	v_mfma_f32_16x16x32_bf16 v[46:49], v[154:157], v[198:201], v[46:49]
	v_mfma_f32_16x16x32_bf16 v[38:41], v[134:137], v[212:215], v[38:41]
	v_mfma_f32_16x16x32_bf16 v[30:33], v[154:157], v[212:215], v[30:33]
	v_mfma_f32_16x16x32_bf16 v[22:25], v[134:137], v[220:223], v[22:25]
	v_mfma_f32_16x16x32_bf16 v[14:17], v[154:157], v[220:223], v[14:17]
	s_setprio 0
	s_setprio 1
	v_mfma_f32_16x16x32_bf16 v[50:53], v[158:161], v[182:185], v[50:53]
	v_mfma_f32_16x16x32_bf16 v[42:45], v[166:169], v[182:185], v[42:45]
	v_mfma_f32_16x16x32_bf16 v[34:37], v[158:161], v[190:193], v[34:37]
	v_mfma_f32_16x16x32_bf16 v[26:29], v[166:169], v[190:193], v[26:29]
	v_mfma_f32_16x16x32_bf16 v[18:21], v[158:161], v[206:209], v[18:21]
	v_mfma_f32_16x16x32_bf16 v[10:13], v[166:169], v[206:209], v[10:13]
	v_mfma_f32_16x16x32_bf16 v[6:9], v[158:161], v[216:219], v[6:9]
	v_mfma_f32_16x16x32_bf16 v[2:5], v[166:169], v[216:219], v[2:5]
	v_mfma_f32_16x16x32_bf16 v[50:53], v[162:165], v[186:189], v[50:53]
	v_mfma_f32_16x16x32_bf16 v[42:45], v[178:181], v[186:189], v[42:45]
	v_mfma_f32_16x16x32_bf16 v[34:37], v[162:165], v[198:201], v[34:37]
	v_mfma_f32_16x16x32_bf16 v[26:29], v[178:181], v[198:201], v[26:29]
	v_mfma_f32_16x16x32_bf16 v[18:21], v[162:165], v[212:215], v[18:21]
	v_mfma_f32_16x16x32_bf16 v[10:13], v[178:181], v[212:215], v[10:13]
	v_mfma_f32_16x16x32_bf16 v[6:9], v[162:165], v[220:223], v[6:9]
	v_mfma_f32_16x16x32_bf16 v[2:5], v[178:181], v[220:223], v[2:5]
	s_setprio 0
	s_barrier
	s_add_i32 s46, s46, 2
	s_add_u32 s16, s16, 0x100
	s_addc_u32 s17, s17, 0
	s_add_u32 s44, s44, 0x100
	s_addc_u32 s45, s45, 0
	s_cmp_gt_u32 s46, 13
	s_cbranch_scc0 .LBB0_457
	v_readfirstlane_b32 s100, v238
	s_nop 3
	s_bfe_u32 s100, s100, 0x40006
	s_cmp_ge_u32 s100, 4
	s_cbranch_scc0 .Lepiprio_3
	s_setprio 1

; #define PG8_STAGE(bufoff, gbase, voff) do { _Pragma("unroll") for (int _i = 0; _i < 2; ++_i) \
;         __builtin_amdgcn_global_load_lds((const unsigned*)((const char*)(gbase) + (voff)[_i]), (PG8_LAS unsigned*)(lds + (bufoff) + ldsw + _i * 8192), 16, 0, 0); } while (0)
; #define PG8_LDA(dst, b, h) do { _Pragma("unroll") for (int m = 0; m < 4; ++m) _Pragma("unroll") for (int k = 0; k < 2; ++k) dst[m][k] = *(const PG8_LAS bf16x8*)(lds + PG8_SA(b, h) + aoff + m * 2048 + k * 1024); } while (0)
; #define PG8_LDB(dst, b, h) do { _Pragma("unroll") for (int n = 0; n < 2; ++n) _Pragma("unroll") for (int k = 0; k < 2; ++k) dst[n][k] = *(const PG8_LAS bf16x8*)(lds + PG8_SB(b, h) + boff + n * 2048 + k * 1024); } while (0)
; #define PG8_MMA(ai, bj, At, Bt) do { __builtin_amdgcn_s_setprio(1); _Pragma("unroll") for (int m = 0; m < 4; ++m) _Pragma("unroll") for (int n = 0; n < 2; ++n) _Pragma("unroll") for (int k = 0; k < 2; ++k) \
;         acc[ai][bj][m][n] = __builtin_amdgcn_mfma_f32_16x16x32_bf16(Bt[n][k], At[m][k], acc[ai][bj][m][n], 0, 0, 0); __builtin_amdgcn_s_setprio(0); } while (0)
; #define PG8_WAIT_V(n) asm volatile("s_waitcnt vmcnt(" #n ")" ::: "memory")
; #define PG8_WAIT_L(n) asm volatile("s_waitcnt lgkmcnt(" #n ")" ::: "memory")
; #define PG8_BAR __builtin_amdgcn_s_barrier()
; #define PG8_SCHED __builtin_amdgcn_sched_barrier(0)
; template <class Epi, class Sched, bool ALIGN_EPI = false, bool SP2 = false>
; __device__ __forceinline__ void gemm_phase(PG8_LAS unsigned char* lds, const Gemm g, const Sched& S, const Epi& E) {
;     ...
;         for (int t = 0; t < nt; t += 2) {
;             const bool last = (t == nt - 2);
;             const char* a1 = cA + (size_t)(t + 1) * kstep;
;             const char* a2 = last ? nA : cA + (size_t)(t + 2) * kstep; const char* b2 = last ? nB : cB + (size_t)(t + 2) * kstep;
;             const char* a3 = a2 + kstep; const char* b3 = b2 + kstep;
;             if (last && has_next) S.a_ready(nxt);
;             if constexpr (SP2) {
;             PG8_LDB(B0, 0, 0); PG8_LDB(B1, 0, 1); PG8_SCHED; PG8_LDA(At, 0, 0); PG8_STAGE(PG8_SA(1, 1), a1 + hstepA, voffA);
;             PG8_WAIT_V(8); PG8_WAIT_L(0); PG8_BAR; PG8_MMA(0, 0, At, B0); PG8_MMA(0, 1, At, B1); PG8_BAR; PG8_SCHED;
;             PG8_LDA(At, 0, 1); PG8_STAGE(PG8_SB(0, 0), b2, voffB); PG8_STAGE(PG8_SB(0, 1), b2 + hstepB, voffB); PG8_STAGE(PG8_SA(0, 0), a2, voffA);
.LBB0_614:
	s_add_u32 s20, s18, 0xfffc0080
	s_addc_u32 s21, s19, -1
	s_add_i32 s53, 0, 0x10000
	s_cmp_eq_u32 s52, 12
	s_cselect_b32 s23, s13, s21
	s_cselect_b32 s22, s48, s20
	s_cselect_b32 s21, s11, s51
	s_cselect_b32 s20, s49, s50
	s_add_i32 s56, 0, 0x14000
	v_add_u32_e32 v158, s53, v143
	v_add_u32_e32 v174, s56, v143
	ds_read_b128 v[146:149], v158
	ds_read_b128 v[150:153], v158 offset:1024
	ds_read_b128 v[154:157], v158 offset:2048
	ds_read_b128 v[158:161], v158 offset:3072
	ds_read_b128 v[162:165], v174
	ds_read_b128 v[166:169], v174 offset:1024
	ds_read_b128 v[170:173], v174 offset:2048
	ds_read_b128 v[174:177], v174 offset:3072
	v_lshl_add_u64 v[220:221], s[18:19], 0, v[138:139]
	s_add_i32 m0, s38, 0xc000
	ds_read_b128 v[178:181], v145
	ds_read_b128 v[182:185], v145 offset:1024
	ds_read_b128 v[186:189], v145 offset:2048
	ds_read_b128 v[190:193], v145 offset:3072
	ds_read_b128 v[198:201], v145 offset:4096
	ds_read_b128 v[206:209], v145 offset:5120
	ds_read_b128 v[212:215], v145 offset:6144
	ds_read_b128 v[216:219], v145 offset:7168
	global_load_lds_dwordx4 v[220:221], off
	v_lshl_add_u64 v[220:221], s[18:19], 0, v[140:141]
	s_add_i32 m0, s38, 0xe000
	s_nop 0
	global_load_lds_dwordx4 v[220:221], off
	s_waitcnt vmcnt(8)
	s_waitcnt lgkmcnt(0)
	s_barrier
	s_setprio 1
	s_waitcnt lgkmcnt(0)
	v_mfma_f32_16x16x32_bf16 v[126:129], v[146:149], v[178:181], v[126:129]
	v_mfma_f32_16x16x32_bf16 v[122:125], v[154:157], v[178:181], v[122:125]
	v_mfma_f32_16x16x32_bf16 v[118:121], v[146:149], v[186:189], v[118:121]
	v_mfma_f32_16x16x32_bf16 v[114:117], v[154:157], v[186:189], v[114:117]
	v_mfma_f32_16x16x32_bf16 v[102:105], v[146:149], v[198:201], v[102:105]
	v_mfma_f32_16x16x32_bf16 v[98:101], v[154:157], v[198:201], v[98:101]
	v_mfma_f32_16x16x32_bf16 v[86:89], v[146:149], v[212:215], v[86:89]
	v_mfma_f32_16x16x32_bf16 v[82:85], v[154:157], v[212:215], v[82:85]
	v_mfma_f32_16x16x32_bf16 v[126:129], v[150:153], v[182:185], v[126:129]
	v_mfma_f32_16x16x32_bf16 v[122:125], v[158:161], v[182:185], v[122:125]
	v_mfma_f32_16x16x32_bf16 v[118:121], v[150:153], v[190:193], v[118:121]
	v_mfma_f32_16x16x32_bf16 v[114:117], v[158:161], v[190:193], v[114:117]
	v_mfma_f32_16x16x32_bf16 v[102:105], v[150:153], v[206:209], v[102:105]
	v_mfma_f32_16x16x32_bf16 v[98:101], v[158:161], v[206:209], v[98:101]
	v_mfma_f32_16x16x32_bf16 v[86:89], v[150:153], v[216:219], v[86:89]
	v_mfma_f32_16x16x32_bf16 v[82:85], v[158:161], v[216:219], v[82:85]
	s_setprio 0
	s_setprio 1
	v_mfma_f32_16x16x32_bf16 v[110:113], v[162:165], v[178:181], v[110:113]
	v_mfma_f32_16x16x32_bf16 v[106:109], v[170:173], v[178:181], v[106:109]
	v_mfma_f32_16x16x32_bf16 v[94:97], v[162:165], v[186:189], v[94:97]
	v_mfma_f32_16x16x32_bf16 v[90:93], v[170:173], v[186:189], v[90:93]
	v_mfma_f32_16x16x32_bf16 v[78:81], v[162:165], v[198:201], v[78:81]
	v_mfma_f32_16x16x32_bf16 v[74:77], v[170:173], v[198:201], v[74:77]
	v_mfma_f32_16x16x32_bf16 v[70:73], v[162:165], v[212:215], v[70:73]
	v_mfma_f32_16x16x32_bf16 v[66:69], v[170:173], v[212:215], v[66:69]
	v_mfma_f32_16x16x32_bf16 v[110:113], v[166:169], v[182:185], v[110:113]
	v_mfma_f32_16x16x32_bf16 v[106:109], v[174:177], v[182:185], v[106:109]
	v_mfma_f32_16x16x32_bf16 v[94:97], v[166:169], v[190:193], v[94:97]
	v_mfma_f32_16x16x32_bf16 v[90:93], v[174:177], v[190:193], v[90:93]
	v_mfma_f32_16x16x32_bf16 v[78:81], v[166:169], v[206:209], v[78:81]
	v_mfma_f32_16x16x32_bf16 v[74:77], v[174:177], v[206:209], v[74:77]
	v_mfma_f32_16x16x32_bf16 v[70:73], v[166:169], v[216:219], v[70:73]
	v_mfma_f32_16x16x32_bf16 v[66:69], v[174:177], v[216:219], v[66:69]
	s_setprio 0
	s_barrier
	s_add_i32 s53, s53, s37
	v_lshl_add_u64 v[220:221], s[20:21], 0, v[0:1]
	s_mov_b32 m0, s53
	ds_read_b128 v[178:181], v145 offset:16384
	ds_read_b128 v[182:185], v145 offset:17408
	ds_read_b128 v[186:189], v145 offset:18432
	ds_read_b128 v[190:193], v145 offset:19456
	ds_read_b128 v[198:201], v145 offset:20480
	ds_read_b128 v[206:209], v145 offset:21504
	ds_read_b128 v[212:215], v145 offset:22528
	ds_read_b128 v[216:219], v145 offset:23552
	global_load_lds_dwordx4 v[220:221], off
	s_add_i32 m0, s53, 0x2000
	s_add_u32 s54, s20, 0x40000
	v_lshl_add_u64 v[222:223], s[20:21], 0, v[136:137]
	s_addc_u32 s55, s21, 0
	s_add_i32 s53, s56, s37
	global_load_lds_dwordx4 v[222:223], off
	v_lshl_add_u64 v[224:225], s[54:55], 0, v[0:1]
	s_mov_b32 m0, s53
	v_lshl_add_u64 v[226:227], s[22:23], 0, v[134:135]
	global_load_lds_dwordx4 v[224:225], off
	v_lshl_add_u64 v[224:225], s[54:55], 0, v[136:137]
	s_add_i32 m0, s53, 0x2000
	s_nop 0
	global_load_lds_dwordx4 v[224:225], off
	v_lshl_add_u64 v[224:225], s[22:23], 0, v[132:133]
	s_mov_b32 m0, s38
	s_nop 0
	global_load_lds_dwordx4 v[224:225], off
	s_mov_b32 m0, s39
	s_nop 0
	global_load_lds_dwordx4 v[226:227], off
	s_waitcnt vmcnt(8)
	s_waitcnt lgkmcnt(0)
	s_barrier
; #define PG8_STAGE(bufoff, gbase, voff) do { _Pragma("unroll") for (int _i = 0; _i < 2; ++_i) \
;         __builtin_amdgcn_global_load_lds((const unsigned*)((const char*)(gbase) + (voff)[_i]), (PG8_LAS unsigned*)(lds + (bufoff) + ldsw + _i * 8192), 16, 0, 0); } while (0)
; #define PG8_LDA(dst, b, h) do { _Pragma("unroll") for (int m = 0; m < 4; ++m) _Pragma("unroll") for (int k = 0; k < 2; ++k) dst[m][k] = *(const PG8_LAS bf16x8*)(lds + PG8_SA(b, h) + aoff + m * 2048 + k * 1024); } while (0)
; #define PG8_LDB(dst, b, h) do { _Pragma("unroll") for (int n = 0; n < 2; ++n) _Pragma("unroll") for (int k = 0; k < 2; ++k) dst[n][k] = *(const PG8_LAS bf16x8*)(lds + PG8_SB(b, h) + boff + n * 2048 + k * 1024); } while (0)
; #define PG8_MMA(ai, bj, At, Bt) do { __builtin_amdgcn_s_setprio(1); _Pragma("unroll") for (int m = 0; m < 4; ++m) _Pragma("unroll") for (int n = 0; n < 2; ++n) _Pragma("unroll") for (int k = 0; k < 2; ++k) \
;         acc[ai][bj][m][n] = __builtin_amdgcn_mfma_f32_16x16x32_bf16(Bt[n][k], At[m][k], acc[ai][bj][m][n], 0, 0, 0); __builtin_amdgcn_s_setprio(0); } while (0)
; #define PG8_WAIT_V(n) asm volatile("s_waitcnt vmcnt(" #n ")" ::: "memory")
; #define PG8_WAIT_L(n) asm volatile("s_waitcnt lgkmcnt(" #n ")" ::: "memory")
; #define PG8_BAR __builtin_amdgcn_s_barrier()
; #define PG8_SCHED __builtin_amdgcn_sched_barrier(0)
; template <class Epi, class Sched, bool ALIGN_EPI = false, bool SP2 = false>
; __device__ __forceinline__ void gemm_phase(PG8_LAS unsigned char* lds, const Gemm g, const Sched& S, const Epi& E) {
;     ...
;             PG8_WAIT_V(8); PG8_WAIT_L(0); PG8_BAR; PG8_MMA(1, 0, At, B0); PG8_MMA(1, 1, At, B1); PG8_BAR; PG8_SCHED;
;             PG8_LDB(B0, 1, 0); PG8_LDB(B1, 1, 1); PG8_SCHED; PG8_LDA(At, 1, 0); PG8_STAGE(PG8_SA(0, 1), a2 + hstepA, voffA);
;             PG8_WAIT_V(8); PG8_WAIT_L(0); PG8_BAR; PG8_MMA(0, 0, At, B0); PG8_MMA(0, 1, At, B1); PG8_BAR; PG8_SCHED;
	s_setprio 1
	s_waitcnt lgkmcnt(0)
	v_mfma_f32_16x16x32_bf16 v[62:65], v[146:149], v[178:181], v[62:65]
	v_mfma_f32_16x16x32_bf16 v[58:61], v[154:157], v[178:181], v[58:61]
	v_mfma_f32_16x16x32_bf16 v[54:57], v[146:149], v[186:189], v[54:57]
	v_mfma_f32_16x16x32_bf16 v[50:53], v[154:157], v[186:189], v[50:53]
	v_mfma_f32_16x16x32_bf16 v[38:41], v[146:149], v[198:201], v[38:41]
	v_mfma_f32_16x16x32_bf16 v[34:37], v[154:157], v[198:201], v[34:37]
	v_mfma_f32_16x16x32_bf16 v[22:25], v[146:149], v[212:215], v[22:25]
	v_mfma_f32_16x16x32_bf16 v[18:21], v[154:157], v[212:215], v[18:21]
	v_mfma_f32_16x16x32_bf16 v[62:65], v[150:153], v[182:185], v[62:65]
	v_mfma_f32_16x16x32_bf16 v[58:61], v[158:161], v[182:185], v[58:61]
	v_mfma_f32_16x16x32_bf16 v[54:57], v[150:153], v[190:193], v[54:57]
	v_mfma_f32_16x16x32_bf16 v[50:53], v[158:161], v[190:193], v[50:53]
	v_mfma_f32_16x16x32_bf16 v[38:41], v[150:153], v[206:209], v[38:41]
	v_mfma_f32_16x16x32_bf16 v[34:37], v[158:161], v[206:209], v[34:37]
	v_mfma_f32_16x16x32_bf16 v[22:25], v[150:153], v[216:219], v[22:25]
	v_mfma_f32_16x16x32_bf16 v[18:21], v[158:161], v[216:219], v[18:21]
	s_setprio 0
	s_setprio 1
	v_mfma_f32_16x16x32_bf16 v[46:49], v[162:165], v[178:181], v[46:49]
	v_mfma_f32_16x16x32_bf16 v[42:45], v[170:173], v[178:181], v[42:45]
	v_mfma_f32_16x16x32_bf16 v[30:33], v[162:165], v[186:189], v[30:33]
	v_mfma_f32_16x16x32_bf16 v[26:29], v[170:173], v[186:189], v[26:29]
	v_mfma_f32_16x16x32_bf16 v[14:17], v[162:165], v[198:201], v[14:17]
	v_mfma_f32_16x16x32_bf16 v[10:13], v[170:173], v[198:201], v[10:13]
	v_mfma_f32_16x16x32_bf16 v[6:9], v[162:165], v[212:215], v[6:9]
	v_mfma_f32_16x16x32_bf16 v[2:5], v[170:173], v[212:215], v[2:5]
	v_mfma_f32_16x16x32_bf16 v[46:49], v[166:169], v[182:185], v[46:49]
	v_mfma_f32_16x16x32_bf16 v[42:45], v[174:177], v[182:185], v[42:45]
	v_mfma_f32_16x16x32_bf16 v[30:33], v[166:169], v[190:193], v[30:33]
	v_mfma_f32_16x16x32_bf16 v[26:29], v[174:177], v[190:193], v[26:29]
	v_mfma_f32_16x16x32_bf16 v[14:17], v[166:169], v[206:209], v[14:17]
	v_mfma_f32_16x16x32_bf16 v[10:13], v[174:177], v[206:209], v[10:13]
	v_mfma_f32_16x16x32_bf16 v[6:9], v[166:169], v[216:219], v[6:9]
	v_mfma_f32_16x16x32_bf16 v[2:5], v[174:177], v[216:219], v[2:5]
	s_setprio 0
	s_barrier
	s_add_i32 s53, 0, 0x18000
	s_add_i32 s54, 0, 0x1c000
	v_add_u32_e32 v158, s53, v143
	v_add_u32_e32 v174, s54, v143
	ds_read_b128 v[146:149], v158
	ds_read_b128 v[150:153], v158 offset:1024
	ds_read_b128 v[154:157], v158 offset:2048
	ds_read_b128 v[158:161], v158 offset:3072
	ds_read_b128 v[162:165], v174
	ds_read_b128 v[166:169], v174 offset:1024
	ds_read_b128 v[170:173], v174 offset:2048
	ds_read_b128 v[174:177], v174 offset:3072
	s_add_u32 s22, s22, 0x40000
	s_addc_u32 s23, s23, 0
	s_mov_b32 m0, s40
	v_lshl_add_u64 v[228:229], s[22:23], 0, v[132:133]
	ds_read_b128 v[178:181], v145 offset:32768
	ds_read_b128 v[182:185], v145 offset:33792
	ds_read_b128 v[186:189], v145 offset:34816
	ds_read_b128 v[190:193], v145 offset:35840
	ds_read_b128 v[198:201], v145 offset:36864
	ds_read_b128 v[206:209], v145 offset:37888
	ds_read_b128 v[212:215], v145 offset:38912
	ds_read_b128 v[216:219], v145 offset:39936
	global_load_lds_dwordx4 v[228:229], off
	v_lshl_add_u64 v[228:229], s[22:23], 0, v[134:135]
	s_mov_b32 m0, s41
	s_nop 0
	global_load_lds_dwordx4 v[228:229], off
	s_waitcnt vmcnt(8)
	s_waitcnt lgkmcnt(0)
	s_barrier
	s_setprio 1
	s_waitcnt lgkmcnt(0)
	v_mfma_f32_16x16x32_bf16 v[126:129], v[146:149], v[178:181], v[126:129]
	v_mfma_f32_16x16x32_bf16 v[122:125], v[154:157], v[178:181], v[122:125]
	v_mfma_f32_16x16x32_bf16 v[118:121], v[146:149], v[186:189], v[118:121]
	v_mfma_f32_16x16x32_bf16 v[114:117], v[154:157], v[186:189], v[114:117]
	v_mfma_f32_16x16x32_bf16 v[102:105], v[146:149], v[198:201], v[102:105]
	v_mfma_f32_16x16x32_bf16 v[98:101], v[154:157], v[198:201], v[98:101]
	v_mfma_f32_16x16x32_bf16 v[86:89], v[146:149], v[212:215], v[86:89]
	v_mfma_f32_16x16x32_bf16 v[82:85], v[154:157], v[212:215], v[82:85]
	v_mfma_f32_16x16x32_bf16 v[126:129], v[150:153], v[182:185], v[126:129]
	v_mfma_f32_16x16x32_bf16 v[122:125], v[158:161], v[182:185], v[122:125]
	v_mfma_f32_16x16x32_bf16 v[118:121], v[150:153], v[190:193], v[118:121]
	v_mfma_f32_16x16x32_bf16 v[114:117], v[158:161], v[190:193], v[114:117]
	v_mfma_f32_16x16x32_bf16 v[102:105], v[150:153], v[206:209], v[102:105]
	v_mfma_f32_16x16x32_bf16 v[98:101], v[158:161], v[206:209], v[98:101]
	v_mfma_f32_16x16x32_bf16 v[86:89], v[150:153], v[216:219], v[86:89]
	v_mfma_f32_16x16x32_bf16 v[82:85], v[158:161], v[216:219], v[82:85]
	s_setprio 0
	s_setprio 1
	v_mfma_f32_16x16x32_bf16 v[110:113], v[162:165], v[178:181], v[110:113]
	v_mfma_f32_16x16x32_bf16 v[106:109], v[170:173], v[178:181], v[106:109]
	v_mfma_f32_16x16x32_bf16 v[94:97], v[162:165], v[186:189], v[94:97]
	v_mfma_f32_16x16x32_bf16 v[90:93], v[170:173], v[186:189], v[90:93]
	v_mfma_f32_16x16x32_bf16 v[78:81], v[162:165], v[198:201], v[78:81]
	v_mfma_f32_16x16x32_bf16 v[74:77], v[170:173], v[198:201], v[74:77]
	v_mfma_f32_16x16x32_bf16 v[70:73], v[162:165], v[212:215], v[70:73]
	v_mfma_f32_16x16x32_bf16 v[66:69], v[170:173], v[212:215], v[66:69]
	v_mfma_f32_16x16x32_bf16 v[110:113], v[166:169], v[182:185], v[110:113]
	v_mfma_f32_16x16x32_bf16 v[106:109], v[174:177], v[182:185], v[106:109]
	v_mfma_f32_16x16x32_bf16 v[94:97], v[166:169], v[190:193], v[94:97]
	v_mfma_f32_16x16x32_bf16 v[90:93], v[174:177], v[190:193], v[90:93]
	v_mfma_f32_16x16x32_bf16 v[78:81], v[166:169], v[206:209], v[78:81]
	v_mfma_f32_16x16x32_bf16 v[74:77], v[174:177], v[206:209], v[74:77]
	v_mfma_f32_16x16x32_bf16 v[70:73], v[166:169], v[216:219], v[70:73]
	v_mfma_f32_16x16x32_bf16 v[66:69], v[174:177], v[216:219], v[66:69]
	s_setprio 0
	s_barrier
; #define PG8_STAGE(bufoff, gbase, voff) do { _Pragma("unroll") for (int _i = 0; _i < 2; ++_i) \
;         __builtin_amdgcn_global_load_lds((const unsigned*)((const char*)(gbase) + (voff)[_i]), (PG8_LAS unsigned*)(lds + (bufoff) + ldsw + _i * 8192), 16, 0, 0); } while (0)
; #define PG8_LDA(dst, b, h) do { _Pragma("unroll") for (int m = 0; m < 4; ++m) _Pragma("unroll") for (int k = 0; k < 2; ++k) dst[m][k] = *(const PG8_LAS bf16x8*)(lds + PG8_SA(b, h) + aoff + m * 2048 + k * 1024); } while (0)
; #define PG8_MMA(ai, bj, At, Bt) do { __builtin_amdgcn_s_setprio(1); _Pragma("unroll") for (int m = 0; m < 4; ++m) _Pragma("unroll") for (int n = 0; n < 2; ++n) _Pragma("unroll") for (int k = 0; k < 2; ++k) \
;         acc[ai][bj][m][n] = __builtin_amdgcn_mfma_f32_16x16x32_bf16(Bt[n][k], At[m][k], acc[ai][bj][m][n], 0, 0, 0); __builtin_amdgcn_s_setprio(0); } while (0)
; #define PG8_WAIT_V(n) asm volatile("s_waitcnt vmcnt(" #n ")" ::: "memory")
; #define PG8_WAIT_L(n) asm volatile("s_waitcnt lgkmcnt(" #n ")" ::: "memory")
; #define PG8_BAR __builtin_amdgcn_s_barrier()
; #define PG8_SCHED __builtin_amdgcn_sched_barrier(0)
; template <class Epi, class Sched, bool ALIGN_EPI = false, bool SP2 = false>
; __device__ __forceinline__ void gemm_phase(PG8_LAS unsigned char* lds, const Gemm g, const Sched& S, const Epi& E) {
;     ...
;             PG8_LDA(At, 1, 1); PG8_STAGE(PG8_SB(1, 0), b3, voffB); PG8_STAGE(PG8_SB(1, 1), b3 + hstepB, voffB); PG8_STAGE(PG8_SA(1, 0), a3, voffA);
;             PG8_WAIT_V(8); PG8_WAIT_L(0); PG8_BAR; PG8_MMA(1, 0, At, B0); PG8_MMA(1, 1, At, B1); PG8_BAR; PG8_SCHED;
;     ...
;         if constexpr (ALIGN_EPI) { if (wr == 0) PG8_BAR; }
	s_add_i32 s22, s53, s37
	v_lshl_add_u64 v[220:221], v[220:221], 0, s[88:89]
	s_mov_b32 m0, s22
	ds_read_b128 v[178:181], v145 offset:49152
	ds_read_b128 v[182:185], v145 offset:50176
	ds_read_b128 v[186:189], v145 offset:51200
	ds_read_b128 v[190:193], v145 offset:52224
	ds_read_b128 v[198:201], v145 offset:53248
	ds_read_b128 v[206:209], v145 offset:54272
	ds_read_b128 v[212:215], v145 offset:55296
	ds_read_b128 v[216:219], v145 offset:56320
	global_load_lds_dwordx4 v[220:221], off
	s_add_i32 m0, s22, 0x2000
	s_add_u32 s20, s20, 0x40080
	v_lshl_add_u64 v[220:221], v[222:223], 0, s[88:89]
	s_addc_u32 s21, s21, 0
	s_add_i32 s22, s54, s37
	global_load_lds_dwordx4 v[220:221], off
	v_lshl_add_u64 v[220:221], s[20:21], 0, v[0:1]
	s_mov_b32 m0, s22
	s_nop 0
	global_load_lds_dwordx4 v[220:221], off
	v_lshl_add_u64 v[220:221], s[20:21], 0, v[136:137]
	s_add_i32 m0, s22, 0x2000
	s_nop 0
	global_load_lds_dwordx4 v[220:221], off
	v_lshl_add_u64 v[220:221], v[224:225], 0, s[88:89]
	s_mov_b32 m0, s43
	s_nop 0
	global_load_lds_dwordx4 v[220:221], off
	v_lshl_add_u64 v[220:221], v[226:227], 0, s[88:89]
	s_mov_b32 m0, s44
	s_nop 0
	global_load_lds_dwordx4 v[220:221], off
	s_waitcnt vmcnt(8)
	s_waitcnt lgkmcnt(0)
	s_barrier
	s_setprio 1
	s_waitcnt lgkmcnt(0)
	v_mfma_f32_16x16x32_bf16 v[62:65], v[146:149], v[178:181], v[62:65]
	v_mfma_f32_16x16x32_bf16 v[58:61], v[154:157], v[178:181], v[58:61]
	v_mfma_f32_16x16x32_bf16 v[54:57], v[146:149], v[186:189], v[54:57]
	v_mfma_f32_16x16x32_bf16 v[50:53], v[154:157], v[186:189], v[50:53]
	v_mfma_f32_16x16x32_bf16 v[38:41], v[146:149], v[198:201], v[38:41]
	v_mfma_f32_16x16x32_bf16 v[34:37], v[154:157], v[198:201], v[34:37]
	v_mfma_f32_16x16x32_bf16 v[22:25], v[146:149], v[212:215], v[22:25]
	v_mfma_f32_16x16x32_bf16 v[18:21], v[154:157], v[212:215], v[18:21]
	v_mfma_f32_16x16x32_bf16 v[62:65], v[150:153], v[182:185], v[62:65]
	v_mfma_f32_16x16x32_bf16 v[58:61], v[158:161], v[182:185], v[58:61]
	v_mfma_f32_16x16x32_bf16 v[54:57], v[150:153], v[190:193], v[54:57]
	v_mfma_f32_16x16x32_bf16 v[50:53], v[158:161], v[190:193], v[50:53]
	v_mfma_f32_16x16x32_bf16 v[38:41], v[150:153], v[206:209], v[38:41]
	v_mfma_f32_16x16x32_bf16 v[34:37], v[158:161], v[206:209], v[34:37]
	v_mfma_f32_16x16x32_bf16 v[22:25], v[150:153], v[216:219], v[22:25]
	v_mfma_f32_16x16x32_bf16 v[18:21], v[158:161], v[216:219], v[18:21]
	s_setprio 0
	s_setprio 1
	v_mfma_f32_16x16x32_bf16 v[46:49], v[162:165], v[178:181], v[46:49]
	v_mfma_f32_16x16x32_bf16 v[42:45], v[170:173], v[178:181], v[42:45]
	v_mfma_f32_16x16x32_bf16 v[30:33], v[162:165], v[186:189], v[30:33]
	v_mfma_f32_16x16x32_bf16 v[26:29], v[170:173], v[186:189], v[26:29]
	v_mfma_f32_16x16x32_bf16 v[14:17], v[162:165], v[198:201], v[14:17]
	v_mfma_f32_16x16x32_bf16 v[10:13], v[170:173], v[198:201], v[10:13]
	v_mfma_f32_16x16x32_bf16 v[6:9], v[162:165], v[212:215], v[6:9]
	v_mfma_f32_16x16x32_bf16 v[2:5], v[170:173], v[212:215], v[2:5]
	v_mfma_f32_16x16x32_bf16 v[46:49], v[166:169], v[182:185], v[46:49]
	v_mfma_f32_16x16x32_bf16 v[42:45], v[174:177], v[182:185], v[42:45]
	v_mfma_f32_16x16x32_bf16 v[30:33], v[166:169], v[190:193], v[30:33]
	v_mfma_f32_16x16x32_bf16 v[26:29], v[174:177], v[190:193], v[26:29]
	v_mfma_f32_16x16x32_bf16 v[14:17], v[166:169], v[206:209], v[14:17]
	v_mfma_f32_16x16x32_bf16 v[10:13], v[174:177], v[206:209], v[10:13]
	v_mfma_f32_16x16x32_bf16 v[6:9], v[166:169], v[216:219], v[6:9]
	v_mfma_f32_16x16x32_bf16 v[2:5], v[174:177], v[216:219], v[2:5]
	s_setprio 0
	s_barrier
	s_add_i32 s52, s52, 2
	s_add_u32 s18, s18, 0x100
	s_addc_u32 s19, s19, 0
	s_add_u32 s50, s50, 0x100
	s_addc_u32 s51, s51, 0
	s_cmp_gt_u32 s52, 13
	s_cbranch_scc0 .LBB0_614
	v_readfirstlane_b32 s100, v238
	s_nop 3
	s_bfe_u32 s100, s100, 0x40006
	s_cmp_ge_u32 s100, 4
	s_cbranch_scc0 .Lepiprio_4
	s_setprio 1

; #define PG8_STAGE(bufoff, gbase, voff) do { _Pragma("unroll") for (int _i = 0; _i < 2; ++_i) \
;         __builtin_amdgcn_global_load_lds((const unsigned*)((const char*)(gbase) + (voff)[_i]), (PG8_LAS unsigned*)(lds + (bufoff) + ldsw + _i * 8192), 16, 0, 0); } while (0)
; #define PG8_LDA(dst, b, h) do { _Pragma("unroll") for (int m = 0; m < 4; ++m) _Pragma("unroll") for (int k = 0; k < 2; ++k) dst[m][k] = *(const PG8_LAS bf16x8*)(lds + PG8_SA(b, h) + aoff + m * 2048 + k * 1024); } while (0)
; #define PG8_LDB(dst, b, h) do { _Pragma("unroll") for (int n = 0; n < 2; ++n) _Pragma("unroll") for (int k = 0; k < 2; ++k) dst[n][k] = *(const PG8_LAS bf16x8*)(lds + PG8_SB(b, h) + boff + n * 2048 + k * 1024); } while (0)
; #define PG8_MMA(ai, bj, At, Bt) do { __builtin_amdgcn_s_setprio(1); _Pragma("unroll") for (int m = 0; m < 4; ++m) _Pragma("unroll") for (int n = 0; n < 2; ++n) _Pragma("unroll") for (int k = 0; k < 2; ++k) \
;         acc[ai][bj][m][n] = __builtin_amdgcn_mfma_f32_16x16x32_bf16(Bt[n][k], At[m][k], acc[ai][bj][m][n], 0, 0, 0); __builtin_amdgcn_s_setprio(0); } while (0)
; #define PG8_WAIT_V(n) asm volatile("s_waitcnt vmcnt(" #n ")" ::: "memory")
; #define PG8_WAIT_L(n) asm volatile("s_waitcnt lgkmcnt(" #n ")" ::: "memory")
; #define PG8_BAR __builtin_amdgcn_s_barrier()
; #define PG8_SCHED __builtin_amdgcn_sched_barrier(0)
; template <class Epi, class Sched, bool ALIGN_EPI = false, bool SP2 = false>
; __device__ __forceinline__ void gemm_phase(PG8_LAS unsigned char* lds, const Gemm g, const Sched& S, const Epi& E) {
;     ...
;         for (int t = 0; t < nt; t += 2) {
;             const bool last = (t == nt - 2);
;             const char* a1 = cA + (size_t)(t + 1) * kstep;
;             const char* a2 = last ? nA : cA + (size_t)(t + 2) * kstep; const char* b2 = last ? nB : cB + (size_t)(t + 2) * kstep;
;             const char* a3 = a2 + kstep; const char* b3 = b2 + kstep;
;             if (last && has_next) S.a_ready(nxt);
;             if constexpr (SP2) {
;             PG8_LDB(B0, 0, 0); PG8_LDB(B1, 0, 1); PG8_SCHED; PG8_LDA(At, 0, 0); PG8_STAGE(PG8_SA(1, 1), a1 + hstepA, voffA);
;             PG8_WAIT_V(8); PG8_WAIT_L(0); PG8_BAR; PG8_MMA(0, 0, At, B0); PG8_MMA(0, 1, At, B1); PG8_BAR; PG8_SCHED;
;             PG8_LDA(At, 0, 1); PG8_STAGE(PG8_SB(0, 0), b2, voffB); PG8_STAGE(PG8_SB(0, 1), b2 + hstepB, voffB); PG8_STAGE(PG8_SA(0, 0), a2, voffA);
.LBB0_634:
	s_add_u32 s20, s18, 0xfffc0080
	s_addc_u32 s21, s19, -1
	s_add_i32 s53, 0, 0x10000
	s_cmp_eq_u32 s52, 12
	s_cselect_b32 s23, s13, s21
	s_cselect_b32 s22, s48, s20
	s_cselect_b32 s21, s11, s51
	s_cselect_b32 s20, s49, s50
	s_add_i32 s56, 0, 0x14000
	v_add_u32_e32 v158, s53, v143
	v_add_u32_e32 v174, s56, v143
	ds_read_b128 v[146:149], v158
	ds_read_b128 v[150:153], v158 offset:1024
	ds_read_b128 v[154:157], v158 offset:2048
	ds_read_b128 v[158:161], v158 offset:3072
	ds_read_b128 v[162:165], v174
	ds_read_b128 v[166:169], v174 offset:1024
	ds_read_b128 v[170:173], v174 offset:2048
	ds_read_b128 v[174:177], v174 offset:3072
	v_lshl_add_u64 v[220:221], s[18:19], 0, v[138:139]
	s_add_i32 m0, s38, 0xc000
	ds_read_b128 v[178:181], v145
	ds_read_b128 v[182:185], v145 offset:1024
	ds_read_b128 v[186:189], v145 offset:2048
	ds_read_b128 v[190:193], v145 offset:3072
	ds_read_b128 v[198:201], v145 offset:4096
	ds_read_b128 v[206:209], v145 offset:5120
	ds_read_b128 v[212:215], v145 offset:6144
	ds_read_b128 v[216:219], v145 offset:7168
	global_load_lds_dwordx4 v[220:221], off
	v_lshl_add_u64 v[220:221], s[18:19], 0, v[140:141]
	s_add_i32 m0, s38, 0xe000
	s_nop 0
	global_load_lds_dwordx4 v[220:221], off
	s_waitcnt vmcnt(8)
	s_waitcnt lgkmcnt(0)
	s_barrier
	s_setprio 1
	s_waitcnt lgkmcnt(0)
	v_mfma_f32_16x16x32_bf16 v[126:129], v[146:149], v[178:181], v[126:129]
	v_mfma_f32_16x16x32_bf16 v[122:125], v[154:157], v[178:181], v[122:125]
	v_mfma_f32_16x16x32_bf16 v[118:121], v[146:149], v[186:189], v[118:121]
	v_mfma_f32_16x16x32_bf16 v[114:117], v[154:157], v[186:189], v[114:117]
	v_mfma_f32_16x16x32_bf16 v[102:105], v[146:149], v[198:201], v[102:105]
	v_mfma_f32_16x16x32_bf16 v[98:101], v[154:157], v[198:201], v[98:101]
	v_mfma_f32_16x16x32_bf16 v[86:89], v[146:149], v[212:215], v[86:89]
	v_mfma_f32_16x16x32_bf16 v[82:85], v[154:157], v[212:215], v[82:85]
	v_mfma_f32_16x16x32_bf16 v[126:129], v[150:153], v[182:185], v[126:129]
	v_mfma_f32_16x16x32_bf16 v[122:125], v[158:161], v[182:185], v[122:125]
	v_mfma_f32_16x16x32_bf16 v[118:121], v[150:153], v[190:193], v[118:121]
	v_mfma_f32_16x16x32_bf16 v[114:117], v[158:161], v[190:193], v[114:117]
	v_mfma_f32_16x16x32_bf16 v[102:105], v[150:153], v[206:209], v[102:105]
	v_mfma_f32_16x16x32_bf16 v[98:101], v[158:161], v[206:209], v[98:101]
	v_mfma_f32_16x16x32_bf16 v[86:89], v[150:153], v[216:219], v[86:89]
	v_mfma_f32_16x16x32_bf16 v[82:85], v[158:161], v[216:219], v[82:85]
	s_setprio 0
	s_setprio 1
	v_mfma_f32_16x16x32_bf16 v[110:113], v[162:165], v[178:181], v[110:113]
	v_mfma_f32_16x16x32_bf16 v[106:109], v[170:173], v[178:181], v[106:109]
	v_mfma_f32_16x16x32_bf16 v[94:97], v[162:165], v[186:189], v[94:97]
	v_mfma_f32_16x16x32_bf16 v[90:93], v[170:173], v[186:189], v[90:93]
	v_mfma_f32_16x16x32_bf16 v[78:81], v[162:165], v[198:201], v[78:81]
	v_mfma_f32_16x16x32_bf16 v[74:77], v[170:173], v[198:201], v[74:77]
	v_mfma_f32_16x16x32_bf16 v[70:73], v[162:165], v[212:215], v[70:73]
	v_mfma_f32_16x16x32_bf16 v[66:69], v[170:173], v[212:215], v[66:69]
	v_mfma_f32_16x16x32_bf16 v[110:113], v[166:169], v[182:185], v[110:113]
	v_mfma_f32_16x16x32_bf16 v[106:109], v[174:177], v[182:185], v[106:109]
	v_mfma_f32_16x16x32_bf16 v[94:97], v[166:169], v[190:193], v[94:97]
	v_mfma_f32_16x16x32_bf16 v[90:93], v[174:177], v[190:193], v[90:93]
	v_mfma_f32_16x16x32_bf16 v[78:81], v[166:169], v[206:209], v[78:81]
	v_mfma_f32_16x16x32_bf16 v[74:77], v[174:177], v[206:209], v[74:77]
	v_mfma_f32_16x16x32_bf16 v[70:73], v[166:169], v[216:219], v[70:73]
	v_mfma_f32_16x16x32_bf16 v[66:69], v[174:177], v[216:219], v[66:69]
	s_setprio 0
	s_barrier
	s_add_i32 s53, s53, s37
	v_lshl_add_u64 v[220:221], s[20:21], 0, v[0:1]
	s_mov_b32 m0, s53
	ds_read_b128 v[178:181], v145 offset:16384
	ds_read_b128 v[182:185], v145 offset:17408
	ds_read_b128 v[186:189], v145 offset:18432
	ds_read_b128 v[190:193], v145 offset:19456
	ds_read_b128 v[198:201], v145 offset:20480
	ds_read_b128 v[206:209], v145 offset:21504
	ds_read_b128 v[212:215], v145 offset:22528
	ds_read_b128 v[216:219], v145 offset:23552
	global_load_lds_dwordx4 v[220:221], off
	s_add_i32 m0, s53, 0x2000
	s_add_u32 s54, s20, 0x40000
	v_lshl_add_u64 v[222:223], s[20:21], 0, v[132:133]
	s_addc_u32 s55, s21, 0
	s_add_i32 s53, s56, s37
	global_load_lds_dwordx4 v[222:223], off
	v_lshl_add_u64 v[224:225], s[54:55], 0, v[0:1]
	s_mov_b32 m0, s53
	v_lshl_add_u64 v[226:227], s[22:23], 0, v[134:135]
	global_load_lds_dwordx4 v[224:225], off
	v_lshl_add_u64 v[224:225], s[54:55], 0, v[132:133]
	s_add_i32 m0, s53, 0x2000
	s_nop 0
	global_load_lds_dwordx4 v[224:225], off
	v_lshl_add_u64 v[224:225], s[22:23], 0, v[136:137]
	s_mov_b32 m0, s38
	s_nop 0
	global_load_lds_dwordx4 v[224:225], off
	s_mov_b32 m0, s39
	s_nop 0
	global_load_lds_dwordx4 v[226:227], off
	s_waitcnt vmcnt(8)
	s_waitcnt lgkmcnt(0)
	s_barrier
; #define PG8_STAGE(bufoff, gbase, voff) do { _Pragma("unroll") for (int _i = 0; _i < 2; ++_i) \
;         __builtin_amdgcn_global_load_lds((const unsigned*)((const char*)(gbase) + (voff)[_i]), (PG8_LAS unsigned*)(lds + (bufoff) + ldsw + _i * 8192), 16, 0, 0); } while (0)
; #define PG8_LDA(dst, b, h) do { _Pragma("unroll") for (int m = 0; m < 4; ++m) _Pragma("unroll") for (int k = 0; k < 2; ++k) dst[m][k] = *(const PG8_LAS bf16x8*)(lds + PG8_SA(b, h) + aoff + m * 2048 + k * 1024); } while (0)
; #define PG8_LDB(dst, b, h) do { _Pragma("unroll") for (int n = 0; n < 2; ++n) _Pragma("unroll") for (int k = 0; k < 2; ++k) dst[n][k] = *(const PG8_LAS bf16x8*)(lds + PG8_SB(b, h) + boff + n * 2048 + k * 1024); } while (0)
; #define PG8_MMA(ai, bj, At, Bt) do { __builtin_amdgcn_s_setprio(1); _Pragma("unroll") for (int m = 0; m < 4; ++m) _Pragma("unroll") for (int n = 0; n < 2; ++n) _Pragma("unroll") for (int k = 0; k < 2; ++k) \
;         acc[ai][bj][m][n] = __builtin_amdgcn_mfma_f32_16x16x32_bf16(Bt[n][k], At[m][k], acc[ai][bj][m][n], 0, 0, 0); __builtin_amdgcn_s_setprio(0); } while (0)
; #define PG8_WAIT_V(n) asm volatile("s_waitcnt vmcnt(" #n ")" ::: "memory")
; #define PG8_WAIT_L(n) asm volatile("s_waitcnt lgkmcnt(" #n ")" ::: "memory")
; #define PG8_BAR __builtin_amdgcn_s_barrier()
; #define PG8_SCHED __builtin_amdgcn_sched_barrier(0)
; template <class Epi, class Sched, bool ALIGN_EPI = false, bool SP2 = false>
; __device__ __forceinline__ void gemm_phase(PG8_LAS unsigned char* lds, const Gemm g, const Sched& S, const Epi& E) {
;     ...
;             PG8_WAIT_V(8); PG8_WAIT_L(0); PG8_BAR; PG8_MMA(1, 0, At, B0); PG8_MMA(1, 1, At, B1); PG8_BAR; PG8_SCHED;
;             PG8_LDB(B0, 1, 0); PG8_LDB(B1, 1, 1); PG8_SCHED; PG8_LDA(At, 1, 0); PG8_STAGE(PG8_SA(0, 1), a2 + hstepA, voffA);
;             PG8_WAIT_V(8); PG8_WAIT_L(0); PG8_BAR; PG8_MMA(0, 0, At, B0); PG8_MMA(0, 1, At, B1); PG8_BAR; PG8_SCHED;
	s_setprio 1
	s_waitcnt lgkmcnt(0)
	v_mfma_f32_16x16x32_bf16 v[62:65], v[146:149], v[178:181], v[62:65]
	v_mfma_f32_16x16x32_bf16 v[58:61], v[154:157], v[178:181], v[58:61]
	v_mfma_f32_16x16x32_bf16 v[54:57], v[146:149], v[186:189], v[54:57]
	v_mfma_f32_16x16x32_bf16 v[50:53], v[154:157], v[186:189], v[50:53]
	v_mfma_f32_16x16x32_bf16 v[38:41], v[146:149], v[198:201], v[38:41]
	v_mfma_f32_16x16x32_bf16 v[34:37], v[154:157], v[198:201], v[34:37]
	v_mfma_f32_16x16x32_bf16 v[22:25], v[146:149], v[212:215], v[22:25]
	v_mfma_f32_16x16x32_bf16 v[18:21], v[154:157], v[212:215], v[18:21]
	v_mfma_f32_16x16x32_bf16 v[62:65], v[150:153], v[182:185], v[62:65]
	v_mfma_f32_16x16x32_bf16 v[58:61], v[158:161], v[182:185], v[58:61]
	v_mfma_f32_16x16x32_bf16 v[54:57], v[150:153], v[190:193], v[54:57]
	v_mfma_f32_16x16x32_bf16 v[50:53], v[158:161], v[190:193], v[50:53]
	v_mfma_f32_16x16x32_bf16 v[38:41], v[150:153], v[206:209], v[38:41]
	v_mfma_f32_16x16x32_bf16 v[34:37], v[158:161], v[206:209], v[34:37]
	v_mfma_f32_16x16x32_bf16 v[22:25], v[150:153], v[216:219], v[22:25]
	v_mfma_f32_16x16x32_bf16 v[18:21], v[158:161], v[216:219], v[18:21]
	s_setprio 0
	s_setprio 1
	v_mfma_f32_16x16x32_bf16 v[46:49], v[162:165], v[178:181], v[46:49]
	v_mfma_f32_16x16x32_bf16 v[42:45], v[170:173], v[178:181], v[42:45]
	v_mfma_f32_16x16x32_bf16 v[30:33], v[162:165], v[186:189], v[30:33]
	v_mfma_f32_16x16x32_bf16 v[26:29], v[170:173], v[186:189], v[26:29]
	v_mfma_f32_16x16x32_bf16 v[14:17], v[162:165], v[198:201], v[14:17]
	v_mfma_f32_16x16x32_bf16 v[10:13], v[170:173], v[198:201], v[10:13]
	v_mfma_f32_16x16x32_bf16 v[6:9], v[162:165], v[212:215], v[6:9]
	v_mfma_f32_16x16x32_bf16 v[2:5], v[170:173], v[212:215], v[2:5]
	v_mfma_f32_16x16x32_bf16 v[46:49], v[166:169], v[182:185], v[46:49]
	v_mfma_f32_16x16x32_bf16 v[42:45], v[174:177], v[182:185], v[42:45]
	v_mfma_f32_16x16x32_bf16 v[30:33], v[166:169], v[190:193], v[30:33]
	v_mfma_f32_16x16x32_bf16 v[26:29], v[174:177], v[190:193], v[26:29]
	v_mfma_f32_16x16x32_bf16 v[14:17], v[166:169], v[206:209], v[14:17]
	v_mfma_f32_16x16x32_bf16 v[10:13], v[174:177], v[206:209], v[10:13]
	v_mfma_f32_16x16x32_bf16 v[6:9], v[166:169], v[216:219], v[6:9]
	v_mfma_f32_16x16x32_bf16 v[2:5], v[174:177], v[216:219], v[2:5]
	s_setprio 0
	s_barrier
	s_add_i32 s53, 0, 0x18000
	s_add_i32 s54, 0, 0x1c000
	v_add_u32_e32 v158, s53, v143
	v_add_u32_e32 v174, s54, v143
	ds_read_b128 v[146:149], v158
	ds_read_b128 v[150:153], v158 offset:1024
	ds_read_b128 v[154:157], v158 offset:2048
	ds_read_b128 v[158:161], v158 offset:3072
	ds_read_b128 v[162:165], v174
	ds_read_b128 v[166:169], v174 offset:1024
	ds_read_b128 v[170:173], v174 offset:2048
	ds_read_b128 v[174:177], v174 offset:3072
	s_add_u32 s22, s22, 0x40000
	s_addc_u32 s23, s23, 0
	s_mov_b32 m0, s40
	v_lshl_add_u64 v[228:229], s[22:23], 0, v[136:137]
	ds_read_b128 v[178:181], v145 offset:32768
	ds_read_b128 v[182:185], v145 offset:33792
	ds_read_b128 v[186:189], v145 offset:34816
	ds_read_b128 v[190:193], v145 offset:35840
	ds_read_b128 v[198:201], v145 offset:36864
	ds_read_b128 v[206:209], v145 offset:37888
	ds_read_b128 v[212:215], v145 offset:38912
	ds_read_b128 v[216:219], v145 offset:39936
	global_load_lds_dwordx4 v[228:229], off
	v_lshl_add_u64 v[228:229], s[22:23], 0, v[134:135]
	s_mov_b32 m0, s41
	s_nop 0
	global_load_lds_dwordx4 v[228:229], off
	s_waitcnt vmcnt(8)
	s_waitcnt lgkmcnt(0)
	s_barrier
	s_setprio 1
	s_waitcnt lgkmcnt(0)
	v_mfma_f32_16x16x32_bf16 v[126:129], v[146:149], v[178:181], v[126:129]
	v_mfma_f32_16x16x32_bf16 v[122:125], v[154:157], v[178:181], v[122:125]
	v_mfma_f32_16x16x32_bf16 v[118:121], v[146:149], v[186:189], v[118:121]
	v_mfma_f32_16x16x32_bf16 v[114:117], v[154:157], v[186:189], v[114:117]
	v_mfma_f32_16x16x32_bf16 v[102:105], v[146:149], v[198:201], v[102:105]
	v_mfma_f32_16x16x32_bf16 v[98:101], v[154:157], v[198:201], v[98:101]
	v_mfma_f32_16x16x32_bf16 v[86:89], v[146:149], v[212:215], v[86:89]
	v_mfma_f32_16x16x32_bf16 v[82:85], v[154:157], v[212:215], v[82:85]
	v_mfma_f32_16x16x32_bf16 v[126:129], v[150:153], v[182:185], v[126:129]
	v_mfma_f32_16x16x32_bf16 v[122:125], v[158:161], v[182:185], v[122:125]
	v_mfma_f32_16x16x32_bf16 v[118:121], v[150:153], v[190:193], v[118:121]
	v_mfma_f32_16x16x32_bf16 v[114:117], v[158:161], v[190:193], v[114:117]
	v_mfma_f32_16x16x32_bf16 v[102:105], v[150:153], v[206:209], v[102:105]
	v_mfma_f32_16x16x32_bf16 v[98:101], v[158:161], v[206:209], v[98:101]
	v_mfma_f32_16x16x32_bf16 v[86:89], v[150:153], v[216:219], v[86:89]
	v_mfma_f32_16x16x32_bf16 v[82:85], v[158:161], v[216:219], v[82:85]
	s_setprio 0
	s_setprio 1
	v_mfma_f32_16x16x32_bf16 v[110:113], v[162:165], v[178:181], v[110:113]
	v_mfma_f32_16x16x32_bf16 v[106:109], v[170:173], v[178:181], v[106:109]
	v_mfma_f32_16x16x32_bf16 v[94:97], v[162:165], v[186:189], v[94:97]
	v_mfma_f32_16x16x32_bf16 v[90:93], v[170:173], v[186:189], v[90:93]
	v_mfma_f32_16x16x32_bf16 v[78:81], v[162:165], v[198:201], v[78:81]
	v_mfma_f32_16x16x32_bf16 v[74:77], v[170:173], v[198:201], v[74:77]
	v_mfma_f32_16x16x32_bf16 v[70:73], v[162:165], v[212:215], v[70:73]
	v_mfma_f32_16x16x32_bf16 v[66:69], v[170:173], v[212:215], v[66:69]
	v_mfma_f32_16x16x32_bf16 v[110:113], v[166:169], v[182:185], v[110:113]
	v_mfma_f32_16x16x32_bf16 v[106:109], v[174:177], v[182:185], v[106:109]
	v_mfma_f32_16x16x32_bf16 v[94:97], v[166:169], v[190:193], v[94:97]
	v_mfma_f32_16x16x32_bf16 v[90:93], v[174:177], v[190:193], v[90:93]
	v_mfma_f32_16x16x32_bf16 v[78:81], v[166:169], v[206:209], v[78:81]
	v_mfma_f32_16x16x32_bf16 v[74:77], v[174:177], v[206:209], v[74:77]
	v_mfma_f32_16x16x32_bf16 v[70:73], v[166:169], v[216:219], v[70:73]
	v_mfma_f32_16x16x32_bf16 v[66:69], v[174:177], v[216:219], v[66:69]
	s_setprio 0
	s_barrier
; #define PG8_STAGE(bufoff, gbase, voff) do { _Pragma("unroll") for (int _i = 0; _i < 2; ++_i) \
;         __builtin_amdgcn_global_load_lds((const unsigned*)((const char*)(gbase) + (voff)[_i]), (PG8_LAS unsigned*)(lds + (bufoff) + ldsw + _i * 8192), 16, 0, 0); } while (0)
; #define PG8_LDA(dst, b, h) do { _Pragma("unroll") for (int m = 0; m < 4; ++m) _Pragma("unroll") for (int k = 0; k < 2; ++k) dst[m][k] = *(const PG8_LAS bf16x8*)(lds + PG8_SA(b, h) + aoff + m * 2048 + k * 1024); } while (0)
; #define PG8_MMA(ai, bj, At, Bt) do { __builtin_amdgcn_s_setprio(1); _Pragma("unroll") for (int m = 0; m < 4; ++m) _Pragma("unroll") for (int n = 0; n < 2; ++n) _Pragma("unroll") for (int k = 0; k < 2; ++k) \
;         acc[ai][bj][m][n] = __builtin_amdgcn_mfma_f32_16x16x32_bf16(Bt[n][k], At[m][k], acc[ai][bj][m][n], 0, 0, 0); __builtin_amdgcn_s_setprio(0); } while (0)
; #define PG8_WAIT_V(n) asm volatile("s_waitcnt vmcnt(" #n ")" ::: "memory")
; #define PG8_WAIT_L(n) asm volatile("s_waitcnt lgkmcnt(" #n ")" ::: "memory")
; #define PG8_BAR __builtin_amdgcn_s_barrier()
; #define PG8_SCHED __builtin_amdgcn_sched_barrier(0)
; template <class Epi, class Sched, bool ALIGN_EPI = false, bool SP2 = false>
; __device__ __forceinline__ void gemm_phase(PG8_LAS unsigned char* lds, const Gemm g, const Sched& S, const Epi& E) {
;     ...
;             PG8_LDA(At, 1, 1); PG8_STAGE(PG8_SB(1, 0), b3, voffB); PG8_STAGE(PG8_SB(1, 1), b3 + hstepB, voffB); PG8_STAGE(PG8_SA(1, 0), a3, voffA);
;             PG8_WAIT_V(8); PG8_WAIT_L(0); PG8_BAR; PG8_MMA(1, 0, At, B0); PG8_MMA(1, 1, At, B1); PG8_BAR; PG8_SCHED;
;     ...
;         if constexpr (ALIGN_EPI) { if (wr == 0) PG8_BAR; }
	s_add_i32 s22, s53, s37
	v_lshl_add_u64 v[220:221], v[220:221], 0, s[88:89]
	s_mov_b32 m0, s22
	ds_read_b128 v[178:181], v145 offset:49152
	ds_read_b128 v[182:185], v145 offset:50176
	ds_read_b128 v[186:189], v145 offset:51200
	ds_read_b128 v[190:193], v145 offset:52224
	ds_read_b128 v[198:201], v145 offset:53248
	ds_read_b128 v[206:209], v145 offset:54272
	ds_read_b128 v[212:215], v145 offset:55296
	ds_read_b128 v[216:219], v145 offset:56320
	global_load_lds_dwordx4 v[220:221], off
	s_add_i32 m0, s22, 0x2000
	s_add_u32 s20, s20, 0x40080
	v_lshl_add_u64 v[220:221], v[222:223], 0, s[88:89]
	s_addc_u32 s21, s21, 0
	s_add_i32 s22, s54, s37
	global_load_lds_dwordx4 v[220:221], off
	v_lshl_add_u64 v[220:221], s[20:21], 0, v[0:1]
	s_mov_b32 m0, s22
	s_nop 0
	global_load_lds_dwordx4 v[220:221], off
	v_lshl_add_u64 v[220:221], s[20:21], 0, v[132:133]
	s_add_i32 m0, s22, 0x2000
	s_nop 0
	global_load_lds_dwordx4 v[220:221], off
	v_lshl_add_u64 v[220:221], v[224:225], 0, s[88:89]
	s_mov_b32 m0, s43
	s_nop 0
	global_load_lds_dwordx4 v[220:221], off
	v_lshl_add_u64 v[220:221], v[226:227], 0, s[88:89]
	s_mov_b32 m0, s44
	s_nop 0
	global_load_lds_dwordx4 v[220:221], off
	s_waitcnt vmcnt(8)
	s_waitcnt lgkmcnt(0)
	s_barrier
	s_setprio 1
	s_waitcnt lgkmcnt(0)
	v_mfma_f32_16x16x32_bf16 v[62:65], v[146:149], v[178:181], v[62:65]
	v_mfma_f32_16x16x32_bf16 v[58:61], v[154:157], v[178:181], v[58:61]
	v_mfma_f32_16x16x32_bf16 v[54:57], v[146:149], v[186:189], v[54:57]
	v_mfma_f32_16x16x32_bf16 v[50:53], v[154:157], v[186:189], v[50:53]
	v_mfma_f32_16x16x32_bf16 v[38:41], v[146:149], v[198:201], v[38:41]
	v_mfma_f32_16x16x32_bf16 v[34:37], v[154:157], v[198:201], v[34:37]
	v_mfma_f32_16x16x32_bf16 v[22:25], v[146:149], v[212:215], v[22:25]
	v_mfma_f32_16x16x32_bf16 v[18:21], v[154:157], v[212:215], v[18:21]
	v_mfma_f32_16x16x32_bf16 v[62:65], v[150:153], v[182:185], v[62:65]
	v_mfma_f32_16x16x32_bf16 v[58:61], v[158:161], v[182:185], v[58:61]
	v_mfma_f32_16x16x32_bf16 v[54:57], v[150:153], v[190:193], v[54:57]
	v_mfma_f32_16x16x32_bf16 v[50:53], v[158:161], v[190:193], v[50:53]
	v_mfma_f32_16x16x32_bf16 v[38:41], v[150:153], v[206:209], v[38:41]
	v_mfma_f32_16x16x32_bf16 v[34:37], v[158:161], v[206:209], v[34:37]
	v_mfma_f32_16x16x32_bf16 v[22:25], v[150:153], v[216:219], v[22:25]
	v_mfma_f32_16x16x32_bf16 v[18:21], v[158:161], v[216:219], v[18:21]
	s_setprio 0
	s_setprio 1
	v_mfma_f32_16x16x32_bf16 v[46:49], v[162:165], v[178:181], v[46:49]
	v_mfma_f32_16x16x32_bf16 v[42:45], v[170:173], v[178:181], v[42:45]
	v_mfma_f32_16x16x32_bf16 v[30:33], v[162:165], v[186:189], v[30:33]
	v_mfma_f32_16x16x32_bf16 v[26:29], v[170:173], v[186:189], v[26:29]
	v_mfma_f32_16x16x32_bf16 v[14:17], v[162:165], v[198:201], v[14:17]
	v_mfma_f32_16x16x32_bf16 v[10:13], v[170:173], v[198:201], v[10:13]
	v_mfma_f32_16x16x32_bf16 v[6:9], v[162:165], v[212:215], v[6:9]
	v_mfma_f32_16x16x32_bf16 v[2:5], v[170:173], v[212:215], v[2:5]
	v_mfma_f32_16x16x32_bf16 v[46:49], v[166:169], v[182:185], v[46:49]
	v_mfma_f32_16x16x32_bf16 v[42:45], v[174:177], v[182:185], v[42:45]
	v_mfma_f32_16x16x32_bf16 v[30:33], v[166:169], v[190:193], v[30:33]
	v_mfma_f32_16x16x32_bf16 v[26:29], v[174:177], v[190:193], v[26:29]
	v_mfma_f32_16x16x32_bf16 v[14:17], v[166:169], v[206:209], v[14:17]
	v_mfma_f32_16x16x32_bf16 v[10:13], v[174:177], v[206:209], v[10:13]
	v_mfma_f32_16x16x32_bf16 v[6:9], v[166:169], v[216:219], v[6:9]
	v_mfma_f32_16x16x32_bf16 v[2:5], v[174:177], v[216:219], v[2:5]
	s_setprio 0
	s_barrier
	s_add_i32 s52, s52, 2
	s_add_u32 s18, s18, 0x100
	s_addc_u32 s19, s19, 0
	s_add_u32 s50, s50, 0x100
	s_addc_u32 s51, s51, 0
	s_cmp_gt_u32 s52, 13
	s_cbranch_scc0 .LBB0_634
	v_readfirstlane_b32 s100, v238
	s_nop 3
	s_bfe_u32 s100, s100, 0x40006
	s_cmp_ge_u32 s100, 4
	s_cbranch_scc0 .Lepiprio_5
	s_setprio 1

; #define PG8_STAGE(bufoff, gbase, voff) do { _Pragma("unroll") for (int _i = 0; _i < 2; ++_i) \
;         __builtin_amdgcn_global_load_lds((const unsigned*)((const char*)(gbase) + (voff)[_i]), (PG8_LAS unsigned*)(lds + (bufoff) + ldsw + _i * 8192), 16, 0, 0); } while (0)
; #define PG8_LDA(dst, b, h) do { _Pragma("unroll") for (int m = 0; m < 4; ++m) _Pragma("unroll") for (int k = 0; k < 2; ++k) dst[m][k] = *(const PG8_LAS bf16x8*)(lds + PG8_SA(b, h) + aoff + m * 2048 + k * 1024); } while (0)
; #define PG8_LDB(dst, b, h) do { _Pragma("unroll") for (int n = 0; n < 2; ++n) _Pragma("unroll") for (int k = 0; k < 2; ++k) dst[n][k] = *(const PG8_LAS bf16x8*)(lds + PG8_SB(b, h) + boff + n * 2048 + k * 1024); } while (0)
; #define PG8_MMA(ai, bj, At, Bt) do { __builtin_amdgcn_s_setprio(1); _Pragma("unroll") for (int m = 0; m < 4; ++m) _Pragma("unroll") for (int n = 0; n < 2; ++n) _Pragma("unroll") for (int k = 0; k < 2; ++k) \
;         acc[ai][bj][m][n] = __builtin_amdgcn_mfma_f32_16x16x32_bf16(Bt[n][k], At[m][k], acc[ai][bj][m][n], 0, 0, 0); __builtin_amdgcn_s_setprio(0); } while (0)
; #define PG8_WAIT_V(n) asm volatile("s_waitcnt vmcnt(" #n ")" ::: "memory")
; #define PG8_WAIT_L(n) asm volatile("s_waitcnt lgkmcnt(" #n ")" ::: "memory")
; #define PG8_BAR __builtin_amdgcn_s_barrier()
; #define PG8_SCHED __builtin_amdgcn_sched_barrier(0)
; template <class Epi, class Sched, bool ALIGN_EPI = false, bool SP2 = false>
; __device__ __forceinline__ void gemm_phase(PG8_LAS unsigned char* lds, const Gemm g, const Sched& S, const Epi& E) {
;     ...
;         for (int t = 0; t < nt; t += 2) {
;             const bool last = (t == nt - 2);
;             const char* a1 = cA + (size_t)(t + 1) * kstep;
;             const char* a2 = last ? nA : cA + (size_t)(t + 2) * kstep; const char* b2 = last ? nB : cB + (size_t)(t + 2) * kstep;
;             const char* a3 = a2 + kstep; const char* b3 = b2 + kstep;
;             if (last && has_next) S.a_ready(nxt);
;             if constexpr (SP2) {
;             PG8_LDB(B0, 0, 0); PG8_LDB(B1, 0, 1); PG8_SCHED; PG8_LDA(At, 0, 0); PG8_STAGE(PG8_SA(1, 1), a1 + hstepA, voffA);
;             PG8_WAIT_V(8); PG8_WAIT_L(0); PG8_BAR; PG8_MMA(0, 0, At, B0); PG8_MMA(0, 1, At, B1); PG8_BAR; PG8_SCHED;
;             PG8_LDA(At, 0, 1); PG8_STAGE(PG8_SB(0, 0), b2, voffB); PG8_STAGE(PG8_SB(0, 1), b2 + hstepB, voffB); PG8_STAGE(PG8_SA(0, 0), a2, voffA);
.LBB0_855:
	s_add_u32 s20, s18, 0xfffe0080
	s_addc_u32 s21, s19, -1
	s_add_i32 s49, 0, 0x10000
	s_cmp_eq_u32 s48, 4
	s_cselect_b32 s23, s11, s21
	s_cselect_b32 s22, s44, s20
	s_cselect_b32 s21, s9, s47
	s_cselect_b32 s20, s45, s46
	s_add_i32 s52, 0, 0x14000
	v_add_u32_e32 v134, s49, v183
	v_add_u32_e32 v168, s52, v183
	ds_read_b128 v[106:109], v134
	ds_read_b128 v[114:117], v134 offset:1024
	ds_read_b128 v[126:129], v134 offset:2048
	ds_read_b128 v[134:137], v134 offset:3072
	ds_read_b128 v[138:141], v168
	ds_read_b128 v[142:145], v168 offset:1024
	ds_read_b128 v[154:157], v168 offset:2048
	ds_read_b128 v[168:171], v168 offset:3072
	v_lshl_add_u64 v[180:181], s[18:19], 0, v[164:165]
	s_add_i32 m0, s34, 0xc000
	ds_read_b128 v[172:175], v185
	ds_read_b128 v[176:179], v185 offset:1024
	ds_read_b128 v[186:189], v185 offset:2048
	ds_read_b128 v[190:193], v185 offset:3072
	ds_read_b128 v[198:201], v185 offset:4096
	ds_read_b128 v[206:209], v185 offset:5120
	ds_read_b128 v[212:215], v185 offset:6144
	ds_read_b128 v[216:219], v185 offset:7168
	global_load_lds_dwordx4 v[180:181], off
	v_lshl_add_u64 v[180:181], s[18:19], 0, v[166:167]
	s_add_i32 m0, s34, 0xe000
	s_nop 0
	global_load_lds_dwordx4 v[180:181], off
	s_waitcnt vmcnt(8)
	s_waitcnt lgkmcnt(0)
	s_barrier
	s_setprio 1
	s_waitcnt lgkmcnt(0)
	v_mfma_f32_16x16x32_bf16 v[150:153], v[106:109], v[172:175], v[150:153]
	v_mfma_f32_16x16x32_bf16 v[146:149], v[126:129], v[172:175], v[146:149]
	v_mfma_f32_16x16x32_bf16 v[118:121], v[106:109], v[186:189], v[118:121]
	v_mfma_f32_16x16x32_bf16 v[110:113], v[126:129], v[186:189], v[110:113]
	v_mfma_f32_16x16x32_bf16 v[94:97], v[106:109], v[198:201], v[94:97]
	v_mfma_f32_16x16x32_bf16 v[90:93], v[126:129], v[198:201], v[90:93]
	v_mfma_f32_16x16x32_bf16 v[78:81], v[106:109], v[212:215], v[78:81]
	v_mfma_f32_16x16x32_bf16 v[74:77], v[126:129], v[212:215], v[74:77]
	v_mfma_f32_16x16x32_bf16 v[150:153], v[114:117], v[176:179], v[150:153]
	v_mfma_f32_16x16x32_bf16 v[146:149], v[134:137], v[176:179], v[146:149]
	v_mfma_f32_16x16x32_bf16 v[118:121], v[114:117], v[190:193], v[118:121]
	v_mfma_f32_16x16x32_bf16 v[110:113], v[134:137], v[190:193], v[110:113]
	v_mfma_f32_16x16x32_bf16 v[94:97], v[114:117], v[206:209], v[94:97]
	v_mfma_f32_16x16x32_bf16 v[90:93], v[134:137], v[206:209], v[90:93]
	v_mfma_f32_16x16x32_bf16 v[78:81], v[114:117], v[216:219], v[78:81]
	v_mfma_f32_16x16x32_bf16 v[74:77], v[134:137], v[216:219], v[74:77]
	s_setprio 0
	s_setprio 1
	v_mfma_f32_16x16x32_bf16 v[130:133], v[138:141], v[172:175], v[130:133]
	v_mfma_f32_16x16x32_bf16 v[122:125], v[154:157], v[172:175], v[122:125]
	v_mfma_f32_16x16x32_bf16 v[102:105], v[138:141], v[186:189], v[102:105]
	v_mfma_f32_16x16x32_bf16 v[98:101], v[154:157], v[186:189], v[98:101]
	v_mfma_f32_16x16x32_bf16 v[86:89], v[138:141], v[198:201], v[86:89]
	v_mfma_f32_16x16x32_bf16 v[82:85], v[154:157], v[198:201], v[82:85]
	v_mfma_f32_16x16x32_bf16 v[70:73], v[138:141], v[212:215], v[70:73]
	v_mfma_f32_16x16x32_bf16 v[66:69], v[154:157], v[212:215], v[66:69]
	v_mfma_f32_16x16x32_bf16 v[130:133], v[142:145], v[176:179], v[130:133]
	v_mfma_f32_16x16x32_bf16 v[122:125], v[168:171], v[176:179], v[122:125]
	v_mfma_f32_16x16x32_bf16 v[102:105], v[142:145], v[190:193], v[102:105]
	v_mfma_f32_16x16x32_bf16 v[98:101], v[168:171], v[190:193], v[98:101]
	v_mfma_f32_16x16x32_bf16 v[86:89], v[142:145], v[206:209], v[86:89]
	v_mfma_f32_16x16x32_bf16 v[82:85], v[168:171], v[206:209], v[82:85]
	v_mfma_f32_16x16x32_bf16 v[70:73], v[142:145], v[216:219], v[70:73]
	v_mfma_f32_16x16x32_bf16 v[66:69], v[168:171], v[216:219], v[66:69]
	s_setprio 0
	s_barrier
	s_add_i32 s49, s49, s31
	v_lshl_add_u64 v[180:181], s[20:21], 0, v[0:1]
	s_mov_b32 m0, s49
	ds_read_b128 v[172:175], v185 offset:16384
	ds_read_b128 v[176:179], v185 offset:17408
	ds_read_b128 v[186:189], v185 offset:18432
	ds_read_b128 v[190:193], v185 offset:19456
	ds_read_b128 v[198:201], v185 offset:20480
	ds_read_b128 v[206:209], v185 offset:21504
	ds_read_b128 v[212:215], v185 offset:22528
	ds_read_b128 v[216:219], v185 offset:23552
	global_load_lds_dwordx4 v[180:181], off
	s_add_i32 m0, s49, 0x2000
	s_add_u32 s50, s20, 0x20000
	v_lshl_add_u64 v[220:221], s[20:21], 0, v[162:163]
	s_addc_u32 s51, s21, 0
	s_add_i32 s49, s52, s31
	global_load_lds_dwordx4 v[220:221], off
	v_lshl_add_u64 v[222:223], s[50:51], 0, v[0:1]
	s_mov_b32 m0, s49
	v_lshl_add_u64 v[224:225], s[22:23], 0, v[160:161]
	global_load_lds_dwordx4 v[222:223], off
	v_lshl_add_u64 v[222:223], s[50:51], 0, v[162:163]
	s_add_i32 m0, s49, 0x2000
	s_nop 0
	global_load_lds_dwordx4 v[222:223], off
	v_lshl_add_u64 v[222:223], s[22:23], 0, v[158:159]
	s_mov_b32 m0, s34
	s_nop 0
	global_load_lds_dwordx4 v[222:223], off
	s_mov_b32 m0, s35
	s_nop 0
	global_load_lds_dwordx4 v[224:225], off
	s_waitcnt vmcnt(8)
	s_waitcnt lgkmcnt(0)
	s_barrier
; #define PG8_STAGE(bufoff, gbase, voff) do { _Pragma("unroll") for (int _i = 0; _i < 2; ++_i) \
;         __builtin_amdgcn_global_load_lds((const unsigned*)((const char*)(gbase) + (voff)[_i]), (PG8_LAS unsigned*)(lds + (bufoff) + ldsw + _i * 8192), 16, 0, 0); } while (0)
; #define PG8_LDA(dst, b, h) do { _Pragma("unroll") for (int m = 0; m < 4; ++m) _Pragma("unroll") for (int k = 0; k < 2; ++k) dst[m][k] = *(const PG8_LAS bf16x8*)(lds + PG8_SA(b, h) + aoff + m * 2048 + k * 1024); } while (0)
; #define PG8_LDB(dst, b, h) do { _Pragma("unroll") for (int n = 0; n < 2; ++n) _Pragma("unroll") for (int k = 0; k < 2; ++k) dst[n][k] = *(const PG8_LAS bf16x8*)(lds + PG8_SB(b, h) + boff + n * 2048 + k * 1024); } while (0)
; #define PG8_MMA(ai, bj, At, Bt) do { __builtin_amdgcn_s_setprio(1); _Pragma("unroll") for (int m = 0; m < 4; ++m) _Pragma("unroll") for (int n = 0; n < 2; ++n) _Pragma("unroll") for (int k = 0; k < 2; ++k) \
;         acc[ai][bj][m][n] = __builtin_amdgcn_mfma_f32_16x16x32_bf16(Bt[n][k], At[m][k], acc[ai][bj][m][n], 0, 0, 0); __builtin_amdgcn_s_setprio(0); } while (0)
; #define PG8_WAIT_V(n) asm volatile("s_waitcnt vmcnt(" #n ")" ::: "memory")
; #define PG8_WAIT_L(n) asm volatile("s_waitcnt lgkmcnt(" #n ")" ::: "memory")
; #define PG8_BAR __builtin_amdgcn_s_barrier()
; #define PG8_SCHED __builtin_amdgcn_sched_barrier(0)
; template <class Epi, class Sched, bool ALIGN_EPI = false, bool SP2 = false>
; __device__ __forceinline__ void gemm_phase(PG8_LAS unsigned char* lds, const Gemm g, const Sched& S, const Epi& E) {
;     ...
;             PG8_WAIT_V(8); PG8_WAIT_L(0); PG8_BAR; PG8_MMA(1, 0, At, B0); PG8_MMA(1, 1, At, B1); PG8_BAR; PG8_SCHED;
;             PG8_LDB(B0, 1, 0); PG8_LDB(B1, 1, 1); PG8_SCHED; PG8_LDA(At, 1, 0); PG8_STAGE(PG8_SA(0, 1), a2 + hstepA, voffA);
;             PG8_WAIT_V(8); PG8_WAIT_L(0); PG8_BAR; PG8_MMA(0, 0, At, B0); PG8_MMA(0, 1, At, B1); PG8_BAR; PG8_SCHED;
	s_setprio 1
	s_waitcnt lgkmcnt(0)
	v_mfma_f32_16x16x32_bf16 v[62:65], v[106:109], v[172:175], v[62:65]
	v_mfma_f32_16x16x32_bf16 v[58:61], v[126:129], v[172:175], v[58:61]
	v_mfma_f32_16x16x32_bf16 v[46:49], v[106:109], v[186:189], v[46:49]
	v_mfma_f32_16x16x32_bf16 v[42:45], v[126:129], v[186:189], v[42:45]
	v_mfma_f32_16x16x32_bf16 v[30:33], v[106:109], v[198:201], v[30:33]
	v_mfma_f32_16x16x32_bf16 v[26:29], v[126:129], v[198:201], v[26:29]
	v_mfma_f32_16x16x32_bf16 v[14:17], v[106:109], v[212:215], v[14:17]
	v_mfma_f32_16x16x32_bf16 v[10:13], v[126:129], v[212:215], v[10:13]
	v_mfma_f32_16x16x32_bf16 v[62:65], v[114:117], v[176:179], v[62:65]
	v_mfma_f32_16x16x32_bf16 v[58:61], v[134:137], v[176:179], v[58:61]
	v_mfma_f32_16x16x32_bf16 v[46:49], v[114:117], v[190:193], v[46:49]
	v_mfma_f32_16x16x32_bf16 v[42:45], v[134:137], v[190:193], v[42:45]
	v_mfma_f32_16x16x32_bf16 v[30:33], v[114:117], v[206:209], v[30:33]
	v_mfma_f32_16x16x32_bf16 v[26:29], v[134:137], v[206:209], v[26:29]
	v_mfma_f32_16x16x32_bf16 v[14:17], v[114:117], v[216:219], v[14:17]
	v_mfma_f32_16x16x32_bf16 v[10:13], v[134:137], v[216:219], v[10:13]
	s_setprio 0
	s_setprio 1
	v_mfma_f32_16x16x32_bf16 v[54:57], v[138:141], v[172:175], v[54:57]
	v_mfma_f32_16x16x32_bf16 v[50:53], v[154:157], v[172:175], v[50:53]
	v_mfma_f32_16x16x32_bf16 v[38:41], v[138:141], v[186:189], v[38:41]
	v_mfma_f32_16x16x32_bf16 v[34:37], v[154:157], v[186:189], v[34:37]
	v_mfma_f32_16x16x32_bf16 v[22:25], v[138:141], v[198:201], v[22:25]
	v_mfma_f32_16x16x32_bf16 v[18:21], v[154:157], v[198:201], v[18:21]
	v_mfma_f32_16x16x32_bf16 v[6:9], v[138:141], v[212:215], v[6:9]
	v_mfma_f32_16x16x32_bf16 v[2:5], v[154:157], v[212:215], v[2:5]
	v_mfma_f32_16x16x32_bf16 v[54:57], v[142:145], v[176:179], v[54:57]
	v_mfma_f32_16x16x32_bf16 v[50:53], v[168:171], v[176:179], v[50:53]
	v_mfma_f32_16x16x32_bf16 v[38:41], v[142:145], v[190:193], v[38:41]
	v_mfma_f32_16x16x32_bf16 v[34:37], v[168:171], v[190:193], v[34:37]
	v_mfma_f32_16x16x32_bf16 v[22:25], v[142:145], v[206:209], v[22:25]
	v_mfma_f32_16x16x32_bf16 v[18:21], v[168:171], v[206:209], v[18:21]
	v_mfma_f32_16x16x32_bf16 v[6:9], v[142:145], v[216:219], v[6:9]
	v_mfma_f32_16x16x32_bf16 v[2:5], v[168:171], v[216:219], v[2:5]
	s_setprio 0
	s_barrier
	s_add_i32 s49, 0, 0x18000
	s_add_i32 s50, 0, 0x1c000
	v_add_u32_e32 v134, s49, v183
	v_add_u32_e32 v168, s50, v183
	ds_read_b128 v[106:109], v134
	ds_read_b128 v[114:117], v134 offset:1024
	ds_read_b128 v[126:129], v134 offset:2048
	ds_read_b128 v[134:137], v134 offset:3072
	ds_read_b128 v[138:141], v168
	ds_read_b128 v[142:145], v168 offset:1024
	ds_read_b128 v[154:157], v168 offset:2048
	ds_read_b128 v[168:171], v168 offset:3072
	s_add_u32 s22, s22, 0x20000
	s_addc_u32 s23, s23, 0
	s_mov_b32 m0, s38
	v_lshl_add_u64 v[226:227], s[22:23], 0, v[158:159]
	ds_read_b128 v[172:175], v185 offset:32768
	ds_read_b128 v[176:179], v185 offset:33792
	ds_read_b128 v[186:189], v185 offset:34816
	ds_read_b128 v[190:193], v185 offset:35840
	ds_read_b128 v[198:201], v185 offset:36864
	ds_read_b128 v[206:209], v185 offset:37888
	ds_read_b128 v[212:215], v185 offset:38912
	ds_read_b128 v[216:219], v185 offset:39936
	global_load_lds_dwordx4 v[226:227], off
	v_lshl_add_u64 v[226:227], s[22:23], 0, v[160:161]
	s_mov_b32 m0, s39
	s_nop 0
	global_load_lds_dwordx4 v[226:227], off
	s_waitcnt vmcnt(8)
	s_waitcnt lgkmcnt(0)
	s_barrier
	s_setprio 1
	s_waitcnt lgkmcnt(0)
	v_mfma_f32_16x16x32_bf16 v[150:153], v[106:109], v[172:175], v[150:153]
	v_mfma_f32_16x16x32_bf16 v[146:149], v[126:129], v[172:175], v[146:149]
	v_mfma_f32_16x16x32_bf16 v[118:121], v[106:109], v[186:189], v[118:121]
	v_mfma_f32_16x16x32_bf16 v[110:113], v[126:129], v[186:189], v[110:113]
	v_mfma_f32_16x16x32_bf16 v[94:97], v[106:109], v[198:201], v[94:97]
	v_mfma_f32_16x16x32_bf16 v[90:93], v[126:129], v[198:201], v[90:93]
	v_mfma_f32_16x16x32_bf16 v[78:81], v[106:109], v[212:215], v[78:81]
	v_mfma_f32_16x16x32_bf16 v[74:77], v[126:129], v[212:215], v[74:77]
	v_mfma_f32_16x16x32_bf16 v[150:153], v[114:117], v[176:179], v[150:153]
	v_mfma_f32_16x16x32_bf16 v[146:149], v[134:137], v[176:179], v[146:149]
	v_mfma_f32_16x16x32_bf16 v[118:121], v[114:117], v[190:193], v[118:121]
	v_mfma_f32_16x16x32_bf16 v[110:113], v[134:137], v[190:193], v[110:113]
	v_mfma_f32_16x16x32_bf16 v[94:97], v[114:117], v[206:209], v[94:97]
	v_mfma_f32_16x16x32_bf16 v[90:93], v[134:137], v[206:209], v[90:93]
	v_mfma_f32_16x16x32_bf16 v[78:81], v[114:117], v[216:219], v[78:81]
	v_mfma_f32_16x16x32_bf16 v[74:77], v[134:137], v[216:219], v[74:77]
	s_setprio 0
	s_setprio 1
	v_mfma_f32_16x16x32_bf16 v[130:133], v[138:141], v[172:175], v[130:133]
	v_mfma_f32_16x16x32_bf16 v[122:125], v[154:157], v[172:175], v[122:125]
	v_mfma_f32_16x16x32_bf16 v[102:105], v[138:141], v[186:189], v[102:105]
	v_mfma_f32_16x16x32_bf16 v[98:101], v[154:157], v[186:189], v[98:101]
	v_mfma_f32_16x16x32_bf16 v[86:89], v[138:141], v[198:201], v[86:89]
	v_mfma_f32_16x16x32_bf16 v[82:85], v[154:157], v[198:201], v[82:85]
	v_mfma_f32_16x16x32_bf16 v[70:73], v[138:141], v[212:215], v[70:73]
	v_mfma_f32_16x16x32_bf16 v[66:69], v[154:157], v[212:215], v[66:69]
	v_mfma_f32_16x16x32_bf16 v[130:133], v[142:145], v[176:179], v[130:133]
	v_mfma_f32_16x16x32_bf16 v[122:125], v[168:171], v[176:179], v[122:125]
	v_mfma_f32_16x16x32_bf16 v[102:105], v[142:145], v[190:193], v[102:105]
	v_mfma_f32_16x16x32_bf16 v[98:101], v[168:171], v[190:193], v[98:101]
	v_mfma_f32_16x16x32_bf16 v[86:89], v[142:145], v[206:209], v[86:89]
	v_mfma_f32_16x16x32_bf16 v[82:85], v[168:171], v[206:209], v[82:85]
	v_mfma_f32_16x16x32_bf16 v[70:73], v[142:145], v[216:219], v[70:73]
	v_mfma_f32_16x16x32_bf16 v[66:69], v[168:171], v[216:219], v[66:69]
	s_setprio 0
	s_barrier
; #define PG8_STAGE(bufoff, gbase, voff) do { _Pragma("unroll") for (int _i = 0; _i < 2; ++_i) \
;         __builtin_amdgcn_global_load_lds((const unsigned*)((const char*)(gbase) + (voff)[_i]), (PG8_LAS unsigned*)(lds + (bufoff) + ldsw + _i * 8192), 16, 0, 0); } while (0)
; #define PG8_LDA(dst, b, h) do { _Pragma("unroll") for (int m = 0; m < 4; ++m) _Pragma("unroll") for (int k = 0; k < 2; ++k) dst[m][k] = *(const PG8_LAS bf16x8*)(lds + PG8_SA(b, h) + aoff + m * 2048 + k * 1024); } while (0)
; #define PG8_MMA(ai, bj, At, Bt) do { __builtin_amdgcn_s_setprio(1); _Pragma("unroll") for (int m = 0; m < 4; ++m) _Pragma("unroll") for (int n = 0; n < 2; ++n) _Pragma("unroll") for (int k = 0; k < 2; ++k) \
;         acc[ai][bj][m][n] = __builtin_amdgcn_mfma_f32_16x16x32_bf16(Bt[n][k], At[m][k], acc[ai][bj][m][n], 0, 0, 0); __builtin_amdgcn_s_setprio(0); } while (0)
; #define PG8_WAIT_V(n) asm volatile("s_waitcnt vmcnt(" #n ")" ::: "memory")
; #define PG8_WAIT_L(n) asm volatile("s_waitcnt lgkmcnt(" #n ")" ::: "memory")
; #define PG8_BAR __builtin_amdgcn_s_barrier()
; #define PG8_SCHED __builtin_amdgcn_sched_barrier(0)
; template <class Epi, class Sched, bool ALIGN_EPI = false, bool SP2 = false>
; __device__ __forceinline__ void gemm_phase(PG8_LAS unsigned char* lds, const Gemm g, const Sched& S, const Epi& E) {
;     ...
;             PG8_LDA(At, 1, 1); PG8_STAGE(PG8_SB(1, 0), b3, voffB); PG8_STAGE(PG8_SB(1, 1), b3 + hstepB, voffB); PG8_STAGE(PG8_SA(1, 0), a3, voffA);
;             PG8_WAIT_V(8); PG8_WAIT_L(0); PG8_BAR; PG8_MMA(1, 0, At, B0); PG8_MMA(1, 1, At, B1); PG8_BAR; PG8_SCHED;
;     ...
;         if constexpr (ALIGN_EPI) { if (wr == 0) PG8_BAR; }
	s_add_i32 s22, s49, s31
	v_lshl_add_u64 v[180:181], v[180:181], 0, s[88:89]
	s_mov_b32 m0, s22
	ds_read_b128 v[172:175], v185 offset:49152
	ds_read_b128 v[176:179], v185 offset:50176
	ds_read_b128 v[186:189], v185 offset:51200
	ds_read_b128 v[190:193], v185 offset:52224
	ds_read_b128 v[198:201], v185 offset:53248
	ds_read_b128 v[206:209], v185 offset:54272
	ds_read_b128 v[212:215], v185 offset:55296
	ds_read_b128 v[216:219], v185 offset:56320
	global_load_lds_dwordx4 v[180:181], off
	s_add_i32 m0, s22, 0x2000
	s_add_u32 s20, s20, 0x20080
	v_lshl_add_u64 v[180:181], v[220:221], 0, s[88:89]
	s_addc_u32 s21, s21, 0
	s_add_i32 s22, s50, s31
	global_load_lds_dwordx4 v[180:181], off
	v_lshl_add_u64 v[180:181], s[20:21], 0, v[0:1]
	s_mov_b32 m0, s22
	s_nop 0
	global_load_lds_dwordx4 v[180:181], off
	v_lshl_add_u64 v[180:181], s[20:21], 0, v[162:163]
	s_add_i32 m0, s22, 0x2000
	s_nop 0
	global_load_lds_dwordx4 v[180:181], off
	v_lshl_add_u64 v[180:181], v[222:223], 0, s[88:89]
	s_mov_b32 m0, s40
	s_nop 0
	global_load_lds_dwordx4 v[180:181], off
	v_lshl_add_u64 v[180:181], v[224:225], 0, s[88:89]
	s_mov_b32 m0, s41
	s_nop 0
	global_load_lds_dwordx4 v[180:181], off
	s_waitcnt vmcnt(8)
	s_waitcnt lgkmcnt(0)
	s_barrier
	s_setprio 1
	s_waitcnt lgkmcnt(0)
	v_mfma_f32_16x16x32_bf16 v[62:65], v[106:109], v[172:175], v[62:65]
	v_mfma_f32_16x16x32_bf16 v[58:61], v[126:129], v[172:175], v[58:61]
	v_mfma_f32_16x16x32_bf16 v[46:49], v[106:109], v[186:189], v[46:49]
	v_mfma_f32_16x16x32_bf16 v[42:45], v[126:129], v[186:189], v[42:45]
	v_mfma_f32_16x16x32_bf16 v[30:33], v[106:109], v[198:201], v[30:33]
	v_mfma_f32_16x16x32_bf16 v[26:29], v[126:129], v[198:201], v[26:29]
	v_mfma_f32_16x16x32_bf16 v[14:17], v[106:109], v[212:215], v[14:17]
	v_mfma_f32_16x16x32_bf16 v[10:13], v[126:129], v[212:215], v[10:13]
	v_mfma_f32_16x16x32_bf16 v[62:65], v[114:117], v[176:179], v[62:65]
	v_mfma_f32_16x16x32_bf16 v[58:61], v[134:137], v[176:179], v[58:61]
	v_mfma_f32_16x16x32_bf16 v[46:49], v[114:117], v[190:193], v[46:49]
	v_mfma_f32_16x16x32_bf16 v[42:45], v[134:137], v[190:193], v[42:45]
	v_mfma_f32_16x16x32_bf16 v[30:33], v[114:117], v[206:209], v[30:33]
	v_mfma_f32_16x16x32_bf16 v[26:29], v[134:137], v[206:209], v[26:29]
	v_mfma_f32_16x16x32_bf16 v[14:17], v[114:117], v[216:219], v[14:17]
	v_mfma_f32_16x16x32_bf16 v[10:13], v[134:137], v[216:219], v[10:13]
	s_setprio 0
	s_setprio 1
	v_mfma_f32_16x16x32_bf16 v[54:57], v[138:141], v[172:175], v[54:57]
	v_mfma_f32_16x16x32_bf16 v[50:53], v[154:157], v[172:175], v[50:53]
	v_mfma_f32_16x16x32_bf16 v[38:41], v[138:141], v[186:189], v[38:41]
	v_mfma_f32_16x16x32_bf16 v[34:37], v[154:157], v[186:189], v[34:37]
	v_mfma_f32_16x16x32_bf16 v[22:25], v[138:141], v[198:201], v[22:25]
	v_mfma_f32_16x16x32_bf16 v[18:21], v[154:157], v[198:201], v[18:21]
	v_mfma_f32_16x16x32_bf16 v[6:9], v[138:141], v[212:215], v[6:9]
	v_mfma_f32_16x16x32_bf16 v[2:5], v[154:157], v[212:215], v[2:5]
	v_mfma_f32_16x16x32_bf16 v[54:57], v[142:145], v[176:179], v[54:57]
	v_mfma_f32_16x16x32_bf16 v[50:53], v[168:171], v[176:179], v[50:53]
	v_mfma_f32_16x16x32_bf16 v[38:41], v[142:145], v[190:193], v[38:41]
	v_mfma_f32_16x16x32_bf16 v[34:37], v[168:171], v[190:193], v[34:37]
	v_mfma_f32_16x16x32_bf16 v[22:25], v[142:145], v[206:209], v[22:25]
	v_mfma_f32_16x16x32_bf16 v[18:21], v[168:171], v[206:209], v[18:21]
	v_mfma_f32_16x16x32_bf16 v[6:9], v[142:145], v[216:219], v[6:9]
	v_mfma_f32_16x16x32_bf16 v[2:5], v[168:171], v[216:219], v[2:5]
	s_setprio 0
	s_barrier
	s_add_i32 s48, s48, 2
	s_add_u32 s18, s18, 0x100
	s_addc_u32 s19, s19, 0
	s_add_u32 s46, s46, 0x100
	s_addc_u32 s47, s47, 0
	s_cmp_gt_u32 s48, 5
	s_cbranch_scc0 .LBB0_855
	v_readfirstlane_b32 s100, v238
	s_nop 3
	s_bfe_u32 s100, s100, 0x40006
	s_cmp_ge_u32 s100, 4
	s_cbranch_scc0 .Lepiprio_7
	s_setprio 1

; #define PG8_STAGE(bufoff, gbase, voff) do { _Pragma("unroll") for (int _i = 0; _i < 2; ++_i) \
;         __builtin_amdgcn_global_load_lds((const unsigned*)((const char*)(gbase) + (voff)[_i]), (PG8_LAS unsigned*)(lds + (bufoff) + ldsw + _i * 8192), 16, 0, 0); } while (0)
; #define PG8_LDA(dst, b, h) do { _Pragma("unroll") for (int m = 0; m < 4; ++m) _Pragma("unroll") for (int k = 0; k < 2; ++k) dst[m][k] = *(const PG8_LAS bf16x8*)(lds + PG8_SA(b, h) + aoff + m * 2048 + k * 1024); } while (0)
; #define PG8_LDB(dst, b, h) do { _Pragma("unroll") for (int n = 0; n < 2; ++n) _Pragma("unroll") for (int k = 0; k < 2; ++k) dst[n][k] = *(const PG8_LAS bf16x8*)(lds + PG8_SB(b, h) + boff + n * 2048 + k * 1024); } while (0)
; #define PG8_MMA(ai, bj, At, Bt) do { __builtin_amdgcn_s_setprio(1); _Pragma("unroll") for (int m = 0; m < 4; ++m) _Pragma("unroll") for (int n = 0; n < 2; ++n) _Pragma("unroll") for (int k = 0; k < 2; ++k) \
;         acc[ai][bj][m][n] = __builtin_amdgcn_mfma_f32_16x16x32_bf16(Bt[n][k], At[m][k], acc[ai][bj][m][n], 0, 0, 0); __builtin_amdgcn_s_setprio(0); } while (0)
; #define PG8_WAIT_V(n) asm volatile("s_waitcnt vmcnt(" #n ")" ::: "memory")
; #define PG8_WAIT_L(n) asm volatile("s_waitcnt lgkmcnt(" #n ")" ::: "memory")
; #define PG8_BAR __builtin_amdgcn_s_barrier()
; #define PG8_SCHED __builtin_amdgcn_sched_barrier(0)
; template <class Epi, class Sched, bool ALIGN_EPI = false, bool SP2 = false>
; __device__ __forceinline__ void gemm_phase(PG8_LAS unsigned char* lds, const Gemm g, const Sched& S, const Epi& E) {
;     ...
;         for (int t = 0; t < nt; t += 2) {
;             const bool last = (t == nt - 2);
;             const char* a1 = cA + (size_t)(t + 1) * kstep;
;             const char* a2 = last ? nA : cA + (size_t)(t + 2) * kstep; const char* b2 = last ? nB : cB + (size_t)(t + 2) * kstep;
;             const char* a3 = a2 + kstep; const char* b3 = b2 + kstep;
;             if (last && has_next) S.a_ready(nxt);
;             if constexpr (SP2) {
;             PG8_LDB(B0, 0, 0); PG8_LDB(B1, 0, 1); PG8_SCHED; PG8_LDA(At, 0, 0); PG8_STAGE(PG8_SA(1, 1), a1 + hstepA, voffA);
;             PG8_WAIT_V(8); PG8_WAIT_L(0); PG8_BAR; PG8_MMA(0, 0, At, B0); PG8_MMA(0, 1, At, B1); PG8_BAR; PG8_SCHED;
;             PG8_LDA(At, 0, 1); PG8_STAGE(PG8_SB(0, 0), b2, voffB); PG8_STAGE(PG8_SB(0, 1), b2 + hstepB, voffB); PG8_STAGE(PG8_SA(0, 0), a2, voffA);
.LBB0_879:
	s_add_u32 s20, s18, 0xfff00080
	s_addc_u32 s21, s19, -1
	s_add_i32 s49, 0, 0x10000
	s_cmp_eq_u32 s48, 12
	s_cselect_b32 s23, s11, s21
	s_cselect_b32 s22, s44, s20
	s_cselect_b32 s21, s9, s47
	s_cselect_b32 s20, s45, s46
	s_add_i32 s52, 0, 0x14000
	v_add_u32_e32 v126, s49, v249
	v_add_u32_e32 v154, s52, v249
	ds_read_b128 v[106:109], v126
	ds_read_b128 v[114:117], v126 offset:1024
	ds_read_b128 v[122:125], v126 offset:2048
	ds_read_b128 v[126:129], v126 offset:3072
	ds_read_b128 v[134:137], v154
	ds_read_b128 v[138:141], v154 offset:1024
	ds_read_b128 v[150:153], v154 offset:2048
	ds_read_b128 v[154:157], v154 offset:3072
	v_lshl_add_u64 v[198:199], s[18:19], 0, v[218:219]
	s_add_i32 m0, s34, 0xc000
	ds_read_b128 v[158:161], v251
	ds_read_b128 v[162:165], v251 offset:1024
	ds_read_b128 v[170:173], v251 offset:2048
	ds_read_b128 v[174:177], v251 offset:3072
	ds_read_b128 v[178:181], v251 offset:4096
	ds_read_b128 v[182:185], v251 offset:5120
	ds_read_b128 v[186:189], v251 offset:6144
	ds_read_b128 v[190:193], v251 offset:7168
	global_load_lds_dwordx4 v[198:199], off
	v_lshl_add_u64 v[198:199], s[18:19], 0, v[220:221]
	s_add_i32 m0, s34, 0xe000
	s_nop 0
	global_load_lds_dwordx4 v[198:199], off
	s_waitcnt vmcnt(8)
	s_waitcnt lgkmcnt(0)
	s_barrier
	s_setprio 1
	s_waitcnt lgkmcnt(0)
	v_mfma_f32_16x16x32_bf16 v[166:169], v[106:109], v[158:161], v[166:169]
	v_mfma_f32_16x16x32_bf16 v[146:149], v[122:125], v[158:161], v[146:149]
	v_mfma_f32_16x16x32_bf16 v[118:121], v[106:109], v[170:173], v[118:121]
	v_mfma_f32_16x16x32_bf16 v[110:113], v[122:125], v[170:173], v[110:113]
	v_mfma_f32_16x16x32_bf16 v[94:97], v[106:109], v[178:181], v[94:97]
	v_mfma_f32_16x16x32_bf16 v[90:93], v[122:125], v[178:181], v[90:93]
	v_mfma_f32_16x16x32_bf16 v[78:81], v[106:109], v[186:189], v[78:81]
	v_mfma_f32_16x16x32_bf16 v[74:77], v[122:125], v[186:189], v[74:77]
	v_mfma_f32_16x16x32_bf16 v[166:169], v[114:117], v[162:165], v[166:169]
	v_mfma_f32_16x16x32_bf16 v[146:149], v[126:129], v[162:165], v[146:149]
	v_mfma_f32_16x16x32_bf16 v[118:121], v[114:117], v[174:177], v[118:121]
	v_mfma_f32_16x16x32_bf16 v[110:113], v[126:129], v[174:177], v[110:113]
	v_mfma_f32_16x16x32_bf16 v[94:97], v[114:117], v[182:185], v[94:97]
	v_mfma_f32_16x16x32_bf16 v[90:93], v[126:129], v[182:185], v[90:93]
	v_mfma_f32_16x16x32_bf16 v[78:81], v[114:117], v[190:193], v[78:81]
	v_mfma_f32_16x16x32_bf16 v[74:77], v[126:129], v[190:193], v[74:77]
	s_setprio 0
	s_setprio 1
	v_mfma_f32_16x16x32_bf16 v[142:145], v[134:137], v[158:161], v[142:145]
	v_mfma_f32_16x16x32_bf16 v[130:133], v[150:153], v[158:161], v[130:133]
	v_mfma_f32_16x16x32_bf16 v[102:105], v[134:137], v[170:173], v[102:105]
	v_mfma_f32_16x16x32_bf16 v[98:101], v[150:153], v[170:173], v[98:101]
	v_mfma_f32_16x16x32_bf16 v[86:89], v[134:137], v[178:181], v[86:89]
	v_mfma_f32_16x16x32_bf16 v[82:85], v[150:153], v[178:181], v[82:85]
	v_mfma_f32_16x16x32_bf16 v[70:73], v[134:137], v[186:189], v[70:73]
	v_mfma_f32_16x16x32_bf16 v[66:69], v[150:153], v[186:189], v[66:69]
	v_mfma_f32_16x16x32_bf16 v[142:145], v[138:141], v[162:165], v[142:145]
	v_mfma_f32_16x16x32_bf16 v[130:133], v[154:157], v[162:165], v[130:133]
	v_mfma_f32_16x16x32_bf16 v[102:105], v[138:141], v[174:177], v[102:105]
	v_mfma_f32_16x16x32_bf16 v[98:101], v[154:157], v[174:177], v[98:101]
	v_mfma_f32_16x16x32_bf16 v[86:89], v[138:141], v[182:185], v[86:89]
	v_mfma_f32_16x16x32_bf16 v[82:85], v[154:157], v[182:185], v[82:85]
	v_mfma_f32_16x16x32_bf16 v[70:73], v[138:141], v[190:193], v[70:73]
	v_mfma_f32_16x16x32_bf16 v[66:69], v[154:157], v[190:193], v[66:69]
	s_setprio 0
	s_barrier
	s_add_i32 s49, s49, s31
	v_lshl_add_u64 v[198:199], s[20:21], 0, v[0:1]
	s_mov_b32 m0, s49
	ds_read_b128 v[158:161], v251 offset:16384
	ds_read_b128 v[162:165], v251 offset:17408
	ds_read_b128 v[170:173], v251 offset:18432
	ds_read_b128 v[174:177], v251 offset:19456
	ds_read_b128 v[178:181], v251 offset:20480
	ds_read_b128 v[182:185], v251 offset:21504
	ds_read_b128 v[186:189], v251 offset:22528
	ds_read_b128 v[190:193], v251 offset:23552
	global_load_lds_dwordx4 v[198:199], off
	s_add_i32 m0, s49, 0x2000
	s_add_u32 s50, s20, 0x40000
	v_lshl_add_u64 v[200:201], s[20:21], 0, v[216:217]
	s_addc_u32 s51, s21, 0
	s_add_i32 s49, s52, s31
	global_load_lds_dwordx4 v[200:201], off
	v_lshl_add_u64 v[206:207], s[50:51], 0, v[0:1]
	s_mov_b32 m0, s49
	v_lshl_add_u64 v[208:209], s[22:23], 0, v[214:215]
	global_load_lds_dwordx4 v[206:207], off
	v_lshl_add_u64 v[206:207], s[50:51], 0, v[216:217]
	s_add_i32 m0, s49, 0x2000
	s_nop 0
	global_load_lds_dwordx4 v[206:207], off
	v_lshl_add_u64 v[206:207], s[22:23], 0, v[212:213]
	s_mov_b32 m0, s34
	s_nop 0
	global_load_lds_dwordx4 v[206:207], off
	s_mov_b32 m0, s35
	s_nop 0
	global_load_lds_dwordx4 v[208:209], off
	s_waitcnt vmcnt(8)
	s_waitcnt lgkmcnt(0)
	s_barrier
; #define PG8_STAGE(bufoff, gbase, voff) do { _Pragma("unroll") for (int _i = 0; _i < 2; ++_i) \
;         __builtin_amdgcn_global_load_lds((const unsigned*)((const char*)(gbase) + (voff)[_i]), (PG8_LAS unsigned*)(lds + (bufoff) + ldsw + _i * 8192), 16, 0, 0); } while (0)
; #define PG8_LDA(dst, b, h) do { _Pragma("unroll") for (int m = 0; m < 4; ++m) _Pragma("unroll") for (int k = 0; k < 2; ++k) dst[m][k] = *(const PG8_LAS bf16x8*)(lds + PG8_SA(b, h) + aoff + m * 2048 + k * 1024); } while (0)
; #define PG8_LDB(dst, b, h) do { _Pragma("unroll") for (int n = 0; n < 2; ++n) _Pragma("unroll") for (int k = 0; k < 2; ++k) dst[n][k] = *(const PG8_LAS bf16x8*)(lds + PG8_SB(b, h) + boff + n * 2048 + k * 1024); } while (0)
; #define PG8_MMA(ai, bj, At, Bt) do { __builtin_amdgcn_s_setprio(1); _Pragma("unroll") for (int m = 0; m < 4; ++m) _Pragma("unroll") for (int n = 0; n < 2; ++n) _Pragma("unroll") for (int k = 0; k < 2; ++k) \
;         acc[ai][bj][m][n] = __builtin_amdgcn_mfma_f32_16x16x32_bf16(Bt[n][k], At[m][k], acc[ai][bj][m][n], 0, 0, 0); __builtin_amdgcn_s_setprio(0); } while (0)
; #define PG8_WAIT_V(n) asm volatile("s_waitcnt vmcnt(" #n ")" ::: "memory")
; #define PG8_WAIT_L(n) asm volatile("s_waitcnt lgkmcnt(" #n ")" ::: "memory")
; #define PG8_BAR __builtin_amdgcn_s_barrier()
; #define PG8_SCHED __builtin_amdgcn_sched_barrier(0)
; template <class Epi, class Sched, bool ALIGN_EPI = false, bool SP2 = false>
; __device__ __forceinline__ void gemm_phase(PG8_LAS unsigned char* lds, const Gemm g, const Sched& S, const Epi& E) {
;     ...
;             PG8_WAIT_V(8); PG8_WAIT_L(0); PG8_BAR; PG8_MMA(1, 0, At, B0); PG8_MMA(1, 1, At, B1); PG8_BAR; PG8_SCHED;
;             PG8_LDB(B0, 1, 0); PG8_LDB(B1, 1, 1); PG8_SCHED; PG8_LDA(At, 1, 0); PG8_STAGE(PG8_SA(0, 1), a2 + hstepA, voffA);
;             PG8_WAIT_V(8); PG8_WAIT_L(0); PG8_BAR; PG8_MMA(0, 0, At, B0); PG8_MMA(0, 1, At, B1); PG8_BAR; PG8_SCHED;
	s_setprio 1
	s_waitcnt lgkmcnt(0)
	v_mfma_f32_16x16x32_bf16 v[62:65], v[106:109], v[158:161], v[62:65]
	v_mfma_f32_16x16x32_bf16 v[58:61], v[122:125], v[158:161], v[58:61]
	v_mfma_f32_16x16x32_bf16 v[46:49], v[106:109], v[170:173], v[46:49]
	v_mfma_f32_16x16x32_bf16 v[42:45], v[122:125], v[170:173], v[42:45]
	v_mfma_f32_16x16x32_bf16 v[30:33], v[106:109], v[178:181], v[30:33]
	v_mfma_f32_16x16x32_bf16 v[26:29], v[122:125], v[178:181], v[26:29]
	v_mfma_f32_16x16x32_bf16 v[14:17], v[106:109], v[186:189], v[14:17]
	v_mfma_f32_16x16x32_bf16 v[10:13], v[122:125], v[186:189], v[10:13]
	v_mfma_f32_16x16x32_bf16 v[62:65], v[114:117], v[162:165], v[62:65]
	v_mfma_f32_16x16x32_bf16 v[58:61], v[126:129], v[162:165], v[58:61]
	v_mfma_f32_16x16x32_bf16 v[46:49], v[114:117], v[174:177], v[46:49]
	v_mfma_f32_16x16x32_bf16 v[42:45], v[126:129], v[174:177], v[42:45]
	v_mfma_f32_16x16x32_bf16 v[30:33], v[114:117], v[182:185], v[30:33]
	v_mfma_f32_16x16x32_bf16 v[26:29], v[126:129], v[182:185], v[26:29]
	v_mfma_f32_16x16x32_bf16 v[14:17], v[114:117], v[190:193], v[14:17]
	v_mfma_f32_16x16x32_bf16 v[10:13], v[126:129], v[190:193], v[10:13]
	s_setprio 0
	s_setprio 1
	v_mfma_f32_16x16x32_bf16 v[54:57], v[134:137], v[158:161], v[54:57]
	v_mfma_f32_16x16x32_bf16 v[50:53], v[150:153], v[158:161], v[50:53]
	v_mfma_f32_16x16x32_bf16 v[38:41], v[134:137], v[170:173], v[38:41]
	v_mfma_f32_16x16x32_bf16 v[34:37], v[150:153], v[170:173], v[34:37]
	v_mfma_f32_16x16x32_bf16 v[22:25], v[134:137], v[178:181], v[22:25]
	v_mfma_f32_16x16x32_bf16 v[18:21], v[150:153], v[178:181], v[18:21]
	v_mfma_f32_16x16x32_bf16 v[6:9], v[134:137], v[186:189], v[6:9]
	v_mfma_f32_16x16x32_bf16 v[2:5], v[150:153], v[186:189], v[2:5]
	v_mfma_f32_16x16x32_bf16 v[54:57], v[138:141], v[162:165], v[54:57]
	v_mfma_f32_16x16x32_bf16 v[50:53], v[154:157], v[162:165], v[50:53]
	v_mfma_f32_16x16x32_bf16 v[38:41], v[138:141], v[174:177], v[38:41]
	v_mfma_f32_16x16x32_bf16 v[34:37], v[154:157], v[174:177], v[34:37]
	v_mfma_f32_16x16x32_bf16 v[22:25], v[138:141], v[182:185], v[22:25]
	v_mfma_f32_16x16x32_bf16 v[18:21], v[154:157], v[182:185], v[18:21]
	v_mfma_f32_16x16x32_bf16 v[6:9], v[138:141], v[190:193], v[6:9]
	v_mfma_f32_16x16x32_bf16 v[2:5], v[154:157], v[190:193], v[2:5]
	s_setprio 0
	s_barrier
	s_add_i32 s49, 0, 0x18000
	s_add_i32 s50, 0, 0x1c000
	v_add_u32_e32 v126, s49, v249
	v_add_u32_e32 v154, s50, v249
	ds_read_b128 v[106:109], v126
	ds_read_b128 v[114:117], v126 offset:1024
	ds_read_b128 v[122:125], v126 offset:2048
	ds_read_b128 v[126:129], v126 offset:3072
	ds_read_b128 v[134:137], v154
	ds_read_b128 v[138:141], v154 offset:1024
	ds_read_b128 v[150:153], v154 offset:2048
	ds_read_b128 v[154:157], v154 offset:3072
	s_add_u32 s22, s22, 0x100000
	s_addc_u32 s23, s23, 0
	s_mov_b32 m0, s38
	v_lshl_add_u64 v[222:223], s[22:23], 0, v[212:213]
	ds_read_b128 v[158:161], v251 offset:32768
	ds_read_b128 v[162:165], v251 offset:33792
	ds_read_b128 v[170:173], v251 offset:34816
	ds_read_b128 v[174:177], v251 offset:35840
	ds_read_b128 v[178:181], v251 offset:36864
	ds_read_b128 v[182:185], v251 offset:37888
	ds_read_b128 v[186:189], v251 offset:38912
	ds_read_b128 v[190:193], v251 offset:39936
	global_load_lds_dwordx4 v[222:223], off
	v_lshl_add_u64 v[222:223], s[22:23], 0, v[214:215]
	s_mov_b32 m0, s39
	s_nop 0
	global_load_lds_dwordx4 v[222:223], off
	s_waitcnt vmcnt(8)
	s_waitcnt lgkmcnt(0)
	s_barrier
	s_setprio 1
	s_waitcnt lgkmcnt(0)
	v_mfma_f32_16x16x32_bf16 v[166:169], v[106:109], v[158:161], v[166:169]
	v_mfma_f32_16x16x32_bf16 v[146:149], v[122:125], v[158:161], v[146:149]
	v_mfma_f32_16x16x32_bf16 v[118:121], v[106:109], v[170:173], v[118:121]
	v_mfma_f32_16x16x32_bf16 v[110:113], v[122:125], v[170:173], v[110:113]
	v_mfma_f32_16x16x32_bf16 v[94:97], v[106:109], v[178:181], v[94:97]
	v_mfma_f32_16x16x32_bf16 v[90:93], v[122:125], v[178:181], v[90:93]
	v_mfma_f32_16x16x32_bf16 v[78:81], v[106:109], v[186:189], v[78:81]
	v_mfma_f32_16x16x32_bf16 v[74:77], v[122:125], v[186:189], v[74:77]
	v_mfma_f32_16x16x32_bf16 v[166:169], v[114:117], v[162:165], v[166:169]
	v_mfma_f32_16x16x32_bf16 v[146:149], v[126:129], v[162:165], v[146:149]
	v_mfma_f32_16x16x32_bf16 v[118:121], v[114:117], v[174:177], v[118:121]
	v_mfma_f32_16x16x32_bf16 v[110:113], v[126:129], v[174:177], v[110:113]
	v_mfma_f32_16x16x32_bf16 v[94:97], v[114:117], v[182:185], v[94:97]
	v_mfma_f32_16x16x32_bf16 v[90:93], v[126:129], v[182:185], v[90:93]
	v_mfma_f32_16x16x32_bf16 v[78:81], v[114:117], v[190:193], v[78:81]
	v_mfma_f32_16x16x32_bf16 v[74:77], v[126:129], v[190:193], v[74:77]
	s_setprio 0
	s_setprio 1
	v_mfma_f32_16x16x32_bf16 v[142:145], v[134:137], v[158:161], v[142:145]
	v_mfma_f32_16x16x32_bf16 v[130:133], v[150:153], v[158:161], v[130:133]
	v_mfma_f32_16x16x32_bf16 v[102:105], v[134:137], v[170:173], v[102:105]
	v_mfma_f32_16x16x32_bf16 v[98:101], v[150:153], v[170:173], v[98:101]
	v_mfma_f32_16x16x32_bf16 v[86:89], v[134:137], v[178:181], v[86:89]
	v_mfma_f32_16x16x32_bf16 v[82:85], v[150:153], v[178:181], v[82:85]
	v_mfma_f32_16x16x32_bf16 v[70:73], v[134:137], v[186:189], v[70:73]
	v_mfma_f32_16x16x32_bf16 v[66:69], v[150:153], v[186:189], v[66:69]
	v_mfma_f32_16x16x32_bf16 v[142:145], v[138:141], v[162:165], v[142:145]
	v_mfma_f32_16x16x32_bf16 v[130:133], v[154:157], v[162:165], v[130:133]
	v_mfma_f32_16x16x32_bf16 v[102:105], v[138:141], v[174:177], v[102:105]
	v_mfma_f32_16x16x32_bf16 v[98:101], v[154:157], v[174:177], v[98:101]
	v_mfma_f32_16x16x32_bf16 v[86:89], v[138:141], v[182:185], v[86:89]
	v_mfma_f32_16x16x32_bf16 v[82:85], v[154:157], v[182:185], v[82:85]
	v_mfma_f32_16x16x32_bf16 v[70:73], v[138:141], v[190:193], v[70:73]
	v_mfma_f32_16x16x32_bf16 v[66:69], v[154:157], v[190:193], v[66:69]
	s_setprio 0
	s_barrier
; #define PG8_STAGE(bufoff, gbase, voff) do { _Pragma("unroll") for (int _i = 0; _i < 2; ++_i) \
;         __builtin_amdgcn_global_load_lds((const unsigned*)((const char*)(gbase) + (voff)[_i]), (PG8_LAS unsigned*)(lds + (bufoff) + ldsw + _i * 8192), 16, 0, 0); } while (0)
; #define PG8_LDA(dst, b, h) do { _Pragma("unroll") for (int m = 0; m < 4; ++m) _Pragma("unroll") for (int k = 0; k < 2; ++k) dst[m][k] = *(const PG8_LAS bf16x8*)(lds + PG8_SA(b, h) + aoff + m * 2048 + k * 1024); } while (0)
; #define PG8_MMA(ai, bj, At, Bt) do { __builtin_amdgcn_s_setprio(1); _Pragma("unroll") for (int m = 0; m < 4; ++m) _Pragma("unroll") for (int n = 0; n < 2; ++n) _Pragma("unroll") for (int k = 0; k < 2; ++k) \
;         acc[ai][bj][m][n] = __builtin_amdgcn_mfma_f32_16x16x32_bf16(Bt[n][k], At[m][k], acc[ai][bj][m][n], 0, 0, 0); __builtin_amdgcn_s_setprio(0); } while (0)
; #define PG8_WAIT_V(n) asm volatile("s_waitcnt vmcnt(" #n ")" ::: "memory")
; #define PG8_WAIT_L(n) asm volatile("s_waitcnt lgkmcnt(" #n ")" ::: "memory")
; #define PG8_BAR __builtin_amdgcn_s_barrier()
; #define PG8_SCHED __builtin_amdgcn_sched_barrier(0)
; template <class Epi, class Sched, bool ALIGN_EPI = false, bool SP2 = false>
; __device__ __forceinline__ void gemm_phase(PG8_LAS unsigned char* lds, const Gemm g, const Sched& S, const Epi& E) {
;     ...
;             PG8_LDA(At, 1, 1); PG8_STAGE(PG8_SB(1, 0), b3, voffB); PG8_STAGE(PG8_SB(1, 1), b3 + hstepB, voffB); PG8_STAGE(PG8_SA(1, 0), a3, voffA);
;             PG8_WAIT_V(8); PG8_WAIT_L(0); PG8_BAR; PG8_MMA(1, 0, At, B0); PG8_MMA(1, 1, At, B1); PG8_BAR; PG8_SCHED;
;     ...
;         if constexpr (ALIGN_EPI) { if (wr == 0) PG8_BAR; }
	s_add_i32 s22, s49, s31
	v_lshl_add_u64 v[198:199], v[198:199], 0, s[88:89]
	s_mov_b32 m0, s22
	ds_read_b128 v[158:161], v251 offset:49152
	ds_read_b128 v[162:165], v251 offset:50176
	ds_read_b128 v[170:173], v251 offset:51200
	ds_read_b128 v[174:177], v251 offset:52224
	ds_read_b128 v[178:181], v251 offset:53248
	ds_read_b128 v[182:185], v251 offset:54272
	ds_read_b128 v[186:189], v251 offset:55296
	ds_read_b128 v[190:193], v251 offset:56320
	global_load_lds_dwordx4 v[198:199], off
	s_add_i32 m0, s22, 0x2000
	s_add_u32 s20, s20, 0x40080
	v_lshl_add_u64 v[198:199], v[200:201], 0, s[88:89]
	s_addc_u32 s21, s21, 0
	s_add_i32 s22, s50, s31
	global_load_lds_dwordx4 v[198:199], off
	v_lshl_add_u64 v[198:199], s[20:21], 0, v[0:1]
	s_mov_b32 m0, s22
	s_nop 0
	global_load_lds_dwordx4 v[198:199], off
	v_lshl_add_u64 v[198:199], s[20:21], 0, v[216:217]
	s_add_i32 m0, s22, 0x2000
	s_nop 0
	global_load_lds_dwordx4 v[198:199], off
	v_lshl_add_u64 v[198:199], v[206:207], 0, s[88:89]
	s_mov_b32 m0, s40
	s_nop 0
	global_load_lds_dwordx4 v[198:199], off
	v_lshl_add_u64 v[198:199], v[208:209], 0, s[88:89]
	s_mov_b32 m0, s41
	s_nop 0
	global_load_lds_dwordx4 v[198:199], off
	s_waitcnt vmcnt(8)
	s_waitcnt lgkmcnt(0)
	s_barrier
	s_setprio 1
	s_waitcnt lgkmcnt(0)
	v_mfma_f32_16x16x32_bf16 v[62:65], v[106:109], v[158:161], v[62:65]
	v_mfma_f32_16x16x32_bf16 v[58:61], v[122:125], v[158:161], v[58:61]
	v_mfma_f32_16x16x32_bf16 v[46:49], v[106:109], v[170:173], v[46:49]
	v_mfma_f32_16x16x32_bf16 v[42:45], v[122:125], v[170:173], v[42:45]
	v_mfma_f32_16x16x32_bf16 v[30:33], v[106:109], v[178:181], v[30:33]
	v_mfma_f32_16x16x32_bf16 v[26:29], v[122:125], v[178:181], v[26:29]
	v_mfma_f32_16x16x32_bf16 v[14:17], v[106:109], v[186:189], v[14:17]
	v_mfma_f32_16x16x32_bf16 v[10:13], v[122:125], v[186:189], v[10:13]
	v_mfma_f32_16x16x32_bf16 v[62:65], v[114:117], v[162:165], v[62:65]
	v_mfma_f32_16x16x32_bf16 v[58:61], v[126:129], v[162:165], v[58:61]
	v_mfma_f32_16x16x32_bf16 v[46:49], v[114:117], v[174:177], v[46:49]
	v_mfma_f32_16x16x32_bf16 v[42:45], v[126:129], v[174:177], v[42:45]
	v_mfma_f32_16x16x32_bf16 v[30:33], v[114:117], v[182:185], v[30:33]
	v_mfma_f32_16x16x32_bf16 v[26:29], v[126:129], v[182:185], v[26:29]
	v_mfma_f32_16x16x32_bf16 v[14:17], v[114:117], v[190:193], v[14:17]
	v_mfma_f32_16x16x32_bf16 v[10:13], v[126:129], v[190:193], v[10:13]
	s_setprio 0
	s_setprio 1
	v_mfma_f32_16x16x32_bf16 v[54:57], v[134:137], v[158:161], v[54:57]
	v_mfma_f32_16x16x32_bf16 v[50:53], v[150:153], v[158:161], v[50:53]
	v_mfma_f32_16x16x32_bf16 v[38:41], v[134:137], v[170:173], v[38:41]
	v_mfma_f32_16x16x32_bf16 v[34:37], v[150:153], v[170:173], v[34:37]
	v_mfma_f32_16x16x32_bf16 v[22:25], v[134:137], v[178:181], v[22:25]
	v_mfma_f32_16x16x32_bf16 v[18:21], v[150:153], v[178:181], v[18:21]
	v_mfma_f32_16x16x32_bf16 v[6:9], v[134:137], v[186:189], v[6:9]
	v_mfma_f32_16x16x32_bf16 v[2:5], v[150:153], v[186:189], v[2:5]
	v_mfma_f32_16x16x32_bf16 v[54:57], v[138:141], v[162:165], v[54:57]
	v_mfma_f32_16x16x32_bf16 v[50:53], v[154:157], v[162:165], v[50:53]
	v_mfma_f32_16x16x32_bf16 v[38:41], v[138:141], v[174:177], v[38:41]
	v_mfma_f32_16x16x32_bf16 v[34:37], v[154:157], v[174:177], v[34:37]
	v_mfma_f32_16x16x32_bf16 v[22:25], v[138:141], v[182:185], v[22:25]
	v_mfma_f32_16x16x32_bf16 v[18:21], v[154:157], v[182:185], v[18:21]
	v_mfma_f32_16x16x32_bf16 v[6:9], v[138:141], v[190:193], v[6:9]
	v_mfma_f32_16x16x32_bf16 v[2:5], v[154:157], v[190:193], v[2:5]
	s_setprio 0
	s_barrier
	s_add_i32 s48, s48, 2
	s_add_u32 s18, s18, 0x100
	s_addc_u32 s19, s19, 0
	s_add_u32 s46, s46, 0x100
	s_addc_u32 s47, s47, 0
	s_cmp_gt_u32 s48, 13
	s_cbranch_scc0 .LBB0_879
	v_readfirstlane_b32 s100, v238
	s_nop 3
	s_bfe_u32 s100, s100, 0x40006
	s_cmp_ge_u32 s100, 4
	s_cbranch_scc0 .Lepiprio_8
	s_setprio 1

; #define PG8_STAGE(bufoff, gbase, voff) do { _Pragma("unroll") for (int _i = 0; _i < 2; ++_i) \
;         __builtin_amdgcn_global_load_lds((const unsigned*)((const char*)(gbase) + (voff)[_i]), (PG8_LAS unsigned*)(lds + (bufoff) + ldsw + _i * 8192), 16, 0, 0); } while (0)
; #define PG8_LDA(dst, b, h) do { _Pragma("unroll") for (int m = 0; m < 4; ++m) _Pragma("unroll") for (int k = 0; k < 2; ++k) dst[m][k] = *(const PG8_LAS bf16x8*)(lds + PG8_SA(b, h) + aoff + m * 2048 + k * 1024); } while (0)
; #define PG8_LDB(dst, b, h) do { _Pragma("unroll") for (int n = 0; n < 2; ++n) _Pragma("unroll") for (int k = 0; k < 2; ++k) dst[n][k] = *(const PG8_LAS bf16x8*)(lds + PG8_SB(b, h) + boff + n * 2048 + k * 1024); } while (0)
; #define PG8_MMA(ai, bj, At, Bt) do { __builtin_amdgcn_s_setprio(1); _Pragma("unroll") for (int m = 0; m < 4; ++m) _Pragma("unroll") for (int n = 0; n < 2; ++n) _Pragma("unroll") for (int k = 0; k < 2; ++k) \
;         acc[ai][bj][m][n] = __builtin_amdgcn_mfma_f32_16x16x32_bf16(Bt[n][k], At[m][k], acc[ai][bj][m][n], 0, 0, 0); __builtin_amdgcn_s_setprio(0); } while (0)
; #define PG8_WAIT_V(n) asm volatile("s_waitcnt vmcnt(" #n ")" ::: "memory")
; #define PG8_WAIT_L(n) asm volatile("s_waitcnt lgkmcnt(" #n ")" ::: "memory")
; #define PG8_BAR __builtin_amdgcn_s_barrier()
; #define PG8_SCHED __builtin_amdgcn_sched_barrier(0)
; template <class Epi, class Sched, bool ALIGN_EPI = false, bool SP2 = false>
; __device__ __forceinline__ void gemm_phase(PG8_LAS unsigned char* lds, const Gemm g, const Sched& S, const Epi& E) {
;     ...
;         for (int t = 0; t < nt; t += 2) {
;             const bool last = (t == nt - 2);
;             const char* a1 = cA + (size_t)(t + 1) * kstep;
;             const char* a2 = last ? nA : cA + (size_t)(t + 2) * kstep; const char* b2 = last ? nB : cB + (size_t)(t + 2) * kstep;
;             const char* a3 = a2 + kstep; const char* b3 = b2 + kstep;
;             if (last && has_next) S.a_ready(nxt);
;             if constexpr (SP2) {
;             PG8_LDB(B0, 0, 0); PG8_LDB(B1, 0, 1); PG8_SCHED; PG8_LDA(At, 0, 0); PG8_STAGE(PG8_SA(1, 1), a1 + hstepA, voffA);
;             PG8_WAIT_V(8); PG8_WAIT_L(0); PG8_BAR; PG8_MMA(0, 0, At, B0); PG8_MMA(0, 1, At, B1); PG8_BAR; PG8_SCHED;
;             PG8_LDA(At, 0, 1); PG8_STAGE(PG8_SB(0, 0), b2, voffB); PG8_STAGE(PG8_SB(0, 1), b2 + hstepB, voffB); PG8_STAGE(PG8_SA(0, 0), a2, voffA);
.LBB0_953:
	s_add_u32 s24, s22, 0xfff00080
	s_addc_u32 s25, s23, -1
	s_add_i32 s54, 0, 0x10000
	s_cmp_eq_u32 s53, 12
	s_cselect_b32 s27, s1, s25
	s_cselect_b32 s26, s15, s24
	s_cselect_b32 s25, s13, s52
	s_cselect_b32 s24, s21, s51
	s_add_i32 s56, 0, 0x14000
	v_add_u32_e32 v152, s54, v217
	v_add_u32_e32 v168, s56, v217
	ds_read_b128 v[140:143], v152
	ds_read_b128 v[144:147], v152 offset:1024
	ds_read_b128 v[148:151], v152 offset:2048
	ds_read_b128 v[152:155], v152 offset:3072
	ds_read_b128 v[156:159], v168
	ds_read_b128 v[160:163], v168 offset:1024
	ds_read_b128 v[164:167], v168 offset:2048
	ds_read_b128 v[168:171], v168 offset:3072
	v_lshl_add_u64 v[192:193], s[22:23], 0, v[136:137]
	s_add_i32 m0, s41, 0xc000
	ds_read_b128 v[172:175], v219
	ds_read_b128 v[176:179], v219 offset:1024
	ds_read_b128 v[180:183], v219 offset:2048
	ds_read_b128 v[184:187], v219 offset:3072
	ds_read_b128 v[188:191], v219 offset:4096
	ds_read_b128 v[198:201], v219 offset:5120
	ds_read_b128 v[206:209], v219 offset:6144
	ds_read_b128 v[212:215], v219 offset:7168
	global_load_lds_dwordx4 v[192:193], off
	v_lshl_add_u64 v[192:193], s[22:23], 0, v[138:139]
	s_add_i32 m0, s41, 0xe000
	s_nop 0
	global_load_lds_dwordx4 v[192:193], off
	s_waitcnt vmcnt(8)
	s_waitcnt lgkmcnt(0)
	s_barrier
	s_setprio 1
	s_waitcnt lgkmcnt(0)
	v_mfma_f32_16x16x32_bf16 v[126:129], v[140:143], v[172:175], v[126:129]
	v_mfma_f32_16x16x32_bf16 v[122:125], v[148:151], v[172:175], v[122:125]
	v_mfma_f32_16x16x32_bf16 v[110:113], v[140:143], v[180:183], v[110:113]
	v_mfma_f32_16x16x32_bf16 v[106:109], v[148:151], v[180:183], v[106:109]
	v_mfma_f32_16x16x32_bf16 v[94:97], v[140:143], v[188:191], v[94:97]
	v_mfma_f32_16x16x32_bf16 v[90:93], v[148:151], v[188:191], v[90:93]
	v_mfma_f32_16x16x32_bf16 v[78:81], v[140:143], v[206:209], v[78:81]
	v_mfma_f32_16x16x32_bf16 v[74:77], v[148:151], v[206:209], v[74:77]
	v_mfma_f32_16x16x32_bf16 v[126:129], v[144:147], v[176:179], v[126:129]
	v_mfma_f32_16x16x32_bf16 v[122:125], v[152:155], v[176:179], v[122:125]
	v_mfma_f32_16x16x32_bf16 v[110:113], v[144:147], v[184:187], v[110:113]
	v_mfma_f32_16x16x32_bf16 v[106:109], v[152:155], v[184:187], v[106:109]
	v_mfma_f32_16x16x32_bf16 v[94:97], v[144:147], v[198:201], v[94:97]
	v_mfma_f32_16x16x32_bf16 v[90:93], v[152:155], v[198:201], v[90:93]
	v_mfma_f32_16x16x32_bf16 v[78:81], v[144:147], v[212:215], v[78:81]
	v_mfma_f32_16x16x32_bf16 v[74:77], v[152:155], v[212:215], v[74:77]
	s_setprio 0
	s_setprio 1
	v_mfma_f32_16x16x32_bf16 v[118:121], v[156:159], v[172:175], v[118:121]
	v_mfma_f32_16x16x32_bf16 v[114:117], v[164:167], v[172:175], v[114:117]
	v_mfma_f32_16x16x32_bf16 v[102:105], v[156:159], v[180:183], v[102:105]
	v_mfma_f32_16x16x32_bf16 v[98:101], v[164:167], v[180:183], v[98:101]
	v_mfma_f32_16x16x32_bf16 v[86:89], v[156:159], v[188:191], v[86:89]
	v_mfma_f32_16x16x32_bf16 v[82:85], v[164:167], v[188:191], v[82:85]
	v_mfma_f32_16x16x32_bf16 v[70:73], v[156:159], v[206:209], v[70:73]
	v_mfma_f32_16x16x32_bf16 v[66:69], v[164:167], v[206:209], v[66:69]
	v_mfma_f32_16x16x32_bf16 v[118:121], v[160:163], v[176:179], v[118:121]
	v_mfma_f32_16x16x32_bf16 v[114:117], v[168:171], v[176:179], v[114:117]
	v_mfma_f32_16x16x32_bf16 v[102:105], v[160:163], v[184:187], v[102:105]
	v_mfma_f32_16x16x32_bf16 v[98:101], v[168:171], v[184:187], v[98:101]
	v_mfma_f32_16x16x32_bf16 v[86:89], v[160:163], v[198:201], v[86:89]
	v_mfma_f32_16x16x32_bf16 v[82:85], v[168:171], v[198:201], v[82:85]
	v_mfma_f32_16x16x32_bf16 v[70:73], v[160:163], v[212:215], v[70:73]
	v_mfma_f32_16x16x32_bf16 v[66:69], v[168:171], v[212:215], v[66:69]
	s_setprio 0
	s_barrier
	s_add_i32 s54, s54, s40
	v_lshl_add_u64 v[192:193], s[24:25], 0, v[0:1]
	s_mov_b32 m0, s54
	ds_read_b128 v[172:175], v219 offset:16384
	ds_read_b128 v[176:179], v219 offset:17408
	ds_read_b128 v[180:183], v219 offset:18432
	ds_read_b128 v[184:187], v219 offset:19456
	ds_read_b128 v[188:191], v219 offset:20480
	ds_read_b128 v[198:201], v219 offset:21504
	ds_read_b128 v[206:209], v219 offset:22528
	ds_read_b128 v[212:215], v219 offset:23552
	global_load_lds_dwordx4 v[192:193], off
	s_add_i32 m0, s54, 0x2000
	s_add_u32 s54, s24, 0x40000
	v_lshl_add_u64 v[220:221], s[24:25], 0, v[134:135]
	s_addc_u32 s55, s25, 0
	s_add_i32 s56, s56, s40
	global_load_lds_dwordx4 v[220:221], off
	v_lshl_add_u64 v[222:223], s[54:55], 0, v[0:1]
	s_mov_b32 m0, s56
	v_lshl_add_u64 v[224:225], s[26:27], 0, v[132:133]
	global_load_lds_dwordx4 v[222:223], off
	v_lshl_add_u64 v[222:223], s[54:55], 0, v[134:135]
	s_add_i32 m0, s56, 0x2000
	s_nop 0
	global_load_lds_dwordx4 v[222:223], off
	v_lshl_add_u64 v[222:223], s[26:27], 0, v[130:131]
	s_mov_b32 m0, s41
	s_nop 0
	global_load_lds_dwordx4 v[222:223], off
	s_mov_b32 m0, s42
	s_nop 0
	global_load_lds_dwordx4 v[224:225], off
	s_waitcnt vmcnt(8)
	s_waitcnt lgkmcnt(0)
	s_barrier
; #define PG8_STAGE(bufoff, gbase, voff) do { _Pragma("unroll") for (int _i = 0; _i < 2; ++_i) \
;         __builtin_amdgcn_global_load_lds((const unsigned*)((const char*)(gbase) + (voff)[_i]), (PG8_LAS unsigned*)(lds + (bufoff) + ldsw + _i * 8192), 16, 0, 0); } while (0)
; #define PG8_LDA(dst, b, h) do { _Pragma("unroll") for (int m = 0; m < 4; ++m) _Pragma("unroll") for (int k = 0; k < 2; ++k) dst[m][k] = *(const PG8_LAS bf16x8*)(lds + PG8_SA(b, h) + aoff + m * 2048 + k * 1024); } while (0)
; #define PG8_LDB(dst, b, h) do { _Pragma("unroll") for (int n = 0; n < 2; ++n) _Pragma("unroll") for (int k = 0; k < 2; ++k) dst[n][k] = *(const PG8_LAS bf16x8*)(lds + PG8_SB(b, h) + boff + n * 2048 + k * 1024); } while (0)
; #define PG8_MMA(ai, bj, At, Bt) do { __builtin_amdgcn_s_setprio(1); _Pragma("unroll") for (int m = 0; m < 4; ++m) _Pragma("unroll") for (int n = 0; n < 2; ++n) _Pragma("unroll") for (int k = 0; k < 2; ++k) \
;         acc[ai][bj][m][n] = __builtin_amdgcn_mfma_f32_16x16x32_bf16(Bt[n][k], At[m][k], acc[ai][bj][m][n], 0, 0, 0); __builtin_amdgcn_s_setprio(0); } while (0)
; #define PG8_WAIT_V(n) asm volatile("s_waitcnt vmcnt(" #n ")" ::: "memory")
; #define PG8_WAIT_L(n) asm volatile("s_waitcnt lgkmcnt(" #n ")" ::: "memory")
; #define PG8_BAR __builtin_amdgcn_s_barrier()
; #define PG8_SCHED __builtin_amdgcn_sched_barrier(0)
; template <class Epi, class Sched, bool ALIGN_EPI = false, bool SP2 = false>
; __device__ __forceinline__ void gemm_phase(PG8_LAS unsigned char* lds, const Gemm g, const Sched& S, const Epi& E) {
;     ...
;             PG8_WAIT_V(8); PG8_WAIT_L(0); PG8_BAR; PG8_MMA(1, 0, At, B0); PG8_MMA(1, 1, At, B1); PG8_BAR; PG8_SCHED;
;             PG8_LDB(B0, 1, 0); PG8_LDB(B1, 1, 1); PG8_SCHED; PG8_LDA(At, 1, 0); PG8_STAGE(PG8_SA(0, 1), a2 + hstepA, voffA);
;             PG8_WAIT_V(8); PG8_WAIT_L(0); PG8_BAR; PG8_MMA(0, 0, At, B0); PG8_MMA(0, 1, At, B1); PG8_BAR; PG8_SCHED;
	s_setprio 1
	s_waitcnt lgkmcnt(0)
	v_mfma_f32_16x16x32_bf16 v[62:65], v[140:143], v[172:175], v[62:65]
	v_mfma_f32_16x16x32_bf16 v[58:61], v[148:151], v[172:175], v[58:61]
	v_mfma_f32_16x16x32_bf16 v[46:49], v[140:143], v[180:183], v[46:49]
	v_mfma_f32_16x16x32_bf16 v[42:45], v[148:151], v[180:183], v[42:45]
	v_mfma_f32_16x16x32_bf16 v[30:33], v[140:143], v[188:191], v[30:33]
	v_mfma_f32_16x16x32_bf16 v[26:29], v[148:151], v[188:191], v[26:29]
	v_mfma_f32_16x16x32_bf16 v[14:17], v[140:143], v[206:209], v[14:17]
	v_mfma_f32_16x16x32_bf16 v[10:13], v[148:151], v[206:209], v[10:13]
	v_mfma_f32_16x16x32_bf16 v[62:65], v[144:147], v[176:179], v[62:65]
	v_mfma_f32_16x16x32_bf16 v[58:61], v[152:155], v[176:179], v[58:61]
	v_mfma_f32_16x16x32_bf16 v[46:49], v[144:147], v[184:187], v[46:49]
	v_mfma_f32_16x16x32_bf16 v[42:45], v[152:155], v[184:187], v[42:45]
	v_mfma_f32_16x16x32_bf16 v[30:33], v[144:147], v[198:201], v[30:33]
	v_mfma_f32_16x16x32_bf16 v[26:29], v[152:155], v[198:201], v[26:29]
	v_mfma_f32_16x16x32_bf16 v[14:17], v[144:147], v[212:215], v[14:17]
	v_mfma_f32_16x16x32_bf16 v[10:13], v[152:155], v[212:215], v[10:13]
	s_setprio 0
	s_setprio 1
	v_mfma_f32_16x16x32_bf16 v[54:57], v[156:159], v[172:175], v[54:57]
	v_mfma_f32_16x16x32_bf16 v[50:53], v[164:167], v[172:175], v[50:53]
	v_mfma_f32_16x16x32_bf16 v[38:41], v[156:159], v[180:183], v[38:41]
	v_mfma_f32_16x16x32_bf16 v[34:37], v[164:167], v[180:183], v[34:37]
	v_mfma_f32_16x16x32_bf16 v[22:25], v[156:159], v[188:191], v[22:25]
	v_mfma_f32_16x16x32_bf16 v[18:21], v[164:167], v[188:191], v[18:21]
	v_mfma_f32_16x16x32_bf16 v[6:9], v[156:159], v[206:209], v[6:9]
	v_mfma_f32_16x16x32_bf16 v[2:5], v[164:167], v[206:209], v[2:5]
	v_mfma_f32_16x16x32_bf16 v[54:57], v[160:163], v[176:179], v[54:57]
	v_mfma_f32_16x16x32_bf16 v[50:53], v[168:171], v[176:179], v[50:53]
	v_mfma_f32_16x16x32_bf16 v[38:41], v[160:163], v[184:187], v[38:41]
	v_mfma_f32_16x16x32_bf16 v[34:37], v[168:171], v[184:187], v[34:37]
	v_mfma_f32_16x16x32_bf16 v[22:25], v[160:163], v[198:201], v[22:25]
	v_mfma_f32_16x16x32_bf16 v[18:21], v[168:171], v[198:201], v[18:21]
	v_mfma_f32_16x16x32_bf16 v[6:9], v[160:163], v[212:215], v[6:9]
	v_mfma_f32_16x16x32_bf16 v[2:5], v[168:171], v[212:215], v[2:5]
	s_setprio 0
	s_barrier
	s_add_i32 s54, 0, 0x18000
	s_add_i32 s55, 0, 0x1c000
	v_add_u32_e32 v152, s54, v217
	v_add_u32_e32 v168, s55, v217
	ds_read_b128 v[140:143], v152
	ds_read_b128 v[144:147], v152 offset:1024
	ds_read_b128 v[148:151], v152 offset:2048
	ds_read_b128 v[152:155], v152 offset:3072
	ds_read_b128 v[156:159], v168
	ds_read_b128 v[160:163], v168 offset:1024
	ds_read_b128 v[164:167], v168 offset:2048
	ds_read_b128 v[168:171], v168 offset:3072
	s_add_u32 s26, s26, 0x100000
	s_addc_u32 s27, s27, 0
	s_mov_b32 m0, s43
	v_lshl_add_u64 v[226:227], s[26:27], 0, v[130:131]
	ds_read_b128 v[172:175], v219 offset:32768
	ds_read_b128 v[176:179], v219 offset:33792
	ds_read_b128 v[180:183], v219 offset:34816
	ds_read_b128 v[184:187], v219 offset:35840
	ds_read_b128 v[188:191], v219 offset:36864
	ds_read_b128 v[198:201], v219 offset:37888
	ds_read_b128 v[206:209], v219 offset:38912
	ds_read_b128 v[212:215], v219 offset:39936
	global_load_lds_dwordx4 v[226:227], off
	v_lshl_add_u64 v[226:227], s[26:27], 0, v[132:133]
	s_mov_b32 m0, s44
	s_nop 0
	global_load_lds_dwordx4 v[226:227], off
	s_waitcnt vmcnt(8)
	s_waitcnt lgkmcnt(0)
	s_barrier
	s_setprio 1
	s_waitcnt lgkmcnt(0)
	v_mfma_f32_16x16x32_bf16 v[126:129], v[140:143], v[172:175], v[126:129]
	v_mfma_f32_16x16x32_bf16 v[122:125], v[148:151], v[172:175], v[122:125]
	v_mfma_f32_16x16x32_bf16 v[110:113], v[140:143], v[180:183], v[110:113]
	v_mfma_f32_16x16x32_bf16 v[106:109], v[148:151], v[180:183], v[106:109]
	v_mfma_f32_16x16x32_bf16 v[94:97], v[140:143], v[188:191], v[94:97]
	v_mfma_f32_16x16x32_bf16 v[90:93], v[148:151], v[188:191], v[90:93]
	v_mfma_f32_16x16x32_bf16 v[78:81], v[140:143], v[206:209], v[78:81]
	v_mfma_f32_16x16x32_bf16 v[74:77], v[148:151], v[206:209], v[74:77]
	v_mfma_f32_16x16x32_bf16 v[126:129], v[144:147], v[176:179], v[126:129]
	v_mfma_f32_16x16x32_bf16 v[122:125], v[152:155], v[176:179], v[122:125]
	v_mfma_f32_16x16x32_bf16 v[110:113], v[144:147], v[184:187], v[110:113]
	v_mfma_f32_16x16x32_bf16 v[106:109], v[152:155], v[184:187], v[106:109]
	v_mfma_f32_16x16x32_bf16 v[94:97], v[144:147], v[198:201], v[94:97]
	v_mfma_f32_16x16x32_bf16 v[90:93], v[152:155], v[198:201], v[90:93]
	v_mfma_f32_16x16x32_bf16 v[78:81], v[144:147], v[212:215], v[78:81]
	v_mfma_f32_16x16x32_bf16 v[74:77], v[152:155], v[212:215], v[74:77]
	s_setprio 0
	s_setprio 1
	v_mfma_f32_16x16x32_bf16 v[118:121], v[156:159], v[172:175], v[118:121]
	v_mfma_f32_16x16x32_bf16 v[114:117], v[164:167], v[172:175], v[114:117]
	v_mfma_f32_16x16x32_bf16 v[102:105], v[156:159], v[180:183], v[102:105]
	v_mfma_f32_16x16x32_bf16 v[98:101], v[164:167], v[180:183], v[98:101]
	v_mfma_f32_16x16x32_bf16 v[86:89], v[156:159], v[188:191], v[86:89]
	v_mfma_f32_16x16x32_bf16 v[82:85], v[164:167], v[188:191], v[82:85]
	v_mfma_f32_16x16x32_bf16 v[70:73], v[156:159], v[206:209], v[70:73]
	v_mfma_f32_16x16x32_bf16 v[66:69], v[164:167], v[206:209], v[66:69]
	v_mfma_f32_16x16x32_bf16 v[118:121], v[160:163], v[176:179], v[118:121]
	v_mfma_f32_16x16x32_bf16 v[114:117], v[168:171], v[176:179], v[114:117]
	v_mfma_f32_16x16x32_bf16 v[102:105], v[160:163], v[184:187], v[102:105]
	v_mfma_f32_16x16x32_bf16 v[98:101], v[168:171], v[184:187], v[98:101]
	v_mfma_f32_16x16x32_bf16 v[86:89], v[160:163], v[198:201], v[86:89]
	v_mfma_f32_16x16x32_bf16 v[82:85], v[168:171], v[198:201], v[82:85]
	v_mfma_f32_16x16x32_bf16 v[70:73], v[160:163], v[212:215], v[70:73]
	v_mfma_f32_16x16x32_bf16 v[66:69], v[168:171], v[212:215], v[66:69]
	s_setprio 0
	s_barrier
; #define PG8_STAGE(bufoff, gbase, voff) do { _Pragma("unroll") for (int _i = 0; _i < 2; ++_i) \
;         __builtin_amdgcn_global_load_lds((const unsigned*)((const char*)(gbase) + (voff)[_i]), (PG8_LAS unsigned*)(lds + (bufoff) + ldsw + _i * 8192), 16, 0, 0); } while (0)
; #define PG8_LDA(dst, b, h) do { _Pragma("unroll") for (int m = 0; m < 4; ++m) _Pragma("unroll") for (int k = 0; k < 2; ++k) dst[m][k] = *(const PG8_LAS bf16x8*)(lds + PG8_SA(b, h) + aoff + m * 2048 + k * 1024); } while (0)
; #define PG8_MMA(ai, bj, At, Bt) do { __builtin_amdgcn_s_setprio(1); _Pragma("unroll") for (int m = 0; m < 4; ++m) _Pragma("unroll") for (int n = 0; n < 2; ++n) _Pragma("unroll") for (int k = 0; k < 2; ++k) \
;         acc[ai][bj][m][n] = __builtin_amdgcn_mfma_f32_16x16x32_bf16(Bt[n][k], At[m][k], acc[ai][bj][m][n], 0, 0, 0); __builtin_amdgcn_s_setprio(0); } while (0)
; #define PG8_WAIT_V(n) asm volatile("s_waitcnt vmcnt(" #n ")" ::: "memory")
; #define PG8_WAIT_L(n) asm volatile("s_waitcnt lgkmcnt(" #n ")" ::: "memory")
; #define PG8_BAR __builtin_amdgcn_s_barrier()
; #define PG8_SCHED __builtin_amdgcn_sched_barrier(0)
; template <class Epi, class Sched, bool ALIGN_EPI = false, bool SP2 = false>
; __device__ __forceinline__ void gemm_phase(PG8_LAS unsigned char* lds, const Gemm g, const Sched& S, const Epi& E) {
;     ...
;             PG8_LDA(At, 1, 1); PG8_STAGE(PG8_SB(1, 0), b3, voffB); PG8_STAGE(PG8_SB(1, 1), b3 + hstepB, voffB); PG8_STAGE(PG8_SA(1, 0), a3, voffA);
;             PG8_WAIT_V(8); PG8_WAIT_L(0); PG8_BAR; PG8_MMA(1, 0, At, B0); PG8_MMA(1, 1, At, B1); PG8_BAR; PG8_SCHED;
;     ...
;         if constexpr (ALIGN_EPI) { if (wr == 0) PG8_BAR; }
	s_add_i32 s26, s54, s40
	v_lshl_add_u64 v[192:193], v[192:193], 0, s[88:89]
	s_mov_b32 m0, s26
	ds_read_b128 v[172:175], v219 offset:49152
	ds_read_b128 v[176:179], v219 offset:50176
	ds_read_b128 v[180:183], v219 offset:51200
	ds_read_b128 v[184:187], v219 offset:52224
	ds_read_b128 v[188:191], v219 offset:53248
	ds_read_b128 v[198:201], v219 offset:54272
	ds_read_b128 v[206:209], v219 offset:55296
	ds_read_b128 v[212:215], v219 offset:56320
	global_load_lds_dwordx4 v[192:193], off
	s_add_i32 m0, s26, 0x2000
	s_add_u32 s24, s24, 0x40080
	v_lshl_add_u64 v[192:193], v[220:221], 0, s[88:89]
	s_addc_u32 s25, s25, 0
	s_add_i32 s26, s55, s40
	global_load_lds_dwordx4 v[192:193], off
	v_lshl_add_u64 v[192:193], s[24:25], 0, v[0:1]
	s_mov_b32 m0, s26
	s_nop 0
	global_load_lds_dwordx4 v[192:193], off
	v_lshl_add_u64 v[192:193], s[24:25], 0, v[134:135]
	s_add_i32 m0, s26, 0x2000
	s_nop 0
	global_load_lds_dwordx4 v[192:193], off
	v_lshl_add_u64 v[192:193], v[222:223], 0, s[88:89]
	s_mov_b32 m0, s46
	s_nop 0
	global_load_lds_dwordx4 v[192:193], off
	v_lshl_add_u64 v[192:193], v[224:225], 0, s[88:89]
	s_mov_b32 m0, s47
	s_nop 0
	global_load_lds_dwordx4 v[192:193], off
	s_waitcnt vmcnt(8)
	s_waitcnt lgkmcnt(0)
	s_barrier
	s_setprio 1
	s_waitcnt lgkmcnt(0)
	v_mfma_f32_16x16x32_bf16 v[62:65], v[140:143], v[172:175], v[62:65]
	v_mfma_f32_16x16x32_bf16 v[58:61], v[148:151], v[172:175], v[58:61]
	v_mfma_f32_16x16x32_bf16 v[46:49], v[140:143], v[180:183], v[46:49]
	v_mfma_f32_16x16x32_bf16 v[42:45], v[148:151], v[180:183], v[42:45]
	v_mfma_f32_16x16x32_bf16 v[30:33], v[140:143], v[188:191], v[30:33]
	v_mfma_f32_16x16x32_bf16 v[26:29], v[148:151], v[188:191], v[26:29]
	v_mfma_f32_16x16x32_bf16 v[14:17], v[140:143], v[206:209], v[14:17]
	v_mfma_f32_16x16x32_bf16 v[10:13], v[148:151], v[206:209], v[10:13]
	v_mfma_f32_16x16x32_bf16 v[62:65], v[144:147], v[176:179], v[62:65]
	v_mfma_f32_16x16x32_bf16 v[58:61], v[152:155], v[176:179], v[58:61]
	v_mfma_f32_16x16x32_bf16 v[46:49], v[144:147], v[184:187], v[46:49]
	v_mfma_f32_16x16x32_bf16 v[42:45], v[152:155], v[184:187], v[42:45]
	v_mfma_f32_16x16x32_bf16 v[30:33], v[144:147], v[198:201], v[30:33]
	v_mfma_f32_16x16x32_bf16 v[26:29], v[152:155], v[198:201], v[26:29]
	v_mfma_f32_16x16x32_bf16 v[14:17], v[144:147], v[212:215], v[14:17]
	v_mfma_f32_16x16x32_bf16 v[10:13], v[152:155], v[212:215], v[10:13]
	s_setprio 0
	s_setprio 1
	v_mfma_f32_16x16x32_bf16 v[54:57], v[156:159], v[172:175], v[54:57]
	v_mfma_f32_16x16x32_bf16 v[50:53], v[164:167], v[172:175], v[50:53]
	v_mfma_f32_16x16x32_bf16 v[38:41], v[156:159], v[180:183], v[38:41]
	v_mfma_f32_16x16x32_bf16 v[34:37], v[164:167], v[180:183], v[34:37]
	v_mfma_f32_16x16x32_bf16 v[22:25], v[156:159], v[188:191], v[22:25]
	v_mfma_f32_16x16x32_bf16 v[18:21], v[164:167], v[188:191], v[18:21]
	v_mfma_f32_16x16x32_bf16 v[6:9], v[156:159], v[206:209], v[6:9]
	v_mfma_f32_16x16x32_bf16 v[2:5], v[164:167], v[206:209], v[2:5]
	v_mfma_f32_16x16x32_bf16 v[54:57], v[160:163], v[176:179], v[54:57]
	v_mfma_f32_16x16x32_bf16 v[50:53], v[168:171], v[176:179], v[50:53]
	v_mfma_f32_16x16x32_bf16 v[38:41], v[160:163], v[184:187], v[38:41]
	v_mfma_f32_16x16x32_bf16 v[34:37], v[168:171], v[184:187], v[34:37]
	v_mfma_f32_16x16x32_bf16 v[22:25], v[160:163], v[198:201], v[22:25]
	v_mfma_f32_16x16x32_bf16 v[18:21], v[168:171], v[198:201], v[18:21]
	v_mfma_f32_16x16x32_bf16 v[6:9], v[160:163], v[212:215], v[6:9]
	v_mfma_f32_16x16x32_bf16 v[2:5], v[168:171], v[212:215], v[2:5]
	s_setprio 0
	s_barrier
	s_add_i32 s53, s53, 2
	s_add_u32 s22, s22, 0x100
	s_addc_u32 s23, s23, 0
	s_add_u32 s51, s51, 0x100
	s_addc_u32 s52, s52, 0
	s_cmp_gt_u32 s53, 13
	s_cbranch_scc0 .LBB0_953
	v_readfirstlane_b32 s100, v238
	s_nop 3
	s_bfe_u32 s100, s100, 0x40006
	s_cmp_ge_u32 s100, 4
	s_cbranch_scc0 .Lepiprio_9
	s_setprio 1
.Lepiprio_9:
	s_and_b64 vcc, exec, s[10:11]
	s_cbranch_vccz .LBB0_956
	s_barrier

; #define PG8_STAGE(bufoff, gbase, voff) do { _Pragma("unroll") for (int _i = 0; _i < 2; ++_i) \
;         __builtin_amdgcn_global_load_lds((const unsigned*)((const char*)(gbase) + (voff)[_i]), (PG8_LAS unsigned*)(lds + (bufoff) + ldsw + _i * 8192), 16, 0, 0); } while (0)
; #define PG8_LDA(dst, b, h) do { _Pragma("unroll") for (int m = 0; m < 4; ++m) _Pragma("unroll") for (int k = 0; k < 2; ++k) dst[m][k] = *(const PG8_LAS bf16x8*)(lds + PG8_SA(b, h) + aoff + m * 2048 + k * 1024); } while (0)
; #define PG8_LDB(dst, b, h) do { _Pragma("unroll") for (int n = 0; n < 2; ++n) _Pragma("unroll") for (int k = 0; k < 2; ++k) dst[n][k] = *(const PG8_LAS bf16x8*)(lds + PG8_SB(b, h) + boff + n * 2048 + k * 1024); } while (0)
; #define PG8_MMA(ai, bj, At, Bt) do { __builtin_amdgcn_s_setprio(1); _Pragma("unroll") for (int m = 0; m < 4; ++m) _Pragma("unroll") for (int n = 0; n < 2; ++n) _Pragma("unroll") for (int k = 0; k < 2; ++k) \
;         acc[ai][bj][m][n] = __builtin_amdgcn_mfma_f32_16x16x32_bf16(Bt[n][k], At[m][k], acc[ai][bj][m][n], 0, 0, 0); __builtin_amdgcn_s_setprio(0); } while (0)
; #define PG8_WAIT_V(n) asm volatile("s_waitcnt vmcnt(" #n ")" ::: "memory")
; #define PG8_WAIT_L(n) asm volatile("s_waitcnt lgkmcnt(" #n ")" ::: "memory")
; #define PG8_BAR __builtin_amdgcn_s_barrier()
; #define PG8_SCHED __builtin_amdgcn_sched_barrier(0)
; template <class Epi, class Sched, bool ALIGN_EPI = false, bool SP2 = false>
; __device__ __forceinline__ void gemm_phase(PG8_LAS unsigned char* lds, const Gemm g, const Sched& S, const Epi& E) {
;     ...
;         for (int t = 0; t < nt; t += 2) {
;             const bool last = (t == nt - 2);
;             const char* a1 = cA + (size_t)(t + 1) * kstep;
;             const char* a2 = last ? nA : cA + (size_t)(t + 2) * kstep; const char* b2 = last ? nB : cB + (size_t)(t + 2) * kstep;
;             const char* a3 = a2 + kstep; const char* b3 = b2 + kstep;
;             if (last && has_next) S.a_ready(nxt);
;             if constexpr (SP2) {
;             PG8_LDB(B0, 0, 0); PG8_LDB(B1, 0, 1); PG8_SCHED; PG8_LDA(At, 0, 0); PG8_STAGE(PG8_SA(1, 1), a1 + hstepA, voffA);
;             PG8_WAIT_V(8); PG8_WAIT_L(0); PG8_BAR; PG8_MMA(0, 0, At, B0); PG8_MMA(0, 1, At, B1); PG8_BAR; PG8_SCHED;
;             PG8_LDA(At, 0, 1); PG8_STAGE(PG8_SB(0, 0), b2, voffB); PG8_STAGE(PG8_SB(0, 1), b2 + hstepB, voffB); PG8_STAGE(PG8_SA(0, 0), a2, voffA);
.LBB0_1170:
	s_add_u32 s24, s22, 0xfffc0080
	s_addc_u32 s25, s23, -1
	s_add_i32 s54, 0, 0x10000
	s_cmp_eq_u32 s53, 12
	s_cselect_b32 s27, s1, s25
	s_cselect_b32 s26, s15, s24
	s_cselect_b32 s25, s13, s52
	s_cselect_b32 s24, s21, s51
	s_add_i32 s56, 0, 0x14000
	v_add_u32_e32 v148, s54, v213
	v_add_u32_e32 v164, s56, v213
	ds_read_b128 v[136:139], v148
	ds_read_b128 v[140:143], v148 offset:1024
	ds_read_b128 v[144:147], v148 offset:2048
	ds_read_b128 v[148:151], v148 offset:3072
	ds_read_b128 v[152:155], v164
	ds_read_b128 v[156:159], v164 offset:1024
	ds_read_b128 v[160:163], v164 offset:2048
	ds_read_b128 v[164:167], v164 offset:3072
	v_lshl_add_u64 v[192:193], s[22:23], 0, v[132:133]
	s_add_i32 m0, s41, 0xc000
	ds_read_b128 v[168:171], v215
	ds_read_b128 v[172:175], v215 offset:1024
	ds_read_b128 v[176:179], v215 offset:2048
	ds_read_b128 v[180:183], v215 offset:3072
	ds_read_b128 v[184:187], v215 offset:4096
	ds_read_b128 v[188:191], v215 offset:5120
	ds_read_b128 v[198:201], v215 offset:6144
	ds_read_b128 v[206:209], v215 offset:7168
	global_load_lds_dwordx4 v[192:193], off
	v_lshl_add_u64 v[192:193], s[22:23], 0, v[134:135]
	s_add_i32 m0, s41, 0xe000
	s_nop 0
	global_load_lds_dwordx4 v[192:193], off
	s_waitcnt vmcnt(8)
	s_waitcnt lgkmcnt(0)
	s_barrier
	s_setprio 1
	s_waitcnt lgkmcnt(0)
	v_mfma_f32_16x16x32_bf16 v[126:129], v[136:139], v[168:171], v[126:129]
	v_mfma_f32_16x16x32_bf16 v[122:125], v[144:147], v[168:171], v[122:125]
	v_mfma_f32_16x16x32_bf16 v[110:113], v[136:139], v[176:179], v[110:113]
	v_mfma_f32_16x16x32_bf16 v[106:109], v[144:147], v[176:179], v[106:109]
	v_mfma_f32_16x16x32_bf16 v[94:97], v[136:139], v[184:187], v[94:97]
	v_mfma_f32_16x16x32_bf16 v[90:93], v[144:147], v[184:187], v[90:93]
	v_mfma_f32_16x16x32_bf16 v[78:81], v[136:139], v[198:201], v[78:81]
	v_mfma_f32_16x16x32_bf16 v[74:77], v[144:147], v[198:201], v[74:77]
	v_mfma_f32_16x16x32_bf16 v[126:129], v[140:143], v[172:175], v[126:129]
	v_mfma_f32_16x16x32_bf16 v[122:125], v[148:151], v[172:175], v[122:125]
	v_mfma_f32_16x16x32_bf16 v[110:113], v[140:143], v[180:183], v[110:113]
	v_mfma_f32_16x16x32_bf16 v[106:109], v[148:151], v[180:183], v[106:109]
	v_mfma_f32_16x16x32_bf16 v[94:97], v[140:143], v[188:191], v[94:97]
	v_mfma_f32_16x16x32_bf16 v[90:93], v[148:151], v[188:191], v[90:93]
	v_mfma_f32_16x16x32_bf16 v[78:81], v[140:143], v[206:209], v[78:81]
	v_mfma_f32_16x16x32_bf16 v[74:77], v[148:151], v[206:209], v[74:77]
	s_setprio 0
	s_setprio 1
	v_mfma_f32_16x16x32_bf16 v[118:121], v[152:155], v[168:171], v[118:121]
	v_mfma_f32_16x16x32_bf16 v[114:117], v[160:163], v[168:171], v[114:117]
	v_mfma_f32_16x16x32_bf16 v[102:105], v[152:155], v[176:179], v[102:105]
	v_mfma_f32_16x16x32_bf16 v[98:101], v[160:163], v[176:179], v[98:101]
	v_mfma_f32_16x16x32_bf16 v[86:89], v[152:155], v[184:187], v[86:89]
	v_mfma_f32_16x16x32_bf16 v[82:85], v[160:163], v[184:187], v[82:85]
	v_mfma_f32_16x16x32_bf16 v[70:73], v[152:155], v[198:201], v[70:73]
	v_mfma_f32_16x16x32_bf16 v[66:69], v[160:163], v[198:201], v[66:69]
	v_mfma_f32_16x16x32_bf16 v[118:121], v[156:159], v[172:175], v[118:121]
	v_mfma_f32_16x16x32_bf16 v[114:117], v[164:167], v[172:175], v[114:117]
	v_mfma_f32_16x16x32_bf16 v[102:105], v[156:159], v[180:183], v[102:105]
	v_mfma_f32_16x16x32_bf16 v[98:101], v[164:167], v[180:183], v[98:101]
	v_mfma_f32_16x16x32_bf16 v[86:89], v[156:159], v[188:191], v[86:89]
	v_mfma_f32_16x16x32_bf16 v[82:85], v[164:167], v[188:191], v[82:85]
	v_mfma_f32_16x16x32_bf16 v[70:73], v[156:159], v[206:209], v[70:73]
	v_mfma_f32_16x16x32_bf16 v[66:69], v[164:167], v[206:209], v[66:69]
	s_setprio 0
	s_barrier
	s_add_i32 s54, s54, s40
	v_lshl_add_u64 v[192:193], s[24:25], 0, v[0:1]
	s_mov_b32 m0, s54
	ds_read_b128 v[168:171], v215 offset:16384
	ds_read_b128 v[172:175], v215 offset:17408
	ds_read_b128 v[176:179], v215 offset:18432
	ds_read_b128 v[180:183], v215 offset:19456
	ds_read_b128 v[184:187], v215 offset:20480
	ds_read_b128 v[188:191], v215 offset:21504
	ds_read_b128 v[198:201], v215 offset:22528
	ds_read_b128 v[206:209], v215 offset:23552
	global_load_lds_dwordx4 v[192:193], off
	s_add_i32 m0, s54, 0x2000
	s_add_u32 s54, s24, 0x40000
	v_lshl_add_u64 v[216:217], s[24:25], 0, v[130:131]
	s_addc_u32 s55, s25, 0
	s_add_i32 s56, s56, s40
	global_load_lds_dwordx4 v[216:217], off
	v_lshl_add_u64 v[218:219], s[54:55], 0, v[0:1]
	s_mov_b32 m0, s56
	v_lshl_add_u64 v[220:221], s[26:27], 0, v[130:131]
	global_load_lds_dwordx4 v[218:219], off
	v_lshl_add_u64 v[218:219], s[54:55], 0, v[130:131]
	s_add_i32 m0, s56, 0x2000
	s_nop 0
	global_load_lds_dwordx4 v[218:219], off
	v_lshl_add_u64 v[218:219], s[26:27], 0, v[0:1]
	s_mov_b32 m0, s41
	s_nop 0
	global_load_lds_dwordx4 v[218:219], off
	s_mov_b32 m0, s42
	s_nop 0
	global_load_lds_dwordx4 v[220:221], off
	s_waitcnt vmcnt(8)
	s_waitcnt lgkmcnt(0)
	s_barrier
; #define PG8_STAGE(bufoff, gbase, voff) do { _Pragma("unroll") for (int _i = 0; _i < 2; ++_i) \
;         __builtin_amdgcn_global_load_lds((const unsigned*)((const char*)(gbase) + (voff)[_i]), (PG8_LAS unsigned*)(lds + (bufoff) + ldsw + _i * 8192), 16, 0, 0); } while (0)
; #define PG8_LDA(dst, b, h) do { _Pragma("unroll") for (int m = 0; m < 4; ++m) _Pragma("unroll") for (int k = 0; k < 2; ++k) dst[m][k] = *(const PG8_LAS bf16x8*)(lds + PG8_SA(b, h) + aoff + m * 2048 + k * 1024); } while (0)
; #define PG8_LDB(dst, b, h) do { _Pragma("unroll") for (int n = 0; n < 2; ++n) _Pragma("unroll") for (int k = 0; k < 2; ++k) dst[n][k] = *(const PG8_LAS bf16x8*)(lds + PG8_SB(b, h) + boff + n * 2048 + k * 1024); } while (0)
; #define PG8_MMA(ai, bj, At, Bt) do { __builtin_amdgcn_s_setprio(1); _Pragma("unroll") for (int m = 0; m < 4; ++m) _Pragma("unroll") for (int n = 0; n < 2; ++n) _Pragma("unroll") for (int k = 0; k < 2; ++k) \
;         acc[ai][bj][m][n] = __builtin_amdgcn_mfma_f32_16x16x32_bf16(Bt[n][k], At[m][k], acc[ai][bj][m][n], 0, 0, 0); __builtin_amdgcn_s_setprio(0); } while (0)
; #define PG8_WAIT_V(n) asm volatile("s_waitcnt vmcnt(" #n ")" ::: "memory")
; #define PG8_WAIT_L(n) asm volatile("s_waitcnt lgkmcnt(" #n ")" ::: "memory")
; #define PG8_BAR __builtin_amdgcn_s_barrier()
; #define PG8_SCHED __builtin_amdgcn_sched_barrier(0)
; template <class Epi, class Sched, bool ALIGN_EPI = false, bool SP2 = false>
; __device__ __forceinline__ void gemm_phase(PG8_LAS unsigned char* lds, const Gemm g, const Sched& S, const Epi& E) {
;     ...
;             PG8_WAIT_V(8); PG8_WAIT_L(0); PG8_BAR; PG8_MMA(1, 0, At, B0); PG8_MMA(1, 1, At, B1); PG8_BAR; PG8_SCHED;
;             PG8_LDB(B0, 1, 0); PG8_LDB(B1, 1, 1); PG8_SCHED; PG8_LDA(At, 1, 0); PG8_STAGE(PG8_SA(0, 1), a2 + hstepA, voffA);
;             PG8_WAIT_V(8); PG8_WAIT_L(0); PG8_BAR; PG8_MMA(0, 0, At, B0); PG8_MMA(0, 1, At, B1); PG8_BAR; PG8_SCHED;
	s_setprio 1
	s_waitcnt lgkmcnt(0)
	v_mfma_f32_16x16x32_bf16 v[62:65], v[136:139], v[168:171], v[62:65]
	v_mfma_f32_16x16x32_bf16 v[58:61], v[144:147], v[168:171], v[58:61]
	v_mfma_f32_16x16x32_bf16 v[46:49], v[136:139], v[176:179], v[46:49]
	v_mfma_f32_16x16x32_bf16 v[42:45], v[144:147], v[176:179], v[42:45]
	v_mfma_f32_16x16x32_bf16 v[30:33], v[136:139], v[184:187], v[30:33]
	v_mfma_f32_16x16x32_bf16 v[26:29], v[144:147], v[184:187], v[26:29]
	v_mfma_f32_16x16x32_bf16 v[14:17], v[136:139], v[198:201], v[14:17]
	v_mfma_f32_16x16x32_bf16 v[10:13], v[144:147], v[198:201], v[10:13]
	v_mfma_f32_16x16x32_bf16 v[62:65], v[140:143], v[172:175], v[62:65]
	v_mfma_f32_16x16x32_bf16 v[58:61], v[148:151], v[172:175], v[58:61]
	v_mfma_f32_16x16x32_bf16 v[46:49], v[140:143], v[180:183], v[46:49]
	v_mfma_f32_16x16x32_bf16 v[42:45], v[148:151], v[180:183], v[42:45]
	v_mfma_f32_16x16x32_bf16 v[30:33], v[140:143], v[188:191], v[30:33]
	v_mfma_f32_16x16x32_bf16 v[26:29], v[148:151], v[188:191], v[26:29]
	v_mfma_f32_16x16x32_bf16 v[14:17], v[140:143], v[206:209], v[14:17]
	v_mfma_f32_16x16x32_bf16 v[10:13], v[148:151], v[206:209], v[10:13]
	s_setprio 0
	s_setprio 1
	v_mfma_f32_16x16x32_bf16 v[54:57], v[152:155], v[168:171], v[54:57]
	v_mfma_f32_16x16x32_bf16 v[50:53], v[160:163], v[168:171], v[50:53]
	v_mfma_f32_16x16x32_bf16 v[38:41], v[152:155], v[176:179], v[38:41]
	v_mfma_f32_16x16x32_bf16 v[34:37], v[160:163], v[176:179], v[34:37]
	v_mfma_f32_16x16x32_bf16 v[22:25], v[152:155], v[184:187], v[22:25]
	v_mfma_f32_16x16x32_bf16 v[18:21], v[160:163], v[184:187], v[18:21]
	v_mfma_f32_16x16x32_bf16 v[6:9], v[152:155], v[198:201], v[6:9]
	v_mfma_f32_16x16x32_bf16 v[2:5], v[160:163], v[198:201], v[2:5]
	v_mfma_f32_16x16x32_bf16 v[54:57], v[156:159], v[172:175], v[54:57]
	v_mfma_f32_16x16x32_bf16 v[50:53], v[164:167], v[172:175], v[50:53]
	v_mfma_f32_16x16x32_bf16 v[38:41], v[156:159], v[180:183], v[38:41]
	v_mfma_f32_16x16x32_bf16 v[34:37], v[164:167], v[180:183], v[34:37]
	v_mfma_f32_16x16x32_bf16 v[22:25], v[156:159], v[188:191], v[22:25]
	v_mfma_f32_16x16x32_bf16 v[18:21], v[164:167], v[188:191], v[18:21]
	v_mfma_f32_16x16x32_bf16 v[6:9], v[156:159], v[206:209], v[6:9]
	v_mfma_f32_16x16x32_bf16 v[2:5], v[164:167], v[206:209], v[2:5]
	s_setprio 0
	s_barrier
	s_add_i32 s54, 0, 0x18000
	s_add_i32 s55, 0, 0x1c000
	v_add_u32_e32 v148, s54, v213
	v_add_u32_e32 v164, s55, v213
	ds_read_b128 v[136:139], v148
	ds_read_b128 v[140:143], v148 offset:1024
	ds_read_b128 v[144:147], v148 offset:2048
	ds_read_b128 v[148:151], v148 offset:3072
	ds_read_b128 v[152:155], v164
	ds_read_b128 v[156:159], v164 offset:1024
	ds_read_b128 v[160:163], v164 offset:2048
	ds_read_b128 v[164:167], v164 offset:3072
	s_add_u32 s26, s26, 0x40000
	s_addc_u32 s27, s27, 0
	s_mov_b32 m0, s43
	v_lshl_add_u64 v[222:223], s[26:27], 0, v[0:1]
	ds_read_b128 v[168:171], v215 offset:32768
	ds_read_b128 v[172:175], v215 offset:33792
	ds_read_b128 v[176:179], v215 offset:34816
	ds_read_b128 v[180:183], v215 offset:35840
	ds_read_b128 v[184:187], v215 offset:36864
	ds_read_b128 v[188:191], v215 offset:37888
	ds_read_b128 v[198:201], v215 offset:38912
	ds_read_b128 v[206:209], v215 offset:39936
	global_load_lds_dwordx4 v[222:223], off
	v_lshl_add_u64 v[222:223], s[26:27], 0, v[130:131]
	s_mov_b32 m0, s44
	s_nop 0
	global_load_lds_dwordx4 v[222:223], off
	s_waitcnt vmcnt(8)
	s_waitcnt lgkmcnt(0)
	s_barrier
	s_setprio 1
	s_waitcnt lgkmcnt(0)
	v_mfma_f32_16x16x32_bf16 v[126:129], v[136:139], v[168:171], v[126:129]
	v_mfma_f32_16x16x32_bf16 v[122:125], v[144:147], v[168:171], v[122:125]
	v_mfma_f32_16x16x32_bf16 v[110:113], v[136:139], v[176:179], v[110:113]
	v_mfma_f32_16x16x32_bf16 v[106:109], v[144:147], v[176:179], v[106:109]
	v_mfma_f32_16x16x32_bf16 v[94:97], v[136:139], v[184:187], v[94:97]
	v_mfma_f32_16x16x32_bf16 v[90:93], v[144:147], v[184:187], v[90:93]
	v_mfma_f32_16x16x32_bf16 v[78:81], v[136:139], v[198:201], v[78:81]
	v_mfma_f32_16x16x32_bf16 v[74:77], v[144:147], v[198:201], v[74:77]
	v_mfma_f32_16x16x32_bf16 v[126:129], v[140:143], v[172:175], v[126:129]
	v_mfma_f32_16x16x32_bf16 v[122:125], v[148:151], v[172:175], v[122:125]
	v_mfma_f32_16x16x32_bf16 v[110:113], v[140:143], v[180:183], v[110:113]
	v_mfma_f32_16x16x32_bf16 v[106:109], v[148:151], v[180:183], v[106:109]
	v_mfma_f32_16x16x32_bf16 v[94:97], v[140:143], v[188:191], v[94:97]
	v_mfma_f32_16x16x32_bf16 v[90:93], v[148:151], v[188:191], v[90:93]
	v_mfma_f32_16x16x32_bf16 v[78:81], v[140:143], v[206:209], v[78:81]
	v_mfma_f32_16x16x32_bf16 v[74:77], v[148:151], v[206:209], v[74:77]
	s_setprio 0
	s_setprio 1
	v_mfma_f32_16x16x32_bf16 v[118:121], v[152:155], v[168:171], v[118:121]
	v_mfma_f32_16x16x32_bf16 v[114:117], v[160:163], v[168:171], v[114:117]
	v_mfma_f32_16x16x32_bf16 v[102:105], v[152:155], v[176:179], v[102:105]
	v_mfma_f32_16x16x32_bf16 v[98:101], v[160:163], v[176:179], v[98:101]
	v_mfma_f32_16x16x32_bf16 v[86:89], v[152:155], v[184:187], v[86:89]
	v_mfma_f32_16x16x32_bf16 v[82:85], v[160:163], v[184:187], v[82:85]
	v_mfma_f32_16x16x32_bf16 v[70:73], v[152:155], v[198:201], v[70:73]
	v_mfma_f32_16x16x32_bf16 v[66:69], v[160:163], v[198:201], v[66:69]
	v_mfma_f32_16x16x32_bf16 v[118:121], v[156:159], v[172:175], v[118:121]
	v_mfma_f32_16x16x32_bf16 v[114:117], v[164:167], v[172:175], v[114:117]
	v_mfma_f32_16x16x32_bf16 v[102:105], v[156:159], v[180:183], v[102:105]
	v_mfma_f32_16x16x32_bf16 v[98:101], v[164:167], v[180:183], v[98:101]
	v_mfma_f32_16x16x32_bf16 v[86:89], v[156:159], v[188:191], v[86:89]
	v_mfma_f32_16x16x32_bf16 v[82:85], v[164:167], v[188:191], v[82:85]
	v_mfma_f32_16x16x32_bf16 v[70:73], v[156:159], v[206:209], v[70:73]
	v_mfma_f32_16x16x32_bf16 v[66:69], v[164:167], v[206:209], v[66:69]
	s_setprio 0
	s_barrier
; #define PG8_STAGE(bufoff, gbase, voff) do { _Pragma("unroll") for (int _i = 0; _i < 2; ++_i) \
;         __builtin_amdgcn_global_load_lds((const unsigned*)((const char*)(gbase) + (voff)[_i]), (PG8_LAS unsigned*)(lds + (bufoff) + ldsw + _i * 8192), 16, 0, 0); } while (0)
; #define PG8_LDA(dst, b, h) do { _Pragma("unroll") for (int m = 0; m < 4; ++m) _Pragma("unroll") for (int k = 0; k < 2; ++k) dst[m][k] = *(const PG8_LAS bf16x8*)(lds + PG8_SA(b, h) + aoff + m * 2048 + k * 1024); } while (0)
; #define PG8_MMA(ai, bj, At, Bt) do { __builtin_amdgcn_s_setprio(1); _Pragma("unroll") for (int m = 0; m < 4; ++m) _Pragma("unroll") for (int n = 0; n < 2; ++n) _Pragma("unroll") for (int k = 0; k < 2; ++k) \
;         acc[ai][bj][m][n] = __builtin_amdgcn_mfma_f32_16x16x32_bf16(Bt[n][k], At[m][k], acc[ai][bj][m][n], 0, 0, 0); __builtin_amdgcn_s_setprio(0); } while (0)
; #define PG8_WAIT_V(n) asm volatile("s_waitcnt vmcnt(" #n ")" ::: "memory")
; #define PG8_WAIT_L(n) asm volatile("s_waitcnt lgkmcnt(" #n ")" ::: "memory")
; #define PG8_BAR __builtin_amdgcn_s_barrier()
; #define PG8_SCHED __builtin_amdgcn_sched_barrier(0)
; template <class Epi, class Sched, bool ALIGN_EPI = false, bool SP2 = false>
; __device__ __forceinline__ void gemm_phase(PG8_LAS unsigned char* lds, const Gemm g, const Sched& S, const Epi& E) {
;     ...
;             PG8_LDA(At, 1, 1); PG8_STAGE(PG8_SB(1, 0), b3, voffB); PG8_STAGE(PG8_SB(1, 1), b3 + hstepB, voffB); PG8_STAGE(PG8_SA(1, 0), a3, voffA);
;             PG8_WAIT_V(8); PG8_WAIT_L(0); PG8_BAR; PG8_MMA(1, 0, At, B0); PG8_MMA(1, 1, At, B1); PG8_BAR; PG8_SCHED;
;     ...
;         if constexpr (ALIGN_EPI) { if (wr == 0) PG8_BAR; }
	s_add_i32 s26, s54, s40
	v_lshl_add_u64 v[192:193], v[192:193], 0, s[88:89]
	s_mov_b32 m0, s26
	ds_read_b128 v[168:171], v215 offset:49152
	ds_read_b128 v[172:175], v215 offset:50176
	ds_read_b128 v[176:179], v215 offset:51200
	ds_read_b128 v[180:183], v215 offset:52224
	ds_read_b128 v[184:187], v215 offset:53248
	ds_read_b128 v[188:191], v215 offset:54272
	ds_read_b128 v[198:201], v215 offset:55296
	ds_read_b128 v[206:209], v215 offset:56320
	global_load_lds_dwordx4 v[192:193], off
	s_add_i32 m0, s26, 0x2000
	s_add_u32 s24, s24, 0x40080
	v_lshl_add_u64 v[192:193], v[216:217], 0, s[88:89]
	s_addc_u32 s25, s25, 0
	s_add_i32 s26, s55, s40
	global_load_lds_dwordx4 v[192:193], off
	v_lshl_add_u64 v[192:193], s[24:25], 0, v[0:1]
	s_mov_b32 m0, s26
	s_nop 0
	global_load_lds_dwordx4 v[192:193], off
	v_lshl_add_u64 v[192:193], s[24:25], 0, v[130:131]
	s_add_i32 m0, s26, 0x2000
	s_nop 0
	global_load_lds_dwordx4 v[192:193], off
	v_lshl_add_u64 v[192:193], v[218:219], 0, s[88:89]
	s_mov_b32 m0, s46
	s_nop 0
	global_load_lds_dwordx4 v[192:193], off
	v_lshl_add_u64 v[192:193], v[220:221], 0, s[88:89]
	s_mov_b32 m0, s47
	s_nop 0
	global_load_lds_dwordx4 v[192:193], off
	s_waitcnt vmcnt(8)
	s_waitcnt lgkmcnt(0)
	s_barrier
	s_setprio 1
	s_waitcnt lgkmcnt(0)
	v_mfma_f32_16x16x32_bf16 v[62:65], v[136:139], v[168:171], v[62:65]
	v_mfma_f32_16x16x32_bf16 v[58:61], v[144:147], v[168:171], v[58:61]
	v_mfma_f32_16x16x32_bf16 v[46:49], v[136:139], v[176:179], v[46:49]
	v_mfma_f32_16x16x32_bf16 v[42:45], v[144:147], v[176:179], v[42:45]
	v_mfma_f32_16x16x32_bf16 v[30:33], v[136:139], v[184:187], v[30:33]
	v_mfma_f32_16x16x32_bf16 v[26:29], v[144:147], v[184:187], v[26:29]
	v_mfma_f32_16x16x32_bf16 v[14:17], v[136:139], v[198:201], v[14:17]
	v_mfma_f32_16x16x32_bf16 v[10:13], v[144:147], v[198:201], v[10:13]
	v_mfma_f32_16x16x32_bf16 v[62:65], v[140:143], v[172:175], v[62:65]
	v_mfma_f32_16x16x32_bf16 v[58:61], v[148:151], v[172:175], v[58:61]
	v_mfma_f32_16x16x32_bf16 v[46:49], v[140:143], v[180:183], v[46:49]
	v_mfma_f32_16x16x32_bf16 v[42:45], v[148:151], v[180:183], v[42:45]
	v_mfma_f32_16x16x32_bf16 v[30:33], v[140:143], v[188:191], v[30:33]
	v_mfma_f32_16x16x32_bf16 v[26:29], v[148:151], v[188:191], v[26:29]
	v_mfma_f32_16x16x32_bf16 v[14:17], v[140:143], v[206:209], v[14:17]
	v_mfma_f32_16x16x32_bf16 v[10:13], v[148:151], v[206:209], v[10:13]
	s_setprio 0
	s_setprio 1
	v_mfma_f32_16x16x32_bf16 v[54:57], v[152:155], v[168:171], v[54:57]
	v_mfma_f32_16x16x32_bf16 v[50:53], v[160:163], v[168:171], v[50:53]
	v_mfma_f32_16x16x32_bf16 v[38:41], v[152:155], v[176:179], v[38:41]
	v_mfma_f32_16x16x32_bf16 v[34:37], v[160:163], v[176:179], v[34:37]
	v_mfma_f32_16x16x32_bf16 v[22:25], v[152:155], v[184:187], v[22:25]
	v_mfma_f32_16x16x32_bf16 v[18:21], v[160:163], v[184:187], v[18:21]
	v_mfma_f32_16x16x32_bf16 v[6:9], v[152:155], v[198:201], v[6:9]
	v_mfma_f32_16x16x32_bf16 v[2:5], v[160:163], v[198:201], v[2:5]
	v_mfma_f32_16x16x32_bf16 v[54:57], v[156:159], v[172:175], v[54:57]
	v_mfma_f32_16x16x32_bf16 v[50:53], v[164:167], v[172:175], v[50:53]
	v_mfma_f32_16x16x32_bf16 v[38:41], v[156:159], v[180:183], v[38:41]
	v_mfma_f32_16x16x32_bf16 v[34:37], v[164:167], v[180:183], v[34:37]
	v_mfma_f32_16x16x32_bf16 v[22:25], v[156:159], v[188:191], v[22:25]
	v_mfma_f32_16x16x32_bf16 v[18:21], v[164:167], v[188:191], v[18:21]
	v_mfma_f32_16x16x32_bf16 v[6:9], v[156:159], v[206:209], v[6:9]
	v_mfma_f32_16x16x32_bf16 v[2:5], v[164:167], v[206:209], v[2:5]
	s_setprio 0
	s_barrier
	s_add_i32 s53, s53, 2
	s_add_u32 s22, s22, 0x100
	s_addc_u32 s23, s23, 0
	s_add_u32 s51, s51, 0x100
	s_addc_u32 s52, s52, 0
	s_cmp_gt_u32 s53, 13
	s_cbranch_scc0 .LBB0_1170
	v_readfirstlane_b32 s100, v238
	s_nop 3
	s_bfe_u32 s100, s100, 0x40006
	s_cmp_ge_u32 s100, 4
	s_cbranch_scc0 .Lepiprio_11
	s_setprio 1

; #define PG8_STAGE(bufoff, gbase, voff) do { _Pragma("unroll") for (int _i = 0; _i < 2; ++_i) \
;         __builtin_amdgcn_global_load_lds((const unsigned*)((const char*)(gbase) + (voff)[_i]), (PG8_LAS unsigned*)(lds + (bufoff) + ldsw + _i * 8192), 16, 0, 0); } while (0)
; #define PG8_LDA(dst, b, h) do { _Pragma("unroll") for (int m = 0; m < 4; ++m) _Pragma("unroll") for (int k = 0; k < 2; ++k) dst[m][k] = *(const PG8_LAS bf16x8*)(lds + PG8_SA(b, h) + aoff + m * 2048 + k * 1024); } while (0)
; #define PG8_LDB(dst, b, h) do { _Pragma("unroll") for (int n = 0; n < 2; ++n) _Pragma("unroll") for (int k = 0; k < 2; ++k) dst[n][k] = *(const PG8_LAS bf16x8*)(lds + PG8_SB(b, h) + boff + n * 2048 + k * 1024); } while (0)
; #define PG8_MMA(ai, bj, At, Bt) do { __builtin_amdgcn_s_setprio(1); _Pragma("unroll") for (int m = 0; m < 4; ++m) _Pragma("unroll") for (int n = 0; n < 2; ++n) _Pragma("unroll") for (int k = 0; k < 2; ++k) \
;         acc[ai][bj][m][n] = __builtin_amdgcn_mfma_f32_16x16x32_bf16(Bt[n][k], At[m][k], acc[ai][bj][m][n], 0, 0, 0); __builtin_amdgcn_s_setprio(0); } while (0)
; #define PG8_WAIT_V(n) asm volatile("s_waitcnt vmcnt(" #n ")" ::: "memory")
; #define PG8_WAIT_L(n) asm volatile("s_waitcnt lgkmcnt(" #n ")" ::: "memory")
; #define PG8_BAR __builtin_amdgcn_s_barrier()
; #define PG8_SCHED __builtin_amdgcn_sched_barrier(0)
; template <class Epi, class Sched, bool ALIGN_EPI = false, bool SP2 = false>
; __device__ __forceinline__ void gemm_phase(PG8_LAS unsigned char* lds, const Gemm g, const Sched& S, const Epi& E) {
;     ...
;         for (int t = 0; t < nt; t += 2) {
;             const bool last = (t == nt - 2);
;             const char* a1 = cA + (size_t)(t + 1) * kstep;
;             const char* a2 = last ? nA : cA + (size_t)(t + 2) * kstep; const char* b2 = last ? nB : cB + (size_t)(t + 2) * kstep;
;             const char* a3 = a2 + kstep; const char* b3 = b2 + kstep;
;             if (last && has_next) S.a_ready(nxt);
;             if constexpr (SP2) {
;             PG8_LDB(B0, 0, 0); PG8_LDB(B1, 0, 1); PG8_SCHED; PG8_LDA(At, 0, 0); PG8_STAGE(PG8_SA(1, 1), a1 + hstepA, voffA);
;             PG8_WAIT_V(8); PG8_WAIT_L(0); PG8_BAR; PG8_MMA(0, 0, At, B0); PG8_MMA(0, 1, At, B1); PG8_BAR; PG8_SCHED;
;             PG8_LDA(At, 0, 1); PG8_STAGE(PG8_SB(0, 0), b2, voffB); PG8_STAGE(PG8_SB(0, 1), b2 + hstepB, voffB); PG8_STAGE(PG8_SA(0, 0), a2, voffA);
.LBB0_1250:
	s_add_u32 s18, s16, 0xfffc0080
	s_addc_u32 s19, s17, -1
	s_add_i32 s47, 0, 0x10000
	s_cmp_eq_u32 s46, 12
	s_cselect_b32 s21, s9, s19
	s_cselect_b32 s20, s42, s18
	s_cselect_b32 s19, s7, s45
	s_cselect_b32 s18, s43, s44
	s_add_i32 s50, 0, 0x14000
	v_add_u32_e32 v154, s47, v169
	v_add_u32_e32 v162, s50, v169
	ds_read_b128 v[130:133], v154
	ds_read_b128 v[134:137], v154 offset:1024
	ds_read_b128 v[138:141], v154 offset:2048
	ds_read_b128 v[154:157], v154 offset:3072
	ds_read_b128 v[158:161], v162
	ds_read_b128 v[176:179], v162 offset:1024
	ds_read_b128 v[180:183], v162 offset:2048
	ds_read_b128 v[184:187], v162 offset:3072
	v_lshl_add_u64 v[162:163], s[16:17], 0, v[150:151]
	s_add_i32 m0, s30, 0xc000
	ds_read_b128 v[188:191], v175
	ds_read_b128 v[198:201], v175 offset:1024
	ds_read_b128 v[206:209], v175 offset:2048
	ds_read_b128 v[212:215], v175 offset:3072
	ds_read_b128 v[216:219], v175 offset:4096
	ds_read_b128 v[220:223], v175 offset:5120
	ds_read_b128 v[224:227], v175 offset:6144
	ds_read_b128 v[228:231], v175 offset:7168
	global_load_lds_dwordx4 v[162:163], off
	v_lshl_add_u64 v[162:163], s[16:17], 0, v[152:153]
	s_add_i32 m0, s30, 0xe000
	s_nop 0
	global_load_lds_dwordx4 v[162:163], off
	s_waitcnt vmcnt(8)
	s_waitcnt lgkmcnt(0)
	s_barrier
	s_setprio 1
	s_waitcnt lgkmcnt(0)
	v_mfma_f32_16x16x32_bf16 v[126:129], v[130:133], v[188:191], v[126:129]
	v_mfma_f32_16x16x32_bf16 v[118:121], v[138:141], v[188:191], v[118:121]
	v_mfma_f32_16x16x32_bf16 v[110:113], v[130:133], v[206:209], v[110:113]
	v_mfma_f32_16x16x32_bf16 v[102:105], v[138:141], v[206:209], v[102:105]
	v_mfma_f32_16x16x32_bf16 v[94:97], v[130:133], v[216:219], v[94:97]
	v_mfma_f32_16x16x32_bf16 v[86:89], v[138:141], v[216:219], v[86:89]
	v_mfma_f32_16x16x32_bf16 v[78:81], v[130:133], v[224:227], v[78:81]
	v_mfma_f32_16x16x32_bf16 v[70:73], v[138:141], v[224:227], v[70:73]
	v_mfma_f32_16x16x32_bf16 v[126:129], v[134:137], v[198:201], v[126:129]
	v_mfma_f32_16x16x32_bf16 v[118:121], v[154:157], v[198:201], v[118:121]
	v_mfma_f32_16x16x32_bf16 v[110:113], v[134:137], v[212:215], v[110:113]
	v_mfma_f32_16x16x32_bf16 v[102:105], v[154:157], v[212:215], v[102:105]
	v_mfma_f32_16x16x32_bf16 v[94:97], v[134:137], v[220:223], v[94:97]
	v_mfma_f32_16x16x32_bf16 v[86:89], v[154:157], v[220:223], v[86:89]
	v_mfma_f32_16x16x32_bf16 v[78:81], v[134:137], v[228:231], v[78:81]
	v_mfma_f32_16x16x32_bf16 v[70:73], v[154:157], v[228:231], v[70:73]
	s_setprio 0
	s_setprio 1
	v_mfma_f32_16x16x32_bf16 v[122:125], v[158:161], v[188:191], v[122:125]
	v_mfma_f32_16x16x32_bf16 v[114:117], v[180:183], v[188:191], v[114:117]
	v_mfma_f32_16x16x32_bf16 v[106:109], v[158:161], v[206:209], v[106:109]
	v_mfma_f32_16x16x32_bf16 v[98:101], v[180:183], v[206:209], v[98:101]
	v_mfma_f32_16x16x32_bf16 v[90:93], v[158:161], v[216:219], v[90:93]
	v_mfma_f32_16x16x32_bf16 v[82:85], v[180:183], v[216:219], v[82:85]
	v_mfma_f32_16x16x32_bf16 v[74:77], v[158:161], v[224:227], v[74:77]
	v_mfma_f32_16x16x32_bf16 v[66:69], v[180:183], v[224:227], v[66:69]
	v_mfma_f32_16x16x32_bf16 v[122:125], v[176:179], v[198:201], v[122:125]
	v_mfma_f32_16x16x32_bf16 v[114:117], v[184:187], v[198:201], v[114:117]
	v_mfma_f32_16x16x32_bf16 v[106:109], v[176:179], v[212:215], v[106:109]
	v_mfma_f32_16x16x32_bf16 v[98:101], v[184:187], v[212:215], v[98:101]
	v_mfma_f32_16x16x32_bf16 v[90:93], v[176:179], v[220:223], v[90:93]
	v_mfma_f32_16x16x32_bf16 v[82:85], v[184:187], v[220:223], v[82:85]
	v_mfma_f32_16x16x32_bf16 v[74:77], v[176:179], v[228:231], v[74:77]
	v_mfma_f32_16x16x32_bf16 v[66:69], v[184:187], v[228:231], v[66:69]
	s_setprio 0
	s_barrier
	s_add_i32 s47, s47, s28
	v_lshl_add_u64 v[162:163], s[18:19], 0, v[0:1]
	s_mov_b32 m0, s47
	ds_read_b128 v[188:191], v175 offset:16384
	ds_read_b128 v[198:201], v175 offset:17408
	ds_read_b128 v[206:209], v175 offset:18432
	ds_read_b128 v[212:215], v175 offset:19456
	ds_read_b128 v[216:219], v175 offset:20480
	ds_read_b128 v[220:223], v175 offset:21504
	ds_read_b128 v[224:227], v175 offset:22528
	ds_read_b128 v[228:231], v175 offset:23552
	global_load_lds_dwordx4 v[162:163], off
	s_add_i32 m0, s47, 0x2000
	s_add_u32 s48, s18, 0x40000
	v_lshl_add_u64 v[166:167], s[18:19], 0, v[142:143]
	s_addc_u32 s49, s19, 0
	s_add_i32 s47, s50, s28
	global_load_lds_dwordx4 v[166:167], off
	v_lshl_add_u64 v[172:173], s[48:49], 0, v[0:1]
	s_mov_b32 m0, s47
	v_lshl_add_u64 v[192:193], s[20:21], 0, v[144:145]
	global_load_lds_dwordx4 v[172:173], off
	v_lshl_add_u64 v[172:173], s[48:49], 0, v[142:143]
	s_add_i32 m0, s47, 0x2000
	s_nop 0
	global_load_lds_dwordx4 v[172:173], off
	v_lshl_add_u64 v[172:173], s[20:21], 0, v[146:147]
	s_mov_b32 m0, s30
	s_nop 0
	global_load_lds_dwordx4 v[172:173], off
	s_mov_b32 m0, s31
	s_nop 0
	global_load_lds_dwordx4 v[192:193], off
	s_waitcnt vmcnt(8)
	s_waitcnt lgkmcnt(0)
	s_barrier
; #define PG8_STAGE(bufoff, gbase, voff) do { _Pragma("unroll") for (int _i = 0; _i < 2; ++_i) \
;         __builtin_amdgcn_global_load_lds((const unsigned*)((const char*)(gbase) + (voff)[_i]), (PG8_LAS unsigned*)(lds + (bufoff) + ldsw + _i * 8192), 16, 0, 0); } while (0)
; #define PG8_LDA(dst, b, h) do { _Pragma("unroll") for (int m = 0; m < 4; ++m) _Pragma("unroll") for (int k = 0; k < 2; ++k) dst[m][k] = *(const PG8_LAS bf16x8*)(lds + PG8_SA(b, h) + aoff + m * 2048 + k * 1024); } while (0)
; #define PG8_LDB(dst, b, h) do { _Pragma("unroll") for (int n = 0; n < 2; ++n) _Pragma("unroll") for (int k = 0; k < 2; ++k) dst[n][k] = *(const PG8_LAS bf16x8*)(lds + PG8_SB(b, h) + boff + n * 2048 + k * 1024); } while (0)
; #define PG8_MMA(ai, bj, At, Bt) do { __builtin_amdgcn_s_setprio(1); _Pragma("unroll") for (int m = 0; m < 4; ++m) _Pragma("unroll") for (int n = 0; n < 2; ++n) _Pragma("unroll") for (int k = 0; k < 2; ++k) \
;         acc[ai][bj][m][n] = __builtin_amdgcn_mfma_f32_16x16x32_bf16(Bt[n][k], At[m][k], acc[ai][bj][m][n], 0, 0, 0); __builtin_amdgcn_s_setprio(0); } while (0)
; #define PG8_WAIT_V(n) asm volatile("s_waitcnt vmcnt(" #n ")" ::: "memory")
; #define PG8_WAIT_L(n) asm volatile("s_waitcnt lgkmcnt(" #n ")" ::: "memory")
; #define PG8_BAR __builtin_amdgcn_s_barrier()
; #define PG8_SCHED __builtin_amdgcn_sched_barrier(0)
; template <class Epi, class Sched, bool ALIGN_EPI = false, bool SP2 = false>
; __device__ __forceinline__ void gemm_phase(PG8_LAS unsigned char* lds, const Gemm g, const Sched& S, const Epi& E) {
;     ...
;             PG8_WAIT_V(8); PG8_WAIT_L(0); PG8_BAR; PG8_MMA(1, 0, At, B0); PG8_MMA(1, 1, At, B1); PG8_BAR; PG8_SCHED;
;             PG8_LDB(B0, 1, 0); PG8_LDB(B1, 1, 1); PG8_SCHED; PG8_LDA(At, 1, 0); PG8_STAGE(PG8_SA(0, 1), a2 + hstepA, voffA);
;             PG8_WAIT_V(8); PG8_WAIT_L(0); PG8_BAR; PG8_MMA(0, 0, At, B0); PG8_MMA(0, 1, At, B1); PG8_BAR; PG8_SCHED;
	s_setprio 1
	s_waitcnt lgkmcnt(0)
	v_mfma_f32_16x16x32_bf16 v[62:65], v[130:133], v[188:191], v[62:65]
	v_mfma_f32_16x16x32_bf16 v[54:57], v[138:141], v[188:191], v[54:57]
	v_mfma_f32_16x16x32_bf16 v[46:49], v[130:133], v[206:209], v[46:49]
	v_mfma_f32_16x16x32_bf16 v[38:41], v[138:141], v[206:209], v[38:41]
	v_mfma_f32_16x16x32_bf16 v[30:33], v[130:133], v[216:219], v[30:33]
	v_mfma_f32_16x16x32_bf16 v[22:25], v[138:141], v[216:219], v[22:25]
	v_mfma_f32_16x16x32_bf16 v[14:17], v[130:133], v[224:227], v[14:17]
	v_mfma_f32_16x16x32_bf16 v[6:9], v[138:141], v[224:227], v[6:9]
	v_mfma_f32_16x16x32_bf16 v[62:65], v[134:137], v[198:201], v[62:65]
	v_mfma_f32_16x16x32_bf16 v[54:57], v[154:157], v[198:201], v[54:57]
	v_mfma_f32_16x16x32_bf16 v[46:49], v[134:137], v[212:215], v[46:49]
	v_mfma_f32_16x16x32_bf16 v[38:41], v[154:157], v[212:215], v[38:41]
	v_mfma_f32_16x16x32_bf16 v[30:33], v[134:137], v[220:223], v[30:33]
	v_mfma_f32_16x16x32_bf16 v[22:25], v[154:157], v[220:223], v[22:25]
	v_mfma_f32_16x16x32_bf16 v[14:17], v[134:137], v[228:231], v[14:17]
	v_mfma_f32_16x16x32_bf16 v[6:9], v[154:157], v[228:231], v[6:9]
	s_setprio 0
	s_setprio 1
	v_mfma_f32_16x16x32_bf16 v[58:61], v[158:161], v[188:191], v[58:61]
	v_mfma_f32_16x16x32_bf16 v[50:53], v[180:183], v[188:191], v[50:53]
	v_mfma_f32_16x16x32_bf16 v[42:45], v[158:161], v[206:209], v[42:45]
	v_mfma_f32_16x16x32_bf16 v[34:37], v[180:183], v[206:209], v[34:37]
	v_mfma_f32_16x16x32_bf16 v[26:29], v[158:161], v[216:219], v[26:29]
	v_mfma_f32_16x16x32_bf16 v[18:21], v[180:183], v[216:219], v[18:21]
	v_mfma_f32_16x16x32_bf16 v[10:13], v[158:161], v[224:227], v[10:13]
	v_mfma_f32_16x16x32_bf16 v[2:5], v[180:183], v[224:227], v[2:5]
	v_mfma_f32_16x16x32_bf16 v[58:61], v[176:179], v[198:201], v[58:61]
	v_mfma_f32_16x16x32_bf16 v[50:53], v[184:187], v[198:201], v[50:53]
	v_mfma_f32_16x16x32_bf16 v[42:45], v[176:179], v[212:215], v[42:45]
	v_mfma_f32_16x16x32_bf16 v[34:37], v[184:187], v[212:215], v[34:37]
	v_mfma_f32_16x16x32_bf16 v[26:29], v[176:179], v[220:223], v[26:29]
	v_mfma_f32_16x16x32_bf16 v[18:21], v[184:187], v[220:223], v[18:21]
	v_mfma_f32_16x16x32_bf16 v[10:13], v[176:179], v[228:231], v[10:13]
	v_mfma_f32_16x16x32_bf16 v[2:5], v[184:187], v[228:231], v[2:5]
	s_setprio 0
	s_barrier
	s_add_i32 s47, 0, 0x18000
	s_add_i32 s48, 0, 0x1c000
	v_add_u32_e32 v154, s47, v169
	v_add_u32_e32 v164, s48, v169
	ds_read_b128 v[130:133], v154
	ds_read_b128 v[134:137], v154 offset:1024
	ds_read_b128 v[138:141], v154 offset:2048
	ds_read_b128 v[154:157], v154 offset:3072
	ds_read_b128 v[158:161], v164
	ds_read_b128 v[176:179], v164 offset:1024
	ds_read_b128 v[180:183], v164 offset:2048
	ds_read_b128 v[184:187], v164 offset:3072
	s_add_u32 s20, s20, 0x40000
	s_addc_u32 s21, s21, 0
	s_mov_b32 m0, s34
	v_lshl_add_u64 v[232:233], s[20:21], 0, v[146:147]
	ds_read_b128 v[188:191], v175 offset:32768
	ds_read_b128 v[198:201], v175 offset:33792
	ds_read_b128 v[206:209], v175 offset:34816
	ds_read_b128 v[212:215], v175 offset:35840
	ds_read_b128 v[216:219], v175 offset:36864
	ds_read_b128 v[220:223], v175 offset:37888
	ds_read_b128 v[224:227], v175 offset:38912
	ds_read_b128 v[228:231], v175 offset:39936
	global_load_lds_dwordx4 v[232:233], off
	v_lshl_add_u64 v[232:233], s[20:21], 0, v[144:145]
	s_mov_b32 m0, s35
	s_nop 0
	global_load_lds_dwordx4 v[232:233], off
	s_waitcnt vmcnt(8)
	s_waitcnt lgkmcnt(0)
	s_barrier
	s_setprio 1
	s_waitcnt lgkmcnt(0)
	v_mfma_f32_16x16x32_bf16 v[126:129], v[130:133], v[188:191], v[126:129]
	v_mfma_f32_16x16x32_bf16 v[118:121], v[138:141], v[188:191], v[118:121]
	v_mfma_f32_16x16x32_bf16 v[110:113], v[130:133], v[206:209], v[110:113]
	v_mfma_f32_16x16x32_bf16 v[102:105], v[138:141], v[206:209], v[102:105]
	v_mfma_f32_16x16x32_bf16 v[94:97], v[130:133], v[216:219], v[94:97]
	v_mfma_f32_16x16x32_bf16 v[86:89], v[138:141], v[216:219], v[86:89]
	v_mfma_f32_16x16x32_bf16 v[78:81], v[130:133], v[224:227], v[78:81]
	v_mfma_f32_16x16x32_bf16 v[70:73], v[138:141], v[224:227], v[70:73]
	v_mfma_f32_16x16x32_bf16 v[126:129], v[134:137], v[198:201], v[126:129]
	v_mfma_f32_16x16x32_bf16 v[118:121], v[154:157], v[198:201], v[118:121]
	v_mfma_f32_16x16x32_bf16 v[110:113], v[134:137], v[212:215], v[110:113]
	v_mfma_f32_16x16x32_bf16 v[102:105], v[154:157], v[212:215], v[102:105]
	v_mfma_f32_16x16x32_bf16 v[94:97], v[134:137], v[220:223], v[94:97]
	v_mfma_f32_16x16x32_bf16 v[86:89], v[154:157], v[220:223], v[86:89]
	v_mfma_f32_16x16x32_bf16 v[78:81], v[134:137], v[228:231], v[78:81]
	v_mfma_f32_16x16x32_bf16 v[70:73], v[154:157], v[228:231], v[70:73]
	s_setprio 0
	s_setprio 1
	v_mfma_f32_16x16x32_bf16 v[122:125], v[158:161], v[188:191], v[122:125]
	v_mfma_f32_16x16x32_bf16 v[114:117], v[180:183], v[188:191], v[114:117]
	v_mfma_f32_16x16x32_bf16 v[106:109], v[158:161], v[206:209], v[106:109]
	v_mfma_f32_16x16x32_bf16 v[98:101], v[180:183], v[206:209], v[98:101]
	v_mfma_f32_16x16x32_bf16 v[90:93], v[158:161], v[216:219], v[90:93]
	v_mfma_f32_16x16x32_bf16 v[82:85], v[180:183], v[216:219], v[82:85]
	v_mfma_f32_16x16x32_bf16 v[74:77], v[158:161], v[224:227], v[74:77]
	v_mfma_f32_16x16x32_bf16 v[66:69], v[180:183], v[224:227], v[66:69]
	v_mfma_f32_16x16x32_bf16 v[122:125], v[176:179], v[198:201], v[122:125]
	v_mfma_f32_16x16x32_bf16 v[114:117], v[184:187], v[198:201], v[114:117]
	v_mfma_f32_16x16x32_bf16 v[106:109], v[176:179], v[212:215], v[106:109]
	v_mfma_f32_16x16x32_bf16 v[98:101], v[184:187], v[212:215], v[98:101]
	v_mfma_f32_16x16x32_bf16 v[90:93], v[176:179], v[220:223], v[90:93]
	v_mfma_f32_16x16x32_bf16 v[82:85], v[184:187], v[220:223], v[82:85]
	v_mfma_f32_16x16x32_bf16 v[74:77], v[176:179], v[228:231], v[74:77]
	v_mfma_f32_16x16x32_bf16 v[66:69], v[184:187], v[228:231], v[66:69]
	s_setprio 0
	s_barrier
; #define PG8_STAGE(bufoff, gbase, voff) do { _Pragma("unroll") for (int _i = 0; _i < 2; ++_i) \
;         __builtin_amdgcn_global_load_lds((const unsigned*)((const char*)(gbase) + (voff)[_i]), (PG8_LAS unsigned*)(lds + (bufoff) + ldsw + _i * 8192), 16, 0, 0); } while (0)
; #define PG8_LDA(dst, b, h) do { _Pragma("unroll") for (int m = 0; m < 4; ++m) _Pragma("unroll") for (int k = 0; k < 2; ++k) dst[m][k] = *(const PG8_LAS bf16x8*)(lds + PG8_SA(b, h) + aoff + m * 2048 + k * 1024); } while (0)
; #define PG8_MMA(ai, bj, At, Bt) do { __builtin_amdgcn_s_setprio(1); _Pragma("unroll") for (int m = 0; m < 4; ++m) _Pragma("unroll") for (int n = 0; n < 2; ++n) _Pragma("unroll") for (int k = 0; k < 2; ++k) \
;         acc[ai][bj][m][n] = __builtin_amdgcn_mfma_f32_16x16x32_bf16(Bt[n][k], At[m][k], acc[ai][bj][m][n], 0, 0, 0); __builtin_amdgcn_s_setprio(0); } while (0)
; #define PG8_WAIT_V(n) asm volatile("s_waitcnt vmcnt(" #n ")" ::: "memory")
; #define PG8_WAIT_L(n) asm volatile("s_waitcnt lgkmcnt(" #n ")" ::: "memory")
; #define PG8_BAR __builtin_amdgcn_s_barrier()
; #define PG8_SCHED __builtin_amdgcn_sched_barrier(0)
; template <class Epi, class Sched, bool ALIGN_EPI = false, bool SP2 = false>
; __device__ __forceinline__ void gemm_phase(PG8_LAS unsigned char* lds, const Gemm g, const Sched& S, const Epi& E) {
;     ...
;             PG8_LDA(At, 1, 1); PG8_STAGE(PG8_SB(1, 0), b3, voffB); PG8_STAGE(PG8_SB(1, 1), b3 + hstepB, voffB); PG8_STAGE(PG8_SA(1, 0), a3, voffA);
;             PG8_WAIT_V(8); PG8_WAIT_L(0); PG8_BAR; PG8_MMA(1, 0, At, B0); PG8_MMA(1, 1, At, B1); PG8_BAR; PG8_SCHED;
;     ...
;         if constexpr (ALIGN_EPI) { if (wr == 0) PG8_BAR; }
	s_add_i32 s20, s47, s28
	v_lshl_add_u64 v[162:163], v[162:163], 0, s[88:89]
	s_mov_b32 m0, s20
	ds_read_b128 v[188:191], v175 offset:49152
	ds_read_b128 v[198:201], v175 offset:50176
	ds_read_b128 v[206:209], v175 offset:51200
	ds_read_b128 v[212:215], v175 offset:52224
	ds_read_b128 v[216:219], v175 offset:53248
	ds_read_b128 v[220:223], v175 offset:54272
	ds_read_b128 v[224:227], v175 offset:55296
	ds_read_b128 v[228:231], v175 offset:56320
	global_load_lds_dwordx4 v[162:163], off
	s_add_i32 m0, s20, 0x2000
	s_add_u32 s18, s18, 0x40080
	v_lshl_add_u64 v[162:163], v[166:167], 0, s[88:89]
	s_addc_u32 s19, s19, 0
	s_add_i32 s20, s48, s28
	global_load_lds_dwordx4 v[162:163], off
	v_lshl_add_u64 v[162:163], s[18:19], 0, v[0:1]
	s_mov_b32 m0, s20
	s_nop 0
	global_load_lds_dwordx4 v[162:163], off
	v_lshl_add_u64 v[162:163], s[18:19], 0, v[142:143]
	s_add_i32 m0, s20, 0x2000
	s_nop 0
	global_load_lds_dwordx4 v[162:163], off
	v_lshl_add_u64 v[162:163], v[172:173], 0, s[88:89]
	s_mov_b32 m0, s38
	s_nop 0
	global_load_lds_dwordx4 v[162:163], off
	v_lshl_add_u64 v[162:163], v[192:193], 0, s[88:89]
	s_mov_b32 m0, s39
	s_nop 0
	global_load_lds_dwordx4 v[162:163], off
	s_waitcnt vmcnt(8)
	s_waitcnt lgkmcnt(0)
	s_barrier
	s_setprio 1
	s_waitcnt lgkmcnt(0)
	v_mfma_f32_16x16x32_bf16 v[62:65], v[130:133], v[188:191], v[62:65]
	v_mfma_f32_16x16x32_bf16 v[54:57], v[138:141], v[188:191], v[54:57]
	v_mfma_f32_16x16x32_bf16 v[46:49], v[130:133], v[206:209], v[46:49]
	v_mfma_f32_16x16x32_bf16 v[38:41], v[138:141], v[206:209], v[38:41]
	v_mfma_f32_16x16x32_bf16 v[30:33], v[130:133], v[216:219], v[30:33]
	v_mfma_f32_16x16x32_bf16 v[22:25], v[138:141], v[216:219], v[22:25]
	v_mfma_f32_16x16x32_bf16 v[14:17], v[130:133], v[224:227], v[14:17]
	v_mfma_f32_16x16x32_bf16 v[6:9], v[138:141], v[224:227], v[6:9]
	v_mfma_f32_16x16x32_bf16 v[62:65], v[134:137], v[198:201], v[62:65]
	v_mfma_f32_16x16x32_bf16 v[54:57], v[154:157], v[198:201], v[54:57]
	v_mfma_f32_16x16x32_bf16 v[46:49], v[134:137], v[212:215], v[46:49]
	v_mfma_f32_16x16x32_bf16 v[38:41], v[154:157], v[212:215], v[38:41]
	v_mfma_f32_16x16x32_bf16 v[30:33], v[134:137], v[220:223], v[30:33]
	v_mfma_f32_16x16x32_bf16 v[22:25], v[154:157], v[220:223], v[22:25]
	v_mfma_f32_16x16x32_bf16 v[14:17], v[134:137], v[228:231], v[14:17]
	v_mfma_f32_16x16x32_bf16 v[6:9], v[154:157], v[228:231], v[6:9]
	s_setprio 0
	s_setprio 1
	v_mfma_f32_16x16x32_bf16 v[58:61], v[158:161], v[188:191], v[58:61]
	v_mfma_f32_16x16x32_bf16 v[50:53], v[180:183], v[188:191], v[50:53]
	v_mfma_f32_16x16x32_bf16 v[42:45], v[158:161], v[206:209], v[42:45]
	v_mfma_f32_16x16x32_bf16 v[34:37], v[180:183], v[206:209], v[34:37]
	v_mfma_f32_16x16x32_bf16 v[26:29], v[158:161], v[216:219], v[26:29]
	v_mfma_f32_16x16x32_bf16 v[18:21], v[180:183], v[216:219], v[18:21]
	v_mfma_f32_16x16x32_bf16 v[10:13], v[158:161], v[224:227], v[10:13]
	v_mfma_f32_16x16x32_bf16 v[2:5], v[180:183], v[224:227], v[2:5]
	v_mfma_f32_16x16x32_bf16 v[58:61], v[176:179], v[198:201], v[58:61]
	v_mfma_f32_16x16x32_bf16 v[50:53], v[184:187], v[198:201], v[50:53]
	v_mfma_f32_16x16x32_bf16 v[42:45], v[176:179], v[212:215], v[42:45]
	v_mfma_f32_16x16x32_bf16 v[34:37], v[184:187], v[212:215], v[34:37]
	v_mfma_f32_16x16x32_bf16 v[26:29], v[176:179], v[220:223], v[26:29]
	v_mfma_f32_16x16x32_bf16 v[18:21], v[184:187], v[220:223], v[18:21]
	v_mfma_f32_16x16x32_bf16 v[10:13], v[176:179], v[228:231], v[10:13]
	v_mfma_f32_16x16x32_bf16 v[2:5], v[184:187], v[228:231], v[2:5]
	s_setprio 0
	s_barrier
	s_add_i32 s46, s46, 2
	s_add_u32 s16, s16, 0x100
	s_addc_u32 s17, s17, 0
	s_add_u32 s44, s44, 0x100
	s_addc_u32 s45, s45, 0
	s_cmp_gt_u32 s46, 13
	s_cbranch_scc0 .LBB0_1250
	v_readfirstlane_b32 s100, v238
	s_nop 3
	s_bfe_u32 s100, s100, 0x40006
	s_cmp_ge_u32 s100, 4
	s_cbranch_scc0 .Lepiprio_12
	s_setprio 1

; #define PG8_STAGE(bufoff, gbase, voff) do { _Pragma("unroll") for (int _i = 0; _i < 2; ++_i) \
;         __builtin_amdgcn_global_load_lds((const unsigned*)((const char*)(gbase) + (voff)[_i]), (PG8_LAS unsigned*)(lds + (bufoff) + ldsw + _i * 8192), 16, 0, 0); } while (0)
; #define PG8_LDA(dst, b, h) do { _Pragma("unroll") for (int m = 0; m < 4; ++m) _Pragma("unroll") for (int k = 0; k < 2; ++k) dst[m][k] = *(const PG8_LAS bf16x8*)(lds + PG8_SA(b, h) + aoff + m * 2048 + k * 1024); } while (0)
; #define PG8_LDB(dst, b, h) do { _Pragma("unroll") for (int n = 0; n < 2; ++n) _Pragma("unroll") for (int k = 0; k < 2; ++k) dst[n][k] = *(const PG8_LAS bf16x8*)(lds + PG8_SB(b, h) + boff + n * 2048 + k * 1024); } while (0)
; #define PG8_MMA(ai, bj, At, Bt) do { __builtin_amdgcn_s_setprio(1); _Pragma("unroll") for (int m = 0; m < 4; ++m) _Pragma("unroll") for (int n = 0; n < 2; ++n) _Pragma("unroll") for (int k = 0; k < 2; ++k) \
;         acc[ai][bj][m][n] = __builtin_amdgcn_mfma_f32_16x16x32_bf16(Bt[n][k], At[m][k], acc[ai][bj][m][n], 0, 0, 0); __builtin_amdgcn_s_setprio(0); } while (0)
; #define PG8_WAIT_V(n) asm volatile("s_waitcnt vmcnt(" #n ")" ::: "memory")
; #define PG8_WAIT_L(n) asm volatile("s_waitcnt lgkmcnt(" #n ")" ::: "memory")
; #define PG8_BAR __builtin_amdgcn_s_barrier()
; #define PG8_SCHED __builtin_amdgcn_sched_barrier(0)
; template <class Epi, class Sched, bool ALIGN_EPI = false, bool SP2 = false>
; __device__ __forceinline__ void gemm_phase(PG8_LAS unsigned char* lds, const Gemm g, const Sched& S, const Epi& E) {
;     ...
;         for (int t = 0; t < nt; t += 2) {
;             const bool last = (t == nt - 2);
;             const char* a1 = cA + (size_t)(t + 1) * kstep;
;             const char* a2 = last ? nA : cA + (size_t)(t + 2) * kstep; const char* b2 = last ? nB : cB + (size_t)(t + 2) * kstep;
;             const char* a3 = a2 + kstep; const char* b3 = b2 + kstep;
;             if (last && has_next) S.a_ready(nxt);
;             if constexpr (SP2) {
;             PG8_LDB(B0, 0, 0); PG8_LDB(B1, 0, 1); PG8_SCHED; PG8_LDA(At, 0, 0); PG8_STAGE(PG8_SA(1, 1), a1 + hstepA, voffA);
;             PG8_WAIT_V(8); PG8_WAIT_L(0); PG8_BAR; PG8_MMA(0, 0, At, B0); PG8_MMA(0, 1, At, B1); PG8_BAR; PG8_SCHED;
;             PG8_LDA(At, 0, 1); PG8_STAGE(PG8_SB(0, 0), b2, voffB); PG8_STAGE(PG8_SB(0, 1), b2 + hstepB, voffB); PG8_STAGE(PG8_SA(0, 0), a2, voffA);
.LBB0_1329:
	s_add_u32 s18, s16, 0x100
	s_addc_u32 s19, s17, 0
	s_add_i32 s54, 0, 0x10000
	s_cmp_eq_u32 s53, 40
	s_cselect_b32 s23, s1, s19
	s_cselect_b32 s22, s0, s18
	s_cselect_b32 s21, s15, s52
	s_cselect_b32 s20, s14, s51
	s_add_i32 s55, 0, 0x14000
	v_add_u32_e32 v148, s54, v191
	v_add_u32_e32 v164, s55, v191
	ds_read_b128 v[136:139], v148
	ds_read_b128 v[140:143], v148 offset:1024
	ds_read_b128 v[144:147], v148 offset:2048
	ds_read_b128 v[148:151], v148 offset:3072
	ds_read_b128 v[152:155], v164
	ds_read_b128 v[156:159], v164 offset:1024
	ds_read_b128 v[160:163], v164 offset:2048
	ds_read_b128 v[164:167], v164 offset:3072
	v_lshl_add_u64 v[188:189], s[16:17], 0, v[132:133]
	s_add_i32 m0, s34, 0xc000
	ds_read_b128 v[168:171], v193
	ds_read_b128 v[172:175], v193 offset:1024
	ds_read_b128 v[176:179], v193 offset:2048
	ds_read_b128 v[180:183], v193 offset:3072
	ds_read_b128 v[184:187], v193 offset:4096
	ds_read_b128 v[198:201], v193 offset:5120
	ds_read_b128 v[206:209], v193 offset:6144
	ds_read_b128 v[212:215], v193 offset:7168
	global_load_lds_dwordx4 v[188:189], off
	v_lshl_add_u64 v[188:189], s[16:17], 0, v[134:135]
	s_add_i32 m0, s34, 0xe000
	s_nop 0
	global_load_lds_dwordx4 v[188:189], off
	s_waitcnt vmcnt(8)
	s_waitcnt lgkmcnt(0)
	s_barrier
	s_setprio 1
	s_waitcnt lgkmcnt(0)
	v_mfma_f32_16x16x32_bf16 v[126:129], v[136:139], v[168:171], v[126:129]
	v_mfma_f32_16x16x32_bf16 v[122:125], v[144:147], v[168:171], v[122:125]
	v_mfma_f32_16x16x32_bf16 v[110:113], v[136:139], v[176:179], v[110:113]
	v_mfma_f32_16x16x32_bf16 v[106:109], v[144:147], v[176:179], v[106:109]
	v_mfma_f32_16x16x32_bf16 v[94:97], v[136:139], v[184:187], v[94:97]
	v_mfma_f32_16x16x32_bf16 v[90:93], v[144:147], v[184:187], v[90:93]
	v_mfma_f32_16x16x32_bf16 v[78:81], v[136:139], v[206:209], v[78:81]
	v_mfma_f32_16x16x32_bf16 v[74:77], v[144:147], v[206:209], v[74:77]
	v_mfma_f32_16x16x32_bf16 v[126:129], v[140:143], v[172:175], v[126:129]
	v_mfma_f32_16x16x32_bf16 v[122:125], v[148:151], v[172:175], v[122:125]
	v_mfma_f32_16x16x32_bf16 v[110:113], v[140:143], v[180:183], v[110:113]
	v_mfma_f32_16x16x32_bf16 v[106:109], v[148:151], v[180:183], v[106:109]
	v_mfma_f32_16x16x32_bf16 v[94:97], v[140:143], v[198:201], v[94:97]
	v_mfma_f32_16x16x32_bf16 v[90:93], v[148:151], v[198:201], v[90:93]
	v_mfma_f32_16x16x32_bf16 v[78:81], v[140:143], v[212:215], v[78:81]
	v_mfma_f32_16x16x32_bf16 v[74:77], v[148:151], v[212:215], v[74:77]
	s_setprio 0
	s_setprio 1
	v_mfma_f32_16x16x32_bf16 v[118:121], v[152:155], v[168:171], v[118:121]
	v_mfma_f32_16x16x32_bf16 v[114:117], v[160:163], v[168:171], v[114:117]
	v_mfma_f32_16x16x32_bf16 v[102:105], v[152:155], v[176:179], v[102:105]
	v_mfma_f32_16x16x32_bf16 v[98:101], v[160:163], v[176:179], v[98:101]
	v_mfma_f32_16x16x32_bf16 v[86:89], v[152:155], v[184:187], v[86:89]
	v_mfma_f32_16x16x32_bf16 v[82:85], v[160:163], v[184:187], v[82:85]
	v_mfma_f32_16x16x32_bf16 v[70:73], v[152:155], v[206:209], v[70:73]
	v_mfma_f32_16x16x32_bf16 v[66:69], v[160:163], v[206:209], v[66:69]
	v_mfma_f32_16x16x32_bf16 v[118:121], v[156:159], v[172:175], v[118:121]
	v_mfma_f32_16x16x32_bf16 v[114:117], v[164:167], v[172:175], v[114:117]
	v_mfma_f32_16x16x32_bf16 v[102:105], v[156:159], v[180:183], v[102:105]
	v_mfma_f32_16x16x32_bf16 v[98:101], v[164:167], v[180:183], v[98:101]
	v_mfma_f32_16x16x32_bf16 v[86:89], v[156:159], v[198:201], v[86:89]
	v_mfma_f32_16x16x32_bf16 v[82:85], v[164:167], v[198:201], v[82:85]
	v_mfma_f32_16x16x32_bf16 v[70:73], v[156:159], v[212:215], v[70:73]
	v_mfma_f32_16x16x32_bf16 v[66:69], v[164:167], v[212:215], v[66:69]
	s_setprio 0
	s_barrier
	s_add_i32 s16, s54, s31
	v_lshl_add_u64 v[188:189], s[20:21], 0, v[0:1]
	s_mov_b32 m0, s16
	ds_read_b128 v[168:171], v193 offset:16384
	ds_read_b128 v[172:175], v193 offset:17408
	ds_read_b128 v[176:179], v193 offset:18432
	ds_read_b128 v[180:183], v193 offset:19456
	ds_read_b128 v[184:187], v193 offset:20480
	ds_read_b128 v[198:201], v193 offset:21504
	ds_read_b128 v[206:209], v193 offset:22528
	ds_read_b128 v[212:215], v193 offset:23552
	global_load_lds_dwordx4 v[188:189], off
	s_add_i32 m0, s16, 0x2000
	s_add_u32 s16, s20, 0xb0000
	v_lshl_add_u64 v[216:217], s[20:21], 0, v[130:131]
	s_addc_u32 s17, s21, 0
	s_add_i32 s54, s55, s31
	global_load_lds_dwordx4 v[216:217], off
	v_lshl_add_u64 v[218:219], s[16:17], 0, v[0:1]
	s_mov_b32 m0, s54
	v_lshl_add_u64 v[220:221], s[22:23], 0, v[130:131]
	global_load_lds_dwordx4 v[218:219], off
	v_lshl_add_u64 v[218:219], s[16:17], 0, v[130:131]
	s_add_i32 m0, s54, 0x2000
	s_nop 0
	global_load_lds_dwordx4 v[218:219], off
	v_lshl_add_u64 v[218:219], s[22:23], 0, v[0:1]
	s_mov_b32 m0, s34
	s_nop 0
	global_load_lds_dwordx4 v[218:219], off
	s_mov_b32 m0, s35
	s_nop 0
	global_load_lds_dwordx4 v[220:221], off
	s_waitcnt vmcnt(8)
	s_waitcnt lgkmcnt(0)
	s_barrier
; #define PG8_STAGE(bufoff, gbase, voff) do { _Pragma("unroll") for (int _i = 0; _i < 2; ++_i) \
;         __builtin_amdgcn_global_load_lds((const unsigned*)((const char*)(gbase) + (voff)[_i]), (PG8_LAS unsigned*)(lds + (bufoff) + ldsw + _i * 8192), 16, 0, 0); } while (0)
; #define PG8_LDA(dst, b, h) do { _Pragma("unroll") for (int m = 0; m < 4; ++m) _Pragma("unroll") for (int k = 0; k < 2; ++k) dst[m][k] = *(const PG8_LAS bf16x8*)(lds + PG8_SA(b, h) + aoff + m * 2048 + k * 1024); } while (0)
; #define PG8_LDB(dst, b, h) do { _Pragma("unroll") for (int n = 0; n < 2; ++n) _Pragma("unroll") for (int k = 0; k < 2; ++k) dst[n][k] = *(const PG8_LAS bf16x8*)(lds + PG8_SB(b, h) + boff + n * 2048 + k * 1024); } while (0)
; #define PG8_MMA(ai, bj, At, Bt) do { __builtin_amdgcn_s_setprio(1); _Pragma("unroll") for (int m = 0; m < 4; ++m) _Pragma("unroll") for (int n = 0; n < 2; ++n) _Pragma("unroll") for (int k = 0; k < 2; ++k) \
;         acc[ai][bj][m][n] = __builtin_amdgcn_mfma_f32_16x16x32_bf16(Bt[n][k], At[m][k], acc[ai][bj][m][n], 0, 0, 0); __builtin_amdgcn_s_setprio(0); } while (0)
; #define PG8_WAIT_V(n) asm volatile("s_waitcnt vmcnt(" #n ")" ::: "memory")
; #define PG8_WAIT_L(n) asm volatile("s_waitcnt lgkmcnt(" #n ")" ::: "memory")
; #define PG8_BAR __builtin_amdgcn_s_barrier()
; #define PG8_SCHED __builtin_amdgcn_sched_barrier(0)
; template <class Epi, class Sched, bool ALIGN_EPI = false, bool SP2 = false>
; __device__ __forceinline__ void gemm_phase(PG8_LAS unsigned char* lds, const Gemm g, const Sched& S, const Epi& E) {
;     ...
;             PG8_WAIT_V(8); PG8_WAIT_L(0); PG8_BAR; PG8_MMA(1, 0, At, B0); PG8_MMA(1, 1, At, B1); PG8_BAR; PG8_SCHED;
;             PG8_LDB(B0, 1, 0); PG8_LDB(B1, 1, 1); PG8_SCHED; PG8_LDA(At, 1, 0); PG8_STAGE(PG8_SA(0, 1), a2 + hstepA, voffA);
;             PG8_WAIT_V(8); PG8_WAIT_L(0); PG8_BAR; PG8_MMA(0, 0, At, B0); PG8_MMA(0, 1, At, B1); PG8_BAR; PG8_SCHED;
	s_setprio 1
	s_waitcnt lgkmcnt(0)
	v_mfma_f32_16x16x32_bf16 v[62:65], v[136:139], v[168:171], v[62:65]
	v_mfma_f32_16x16x32_bf16 v[58:61], v[144:147], v[168:171], v[58:61]
	v_mfma_f32_16x16x32_bf16 v[46:49], v[136:139], v[176:179], v[46:49]
	v_mfma_f32_16x16x32_bf16 v[42:45], v[144:147], v[176:179], v[42:45]
	v_mfma_f32_16x16x32_bf16 v[30:33], v[136:139], v[184:187], v[30:33]
	v_mfma_f32_16x16x32_bf16 v[26:29], v[144:147], v[184:187], v[26:29]
	v_mfma_f32_16x16x32_bf16 v[14:17], v[136:139], v[206:209], v[14:17]
	v_mfma_f32_16x16x32_bf16 v[10:13], v[144:147], v[206:209], v[10:13]
	v_mfma_f32_16x16x32_bf16 v[62:65], v[140:143], v[172:175], v[62:65]
	v_mfma_f32_16x16x32_bf16 v[58:61], v[148:151], v[172:175], v[58:61]
	v_mfma_f32_16x16x32_bf16 v[46:49], v[140:143], v[180:183], v[46:49]
	v_mfma_f32_16x16x32_bf16 v[42:45], v[148:151], v[180:183], v[42:45]
	v_mfma_f32_16x16x32_bf16 v[30:33], v[140:143], v[198:201], v[30:33]
	v_mfma_f32_16x16x32_bf16 v[26:29], v[148:151], v[198:201], v[26:29]
	v_mfma_f32_16x16x32_bf16 v[14:17], v[140:143], v[212:215], v[14:17]
	v_mfma_f32_16x16x32_bf16 v[10:13], v[148:151], v[212:215], v[10:13]
	s_setprio 0
	s_setprio 1
	v_mfma_f32_16x16x32_bf16 v[54:57], v[152:155], v[168:171], v[54:57]
	v_mfma_f32_16x16x32_bf16 v[50:53], v[160:163], v[168:171], v[50:53]
	v_mfma_f32_16x16x32_bf16 v[38:41], v[152:155], v[176:179], v[38:41]
	v_mfma_f32_16x16x32_bf16 v[34:37], v[160:163], v[176:179], v[34:37]
	v_mfma_f32_16x16x32_bf16 v[22:25], v[152:155], v[184:187], v[22:25]
	v_mfma_f32_16x16x32_bf16 v[18:21], v[160:163], v[184:187], v[18:21]
	v_mfma_f32_16x16x32_bf16 v[6:9], v[152:155], v[206:209], v[6:9]
	v_mfma_f32_16x16x32_bf16 v[2:5], v[160:163], v[206:209], v[2:5]
	v_mfma_f32_16x16x32_bf16 v[54:57], v[156:159], v[172:175], v[54:57]
	v_mfma_f32_16x16x32_bf16 v[50:53], v[164:167], v[172:175], v[50:53]
	v_mfma_f32_16x16x32_bf16 v[38:41], v[156:159], v[180:183], v[38:41]
	v_mfma_f32_16x16x32_bf16 v[34:37], v[164:167], v[180:183], v[34:37]
	v_mfma_f32_16x16x32_bf16 v[22:25], v[156:159], v[198:201], v[22:25]
	v_mfma_f32_16x16x32_bf16 v[18:21], v[164:167], v[198:201], v[18:21]
	v_mfma_f32_16x16x32_bf16 v[6:9], v[156:159], v[212:215], v[6:9]
	v_mfma_f32_16x16x32_bf16 v[2:5], v[164:167], v[212:215], v[2:5]
	s_setprio 0
	s_barrier
	s_add_i32 s54, 0, 0x18000
	s_add_i32 s55, 0, 0x1c000
	v_add_u32_e32 v148, s54, v191
	v_add_u32_e32 v164, s55, v191
	ds_read_b128 v[136:139], v148
	ds_read_b128 v[140:143], v148 offset:1024
	ds_read_b128 v[144:147], v148 offset:2048
	ds_read_b128 v[148:151], v148 offset:3072
	ds_read_b128 v[152:155], v164
	ds_read_b128 v[156:159], v164 offset:1024
	ds_read_b128 v[160:163], v164 offset:2048
	ds_read_b128 v[164:167], v164 offset:3072
	s_add_u32 s16, s22, 0xb0000
	s_addc_u32 s17, s23, 0
	s_mov_b32 m0, s40
	v_lshl_add_u64 v[222:223], s[16:17], 0, v[0:1]
	ds_read_b128 v[168:171], v193 offset:32768
	ds_read_b128 v[172:175], v193 offset:33792
	ds_read_b128 v[176:179], v193 offset:34816
	ds_read_b128 v[180:183], v193 offset:35840
	ds_read_b128 v[184:187], v193 offset:36864
	ds_read_b128 v[198:201], v193 offset:37888
	ds_read_b128 v[206:209], v193 offset:38912
	ds_read_b128 v[212:215], v193 offset:39936
	global_load_lds_dwordx4 v[222:223], off
	v_lshl_add_u64 v[222:223], s[16:17], 0, v[130:131]
	s_mov_b32 m0, s41
	s_nop 0
	global_load_lds_dwordx4 v[222:223], off
	s_waitcnt vmcnt(8)
	s_waitcnt lgkmcnt(0)
	s_barrier
	s_setprio 1
	s_waitcnt lgkmcnt(0)
	v_mfma_f32_16x16x32_bf16 v[126:129], v[136:139], v[168:171], v[126:129]
	v_mfma_f32_16x16x32_bf16 v[122:125], v[144:147], v[168:171], v[122:125]
	v_mfma_f32_16x16x32_bf16 v[110:113], v[136:139], v[176:179], v[110:113]
	v_mfma_f32_16x16x32_bf16 v[106:109], v[144:147], v[176:179], v[106:109]
	v_mfma_f32_16x16x32_bf16 v[94:97], v[136:139], v[184:187], v[94:97]
	v_mfma_f32_16x16x32_bf16 v[90:93], v[144:147], v[184:187], v[90:93]
	v_mfma_f32_16x16x32_bf16 v[78:81], v[136:139], v[206:209], v[78:81]
	v_mfma_f32_16x16x32_bf16 v[74:77], v[144:147], v[206:209], v[74:77]
	v_mfma_f32_16x16x32_bf16 v[126:129], v[140:143], v[172:175], v[126:129]
	v_mfma_f32_16x16x32_bf16 v[122:125], v[148:151], v[172:175], v[122:125]
	v_mfma_f32_16x16x32_bf16 v[110:113], v[140:143], v[180:183], v[110:113]
	v_mfma_f32_16x16x32_bf16 v[106:109], v[148:151], v[180:183], v[106:109]
	v_mfma_f32_16x16x32_bf16 v[94:97], v[140:143], v[198:201], v[94:97]
	v_mfma_f32_16x16x32_bf16 v[90:93], v[148:151], v[198:201], v[90:93]
	v_mfma_f32_16x16x32_bf16 v[78:81], v[140:143], v[212:215], v[78:81]
	v_mfma_f32_16x16x32_bf16 v[74:77], v[148:151], v[212:215], v[74:77]
	s_setprio 0
	s_setprio 1
	v_mfma_f32_16x16x32_bf16 v[118:121], v[152:155], v[168:171], v[118:121]
	v_mfma_f32_16x16x32_bf16 v[114:117], v[160:163], v[168:171], v[114:117]
	v_mfma_f32_16x16x32_bf16 v[102:105], v[152:155], v[176:179], v[102:105]
	v_mfma_f32_16x16x32_bf16 v[98:101], v[160:163], v[176:179], v[98:101]
	v_mfma_f32_16x16x32_bf16 v[86:89], v[152:155], v[184:187], v[86:89]
	v_mfma_f32_16x16x32_bf16 v[82:85], v[160:163], v[184:187], v[82:85]
	v_mfma_f32_16x16x32_bf16 v[70:73], v[152:155], v[206:209], v[70:73]
	v_mfma_f32_16x16x32_bf16 v[66:69], v[160:163], v[206:209], v[66:69]
	v_mfma_f32_16x16x32_bf16 v[118:121], v[156:159], v[172:175], v[118:121]
	v_mfma_f32_16x16x32_bf16 v[114:117], v[164:167], v[172:175], v[114:117]
	v_mfma_f32_16x16x32_bf16 v[102:105], v[156:159], v[180:183], v[102:105]
	v_mfma_f32_16x16x32_bf16 v[98:101], v[164:167], v[180:183], v[98:101]
	v_mfma_f32_16x16x32_bf16 v[86:89], v[156:159], v[198:201], v[86:89]
	v_mfma_f32_16x16x32_bf16 v[82:85], v[164:167], v[198:201], v[82:85]
	v_mfma_f32_16x16x32_bf16 v[70:73], v[156:159], v[212:215], v[70:73]
	v_mfma_f32_16x16x32_bf16 v[66:69], v[164:167], v[212:215], v[66:69]
	s_setprio 0
	s_barrier
; #define PG8_STAGE(bufoff, gbase, voff) do { _Pragma("unroll") for (int _i = 0; _i < 2; ++_i) \
;         __builtin_amdgcn_global_load_lds((const unsigned*)((const char*)(gbase) + (voff)[_i]), (PG8_LAS unsigned*)(lds + (bufoff) + ldsw + _i * 8192), 16, 0, 0); } while (0)
; #define PG8_LDA(dst, b, h) do { _Pragma("unroll") for (int m = 0; m < 4; ++m) _Pragma("unroll") for (int k = 0; k < 2; ++k) dst[m][k] = *(const PG8_LAS bf16x8*)(lds + PG8_SA(b, h) + aoff + m * 2048 + k * 1024); } while (0)
; #define PG8_MMA(ai, bj, At, Bt) do { __builtin_amdgcn_s_setprio(1); _Pragma("unroll") for (int m = 0; m < 4; ++m) _Pragma("unroll") for (int n = 0; n < 2; ++n) _Pragma("unroll") for (int k = 0; k < 2; ++k) \
;         acc[ai][bj][m][n] = __builtin_amdgcn_mfma_f32_16x16x32_bf16(Bt[n][k], At[m][k], acc[ai][bj][m][n], 0, 0, 0); __builtin_amdgcn_s_setprio(0); } while (0)
; #define PG8_WAIT_V(n) asm volatile("s_waitcnt vmcnt(" #n ")" ::: "memory")
; #define PG8_WAIT_L(n) asm volatile("s_waitcnt lgkmcnt(" #n ")" ::: "memory")
; #define PG8_BAR __builtin_amdgcn_s_barrier()
; #define PG8_SCHED __builtin_amdgcn_sched_barrier(0)
; template <class Epi, class Sched, bool ALIGN_EPI = false, bool SP2 = false>
; __device__ __forceinline__ void gemm_phase(PG8_LAS unsigned char* lds, const Gemm g, const Sched& S, const Epi& E) {
;     ...
;             PG8_LDA(At, 1, 1); PG8_STAGE(PG8_SB(1, 0), b3, voffB); PG8_STAGE(PG8_SB(1, 1), b3 + hstepB, voffB); PG8_STAGE(PG8_SA(1, 0), a3, voffA);
;             PG8_WAIT_V(8); PG8_WAIT_L(0); PG8_BAR; PG8_MMA(1, 0, At, B0); PG8_MMA(1, 1, At, B1); PG8_BAR; PG8_SCHED;
;     ...
;         if constexpr (ALIGN_EPI) { if (wr == 0) PG8_BAR; }
	s_add_i32 s16, s54, s31
	v_lshl_add_u64 v[188:189], v[188:189], 0, s[88:89]
	s_mov_b32 m0, s16
	ds_read_b128 v[168:171], v193 offset:49152
	ds_read_b128 v[172:175], v193 offset:50176
	ds_read_b128 v[176:179], v193 offset:51200
	ds_read_b128 v[180:183], v193 offset:52224
	ds_read_b128 v[184:187], v193 offset:53248
	ds_read_b128 v[198:201], v193 offset:54272
	ds_read_b128 v[206:209], v193 offset:55296
	ds_read_b128 v[212:215], v193 offset:56320
	global_load_lds_dwordx4 v[188:189], off
	s_add_i32 m0, s16, 0x2000
	s_add_u32 s16, s20, 0xb0080
	v_lshl_add_u64 v[188:189], v[216:217], 0, s[88:89]
	s_addc_u32 s17, s21, 0
	s_add_i32 s20, s55, s31
	global_load_lds_dwordx4 v[188:189], off
	v_lshl_add_u64 v[188:189], s[16:17], 0, v[0:1]
	s_mov_b32 m0, s20
	s_nop 0
	global_load_lds_dwordx4 v[188:189], off
	v_lshl_add_u64 v[188:189], s[16:17], 0, v[130:131]
	s_add_i32 m0, s20, 0x2000
	s_nop 0
	global_load_lds_dwordx4 v[188:189], off
	v_lshl_add_u64 v[188:189], v[218:219], 0, s[88:89]
	s_mov_b32 m0, s43
	s_nop 0
	global_load_lds_dwordx4 v[188:189], off
	v_lshl_add_u64 v[188:189], v[220:221], 0, s[88:89]
	s_mov_b32 m0, s44
	s_nop 0
	global_load_lds_dwordx4 v[188:189], off
	s_waitcnt vmcnt(8)
	s_waitcnt lgkmcnt(0)
	s_barrier
	s_setprio 1
	s_waitcnt lgkmcnt(0)
	v_mfma_f32_16x16x32_bf16 v[62:65], v[136:139], v[168:171], v[62:65]
	v_mfma_f32_16x16x32_bf16 v[58:61], v[144:147], v[168:171], v[58:61]
	v_mfma_f32_16x16x32_bf16 v[46:49], v[136:139], v[176:179], v[46:49]
	v_mfma_f32_16x16x32_bf16 v[42:45], v[144:147], v[176:179], v[42:45]
	v_mfma_f32_16x16x32_bf16 v[30:33], v[136:139], v[184:187], v[30:33]
	v_mfma_f32_16x16x32_bf16 v[26:29], v[144:147], v[184:187], v[26:29]
	v_mfma_f32_16x16x32_bf16 v[14:17], v[136:139], v[206:209], v[14:17]
	v_mfma_f32_16x16x32_bf16 v[10:13], v[144:147], v[206:209], v[10:13]
	v_mfma_f32_16x16x32_bf16 v[62:65], v[140:143], v[172:175], v[62:65]
	v_mfma_f32_16x16x32_bf16 v[58:61], v[148:151], v[172:175], v[58:61]
	v_mfma_f32_16x16x32_bf16 v[46:49], v[140:143], v[180:183], v[46:49]
	v_mfma_f32_16x16x32_bf16 v[42:45], v[148:151], v[180:183], v[42:45]
	v_mfma_f32_16x16x32_bf16 v[30:33], v[140:143], v[198:201], v[30:33]
	v_mfma_f32_16x16x32_bf16 v[26:29], v[148:151], v[198:201], v[26:29]
	v_mfma_f32_16x16x32_bf16 v[14:17], v[140:143], v[212:215], v[14:17]
	v_mfma_f32_16x16x32_bf16 v[10:13], v[148:151], v[212:215], v[10:13]
	s_setprio 0
	s_setprio 1
	v_mfma_f32_16x16x32_bf16 v[54:57], v[152:155], v[168:171], v[54:57]
	v_mfma_f32_16x16x32_bf16 v[50:53], v[160:163], v[168:171], v[50:53]
	v_mfma_f32_16x16x32_bf16 v[38:41], v[152:155], v[176:179], v[38:41]
	v_mfma_f32_16x16x32_bf16 v[34:37], v[160:163], v[176:179], v[34:37]
	v_mfma_f32_16x16x32_bf16 v[22:25], v[152:155], v[184:187], v[22:25]
	v_mfma_f32_16x16x32_bf16 v[18:21], v[160:163], v[184:187], v[18:21]
	v_mfma_f32_16x16x32_bf16 v[6:9], v[152:155], v[206:209], v[6:9]
	v_mfma_f32_16x16x32_bf16 v[2:5], v[160:163], v[206:209], v[2:5]
	v_mfma_f32_16x16x32_bf16 v[54:57], v[156:159], v[172:175], v[54:57]
	v_mfma_f32_16x16x32_bf16 v[50:53], v[164:167], v[172:175], v[50:53]
	v_mfma_f32_16x16x32_bf16 v[38:41], v[156:159], v[180:183], v[38:41]
	v_mfma_f32_16x16x32_bf16 v[34:37], v[164:167], v[180:183], v[34:37]
	v_mfma_f32_16x16x32_bf16 v[22:25], v[156:159], v[198:201], v[22:25]
	v_mfma_f32_16x16x32_bf16 v[18:21], v[164:167], v[198:201], v[18:21]
	v_mfma_f32_16x16x32_bf16 v[6:9], v[156:159], v[212:215], v[6:9]
	v_mfma_f32_16x16x32_bf16 v[2:5], v[164:167], v[212:215], v[2:5]
	s_setprio 0
	s_barrier
	s_add_i32 s53, s53, 2
	s_add_u32 s51, s51, 0x100
	s_addc_u32 s52, s52, 0
	s_cmp_gt_u32 s53, 41
	s_mov_b64 s[16:17], s[18:19]
	s_cbranch_scc0 .LBB0_1329
	v_readfirstlane_b32 s100, v238
	s_nop 3
	s_bfe_u32 s100, s100, 0x40006
	s_cmp_ge_u32 s100, 4
	s_cbranch_scc0 .Lepiprio_13
	s_setprio 1
